# v35 + MFMA-segment tail prep (m0/address for next DMA) hoisted into the preceding light load segment instead of after the closing barrier; bit-identical
# speedup vs baseline: 1.0085x; 1.0039x over previous
; #define PG8_WAIT_L(n) asm volatile("s_waitcnt lgkmcnt(" #n ")" ::: "memory")
; #define PG8_BAR __builtin_amdgcn_s_barrier()
; #define PG8_SCHED __builtin_amdgcn_sched_barrier(0)
; template <class Epi, class AddrA, class AddrB>
; __device__ __forceinline__ void gemm_phase(const Sched S, const int lda, const int ldb, const int K, const AddrA addrA,
;                                            const AddrB addrB, const Epi E) {
;     ...
;     const bool has_next = S.next(ui + 1, nxt);
;     const char* nA = has_next ? addrA(nxt) : cA;
;     const char* nB = has_next ? addrB(nxt) : cB;
;     for (int t = 0; t < nt; t += 2) {
;       const bool last = (t == nt - 2);
;       const char* a1 = cA + (size_t)(t + 1) * kstep;
;       const char* a2 = last ? nA : cA + (size_t)(t + 2) * kstep;
;       const char* b2 = last ? nB : cB + (size_t)(t + 2) * kstep;
;       const char* a3 = a2 + kstep;
;       const char* b3 = b2 + kstep;
;       PG8_LDB(B0, 0, 0); PG8_SCHED; PG8_LDA(At, 0, 0); PG8_STAGE(PG8_SA(1, 1), a1 + hstepA, voffA);
;       PG8_WAIT_L(8); PG8_BAR; PG8_WAIT_L(0); PG8_MMA(0, 0, At, B0); PG8_BAR; PG8_SCHED;
;       PG8_LDB(B1, 0, 1); PG8_STAGE(PG8_SB(0, 0), b2, voffB);
;       PG8_BAR; PG8_WAIT_L(0); PG8_MMA(0, 1, At, B1); PG8_BAR;
;       PG8_LDA(At, 0, 1); PG8_STAGE(PG8_SA(0, 0), a2, voffA);
;       PG8_BAR; PG8_WAIT_L(0); PG8_MMA(1, 0, At, B0); PG8_BAR; PG8_SCHED;
.LBB0_108:
	s_ashr_i32 s1, s0, 31
	s_lshl_b64 s[6:7], s[0:1], 20
	s_add_u32 s6, s20, s6
	s_addc_u32 s7, s21, s7
	s_and_b64 s[8:9], s[16:17], exec
	s_cselect_b32 s1, s7, s15
	s_cselect_b32 s11, s6, s14
	s_ashr_i32 s3, s2, 31
	s_lshl_b64 s[8:9], s[2:3], 20
	s_add_u32 s8, s22, s8
	s_addc_u32 s9, s23, s9
	s_and_b64 s[16:17], s[16:17], exec
	s_cselect_b32 s3, s9, s13
	s_cselect_b32 s36, s8, s12
	s_add_u32 s37, s12, 0x100
	s_addc_u32 s38, s13, 0
	s_add_u32 s12, s14, 0x80080
	s_addc_u32 s13, s15, 0
	s_mov_b32 s39, -2
	s_add_i32 s40, 0, 0x10000
	v_add_u32_e32 v142, s40, v145
	ds_read_b128 v[148:151], v142
	ds_read_b128 v[152:155], v142 offset:1024
	ds_read_b128 v[156:159], v142 offset:2048
	ds_read_b128 v[160:163], v142 offset:3072
	v_lshl_add_u64 v[142:143], s[12:13], 0, v[140:141]
	s_add_i32 m0, s24, 0xc000
	ds_read_b128 v[168:171], v146
	ds_read_b128 v[172:175], v146 offset:1024
	ds_read_b128 v[176:179], v146 offset:2048
	ds_read_b128 v[180:183], v146 offset:3072
	ds_read_b128 v[184:187], v146 offset:4096
	ds_read_b128 v[188:191], v146 offset:5120
	ds_read_b128 v[192:195], v146 offset:6144
	ds_read_b128 v[212:215], v146 offset:7168
	global_load_lds_dwordx4 v[142:143], off
	v_lshl_add_u64 v[142:143], s[12:13], 0, v[138:139]
	s_add_i32 m0, s24, 0xe000
	s_nop 0
	global_load_lds_dwordx4 v[142:143], off
	s_waitcnt lgkmcnt(8)
	s_setprio 1
	s_barrier
	s_waitcnt lgkmcnt(0)
	v_mfma_f32_16x16x32_bf16 v[128:131], v[148:151], v[168:171], 0
	v_mfma_f32_16x16x32_bf16 v[128:131], v[152:155], v[172:175], v[128:131]
	v_mfma_f32_16x16x32_bf16 v[120:123], v[148:151], v[176:179], 0
	v_mfma_f32_16x16x32_bf16 v[120:123], v[152:155], v[180:183], v[120:123]
	v_mfma_f32_16x16x32_bf16 v[104:107], v[148:151], v[184:187], 0
	v_mfma_f32_16x16x32_bf16 v[104:107], v[152:155], v[188:191], v[104:107]
	v_mfma_f32_16x16x32_bf16 v[88:91], v[148:151], v[192:195], 0
	v_mfma_f32_16x16x32_bf16 v[88:91], v[152:155], v[212:215], v[88:91]
	v_mfma_f32_16x16x32_bf16 v[124:127], v[156:159], v[168:171], 0
	v_mfma_f32_16x16x32_bf16 v[124:127], v[160:163], v[172:175], v[124:127]
	v_mfma_f32_16x16x32_bf16 v[112:115], v[156:159], v[176:179], 0
	v_mfma_f32_16x16x32_bf16 v[112:115], v[160:163], v[180:183], v[112:115]
	v_mfma_f32_16x16x32_bf16 v[96:99], v[156:159], v[184:187], 0
	v_mfma_f32_16x16x32_bf16 v[96:99], v[160:163], v[188:191], v[96:99]
	v_mfma_f32_16x16x32_bf16 v[80:83], v[156:159], v[192:195], 0
	v_mfma_f32_16x16x32_bf16 v[80:83], v[160:163], v[212:215], v[80:83]
	s_barrier
	s_setprio 0
	s_add_u32 s14, s12, 0xfff80080
	s_addc_u32 s15, s13, -1
	s_cmp_eq_u32 s39, 28
	s_cselect_b32 s17, s1, s15
	s_cselect_b32 s16, s11, s14
	s_cselect_b32 s15, s3, s38
	s_cselect_b32 s14, s36, s37
	s_add_i32 s42, 0, 0x14000
	v_add_u32_e32 v142, s42, v145
	s_add_i32 s40, s40, s19
	ds_read_b128 v[216:219], v142
	ds_read_b128 v[220:223], v142 offset:1024
	ds_read_b128 v[224:227], v142 offset:2048
	ds_read_b128 v[228:231], v142 offset:3072
	v_lshl_add_u64 v[142:143], s[14:15], 0, v[134:135]
	s_mov_b32 m0, s40
	v_lshl_add_u64 v[196:197], s[14:15], 0, v[0:1]
	global_load_lds_dwordx4 v[142:143], off
	s_add_i32 m0, s40, 0x2000
	s_nop 0
	global_load_lds_dwordx4 v[196:197], off
	s_mov_b32 m0, s24
	v_lshl_add_u64 v[232:233], s[16:17], 0, v[136:137]
	s_setprio 1
	s_barrier
	s_waitcnt lgkmcnt(0)
	v_mfma_f32_16x16x32_bf16 v[116:119], v[216:219], v[168:171], 0
	v_mfma_f32_16x16x32_bf16 v[116:119], v[220:223], v[172:175], v[116:119]
	v_mfma_f32_16x16x32_bf16 v[100:103], v[216:219], v[176:179], 0
	v_mfma_f32_16x16x32_bf16 v[100:103], v[220:223], v[180:183], v[100:103]
	v_mfma_f32_16x16x32_bf16 v[84:87], v[216:219], v[184:187], 0
	v_mfma_f32_16x16x32_bf16 v[84:87], v[220:223], v[188:191], v[84:87]
	v_mfma_f32_16x16x32_bf16 v[72:75], v[216:219], v[192:195], 0
	v_mfma_f32_16x16x32_bf16 v[72:75], v[220:223], v[212:215], v[72:75]
	v_mfma_f32_16x16x32_bf16 v[108:111], v[224:227], v[168:171], 0
	v_mfma_f32_16x16x32_bf16 v[108:111], v[228:231], v[172:175], v[108:111]
	v_mfma_f32_16x16x32_bf16 v[92:95], v[224:227], v[176:179], 0
	v_mfma_f32_16x16x32_bf16 v[92:95], v[228:231], v[180:183], v[92:95]
	v_mfma_f32_16x16x32_bf16 v[76:79], v[224:227], v[184:187], 0
	v_mfma_f32_16x16x32_bf16 v[76:79], v[228:231], v[188:191], v[76:79]
	v_mfma_f32_16x16x32_bf16 v[68:71], v[224:227], v[192:195], 0
	v_mfma_f32_16x16x32_bf16 v[68:71], v[228:231], v[212:215], v[68:71]
	s_barrier
	s_setprio 0
	ds_read_b128 v[168:171], v146 offset:16384
	ds_read_b128 v[172:175], v146 offset:17408
	ds_read_b128 v[176:179], v146 offset:18432
	ds_read_b128 v[180:183], v146 offset:19456
	ds_read_b128 v[184:187], v146 offset:20480
	ds_read_b128 v[188:191], v146 offset:21504
	ds_read_b128 v[192:195], v146 offset:22528
	ds_read_b128 v[212:215], v146 offset:23552
	global_load_lds_dwordx4 v[232:233], off
	v_lshl_add_u64 v[234:235], s[16:17], 0, v[132:133]
	s_mov_b32 m0, s25
	s_nop 0
	global_load_lds_dwordx4 v[234:235], off
	s_setprio 1
	s_barrier
	s_waitcnt lgkmcnt(0)
	v_mfma_f32_16x16x32_bf16 v[64:67], v[148:151], v[168:171], 0
	v_mfma_f32_16x16x32_bf16 v[64:67], v[152:155], v[172:175], v[64:67]
	v_mfma_f32_16x16x32_bf16 v[56:59], v[148:151], v[176:179], 0
	v_mfma_f32_16x16x32_bf16 v[56:59], v[152:155], v[180:183], v[56:59]
	v_mfma_f32_16x16x32_bf16 v[40:43], v[148:151], v[184:187], 0
	v_mfma_f32_16x16x32_bf16 v[40:43], v[152:155], v[188:191], v[40:43]
	v_mfma_f32_16x16x32_bf16 v[24:27], v[148:151], v[192:195], 0
	v_mfma_f32_16x16x32_bf16 v[24:27], v[152:155], v[212:215], v[24:27]
	v_mfma_f32_16x16x32_bf16 v[60:63], v[156:159], v[168:171], 0
	v_mfma_f32_16x16x32_bf16 v[60:63], v[160:163], v[172:175], v[60:63]
	v_mfma_f32_16x16x32_bf16 v[48:51], v[156:159], v[176:179], 0
	v_mfma_f32_16x16x32_bf16 v[48:51], v[160:163], v[180:183], v[48:51]
	v_mfma_f32_16x16x32_bf16 v[32:35], v[156:159], v[184:187], 0
	v_mfma_f32_16x16x32_bf16 v[32:35], v[160:163], v[188:191], v[32:35]
	v_mfma_f32_16x16x32_bf16 v[16:19], v[156:159], v[192:195], 0
	v_mfma_f32_16x16x32_bf16 v[16:19], v[160:163], v[212:215], v[16:19]
	s_barrier
; #define PG8_WAIT_V(n) asm volatile("s_waitcnt vmcnt(" #n ")" ::: "memory")
; #define PG8_WAIT_L(n) asm volatile("s_waitcnt lgkmcnt(" #n ")" ::: "memory")
; #define PG8_BAR __builtin_amdgcn_s_barrier()
; #define PG8_SCHED __builtin_amdgcn_sched_barrier(0)
; template <class Epi, class AddrA, class AddrB>
; __device__ __forceinline__ void gemm_phase(const Sched S, const int lda, const int ldb, const int K, const AddrA addrA,
;                                            const AddrB addrB, const Epi E) {
;     ...
;       PG8_BAR; PG8_WAIT_L(0); PG8_MMA(1, 0, At, B0); PG8_BAR; PG8_SCHED;
;       PG8_STAGE(PG8_SB(0, 1), b2 + hstepB, voffB);
;       PG8_WAIT_V(6); PG8_BAR; PG8_MMA(1, 1, At, B1); PG8_BAR;
;       PG8_LDB(B0, 1, 0); PG8_SCHED; PG8_LDA(At, 1, 0); PG8_STAGE(PG8_SA(0, 1), a2 + hstepA, voffA);
;       PG8_WAIT_L(8); PG8_BAR; PG8_WAIT_L(0); PG8_MMA(0, 0, At, B0); PG8_BAR; PG8_SCHED;
;       PG8_LDB(B1, 1, 1); PG8_STAGE(PG8_SB(1, 0), b3, voffB);
;       PG8_BAR; PG8_WAIT_L(0); PG8_MMA(0, 1, At, B1); PG8_BAR;
;       PG8_LDA(At, 1, 1); PG8_STAGE(PG8_SA(1, 0), a3, voffA);
;       PG8_BAR; PG8_WAIT_L(0); PG8_MMA(1, 0, At, B0); PG8_BAR; PG8_SCHED;
	s_setprio 0
	s_add_u32 s40, s14, 0x80000
	s_addc_u32 s41, s15, 0
	s_add_i32 s42, s42, s19
	v_lshl_add_u64 v[148:149], s[40:41], 0, v[134:135]
	s_mov_b32 m0, s42
	s_nop 0
	global_load_lds_dwordx4 v[148:149], off
	v_lshl_add_u64 v[148:149], s[40:41], 0, v[0:1]
	s_add_i32 m0, s42, 0x2000
	s_nop 0
	global_load_lds_dwordx4 v[148:149], off
	s_add_i32 s40, 0, 0x18000
	v_add_u32_e32 v147, s40, v145
	s_waitcnt vmcnt(6)
	s_setprio 1
	s_barrier
	v_mfma_f32_16x16x32_bf16 v[52:55], v[216:219], v[168:171], 0
	v_mfma_f32_16x16x32_bf16 v[52:55], v[220:223], v[172:175], v[52:55]
	v_mfma_f32_16x16x32_bf16 v[36:39], v[216:219], v[176:179], 0
	v_mfma_f32_16x16x32_bf16 v[36:39], v[220:223], v[180:183], v[36:39]
	v_mfma_f32_16x16x32_bf16 v[20:23], v[216:219], v[184:187], 0
	v_mfma_f32_16x16x32_bf16 v[20:23], v[220:223], v[188:191], v[20:23]
	v_mfma_f32_16x16x32_bf16 v[8:11], v[216:219], v[192:195], 0
	v_mfma_f32_16x16x32_bf16 v[8:11], v[220:223], v[212:215], v[8:11]
	v_mfma_f32_16x16x32_bf16 v[44:47], v[224:227], v[168:171], 0
	v_mfma_f32_16x16x32_bf16 v[44:47], v[228:231], v[172:175], v[44:47]
	v_mfma_f32_16x16x32_bf16 v[28:31], v[224:227], v[176:179], 0
	v_mfma_f32_16x16x32_bf16 v[28:31], v[228:231], v[180:183], v[28:31]
	v_mfma_f32_16x16x32_bf16 v[12:15], v[224:227], v[184:187], 0
	v_mfma_f32_16x16x32_bf16 v[12:15], v[228:231], v[188:191], v[12:15]
	v_mfma_f32_16x16x32_bf16 v[4:7], v[224:227], v[192:195], 0
	v_mfma_f32_16x16x32_bf16 v[4:7], v[228:231], v[212:215], v[4:7]
	s_barrier
	s_setprio 0
	ds_read_b128 v[148:151], v147
	ds_read_b128 v[152:155], v147 offset:1024
	ds_read_b128 v[156:159], v147 offset:2048
	ds_read_b128 v[160:163], v147 offset:3072
	s_add_u32 s16, s16, 0x80000
	s_addc_u32 s17, s17, 0
	s_mov_b32 m0, s26
	v_lshl_add_u64 v[216:217], s[16:17], 0, v[136:137]
	ds_read_b128 v[168:171], v146 offset:32768
	ds_read_b128 v[172:175], v146 offset:33792
	ds_read_b128 v[176:179], v146 offset:34816
	ds_read_b128 v[180:183], v146 offset:35840
	ds_read_b128 v[184:187], v146 offset:36864
	ds_read_b128 v[188:191], v146 offset:37888
	ds_read_b128 v[192:195], v146 offset:38912
	ds_read_b128 v[212:215], v146 offset:39936
	global_load_lds_dwordx4 v[216:217], off
	v_lshl_add_u64 v[216:217], s[16:17], 0, v[132:133]
	s_mov_b32 m0, s27
	s_nop 0
	global_load_lds_dwordx4 v[216:217], off
	s_waitcnt lgkmcnt(8)
	s_setprio 1
	s_barrier
	s_waitcnt lgkmcnt(0)
	v_mfma_f32_16x16x32_bf16 v[128:131], v[148:151], v[168:171], v[128:131]
	v_mfma_f32_16x16x32_bf16 v[128:131], v[152:155], v[172:175], v[128:131]
	v_mfma_f32_16x16x32_bf16 v[120:123], v[148:151], v[176:179], v[120:123]
	v_mfma_f32_16x16x32_bf16 v[120:123], v[152:155], v[180:183], v[120:123]
	v_mfma_f32_16x16x32_bf16 v[104:107], v[148:151], v[184:187], v[104:107]
	v_mfma_f32_16x16x32_bf16 v[104:107], v[152:155], v[188:191], v[104:107]
	v_mfma_f32_16x16x32_bf16 v[88:91], v[148:151], v[192:195], v[88:91]
	v_mfma_f32_16x16x32_bf16 v[88:91], v[152:155], v[212:215], v[88:91]
	v_mfma_f32_16x16x32_bf16 v[124:127], v[156:159], v[168:171], v[124:127]
	v_mfma_f32_16x16x32_bf16 v[124:127], v[160:163], v[172:175], v[124:127]
	v_mfma_f32_16x16x32_bf16 v[112:115], v[156:159], v[176:179], v[112:115]
	v_mfma_f32_16x16x32_bf16 v[112:115], v[160:163], v[180:183], v[112:115]
	v_mfma_f32_16x16x32_bf16 v[96:99], v[156:159], v[184:187], v[96:99]
	v_mfma_f32_16x16x32_bf16 v[96:99], v[160:163], v[188:191], v[96:99]
	v_mfma_f32_16x16x32_bf16 v[80:83], v[156:159], v[192:195], v[80:83]
	v_mfma_f32_16x16x32_bf16 v[80:83], v[160:163], v[212:215], v[80:83]
	s_barrier
	s_setprio 0
	s_add_i32 s16, 0, 0x1c000
	s_add_i32 s17, s40, s19
	v_add_u32_e32 v147, s16, v145
	v_lshl_add_u64 v[142:143], v[142:143], 0, s[52:53]
	s_mov_b32 m0, s17
	ds_read_b128 v[216:219], v147
	ds_read_b128 v[220:223], v147 offset:1024
	ds_read_b128 v[224:227], v147 offset:2048
	ds_read_b128 v[228:231], v147 offset:3072
	global_load_lds_dwordx4 v[142:143], off
	v_lshl_add_u64 v[142:143], v[196:197], 0, s[52:53]
	s_add_i32 m0, s17, 0x2000
	s_nop 0
	global_load_lds_dwordx4 v[142:143], off
	s_mov_b32 m0, s30
	v_lshl_add_u64 v[142:143], v[232:233], 0, s[52:53]
	s_setprio 1
	s_barrier
	s_waitcnt lgkmcnt(0)
	v_mfma_f32_16x16x32_bf16 v[116:119], v[216:219], v[168:171], v[116:119]
	v_mfma_f32_16x16x32_bf16 v[116:119], v[220:223], v[172:175], v[116:119]
	v_mfma_f32_16x16x32_bf16 v[100:103], v[216:219], v[176:179], v[100:103]
	v_mfma_f32_16x16x32_bf16 v[100:103], v[220:223], v[180:183], v[100:103]
	v_mfma_f32_16x16x32_bf16 v[84:87], v[216:219], v[184:187], v[84:87]
	v_mfma_f32_16x16x32_bf16 v[84:87], v[220:223], v[188:191], v[84:87]
	v_mfma_f32_16x16x32_bf16 v[72:75], v[216:219], v[192:195], v[72:75]
	v_mfma_f32_16x16x32_bf16 v[72:75], v[220:223], v[212:215], v[72:75]
	v_mfma_f32_16x16x32_bf16 v[108:111], v[224:227], v[168:171], v[108:111]
	v_mfma_f32_16x16x32_bf16 v[108:111], v[228:231], v[172:175], v[108:111]
	v_mfma_f32_16x16x32_bf16 v[92:95], v[224:227], v[176:179], v[92:95]
	v_mfma_f32_16x16x32_bf16 v[92:95], v[228:231], v[180:183], v[92:95]
	v_mfma_f32_16x16x32_bf16 v[76:79], v[224:227], v[184:187], v[76:79]
	v_mfma_f32_16x16x32_bf16 v[76:79], v[228:231], v[188:191], v[76:79]
	v_mfma_f32_16x16x32_bf16 v[68:71], v[224:227], v[192:195], v[68:71]
	v_mfma_f32_16x16x32_bf16 v[68:71], v[228:231], v[212:215], v[68:71]
	s_barrier
	s_setprio 0
	ds_read_b128 v[168:171], v146 offset:49152
	ds_read_b128 v[172:175], v146 offset:50176
	ds_read_b128 v[176:179], v146 offset:51200
	ds_read_b128 v[180:183], v146 offset:52224
	ds_read_b128 v[184:187], v146 offset:53248
	ds_read_b128 v[188:191], v146 offset:54272
	ds_read_b128 v[192:195], v146 offset:55296
	ds_read_b128 v[212:215], v146 offset:56320
	global_load_lds_dwordx4 v[142:143], off
	v_lshl_add_u64 v[142:143], v[234:235], 0, s[52:53]
	s_mov_b32 m0, s31
	s_nop 0
	global_load_lds_dwordx4 v[142:143], off
	s_setprio 1
	s_barrier
; #define PG8_WAIT_V(n) asm volatile("s_waitcnt vmcnt(" #n ")" ::: "memory")
; #define PG8_WAIT_L(n) asm volatile("s_waitcnt lgkmcnt(" #n ")" ::: "memory")
; #define PG8_BAR __builtin_amdgcn_s_barrier()
; #define PG8_SCHED __builtin_amdgcn_sched_barrier(0)
; template <class Epi, class AddrA, class AddrB>
; __device__ __forceinline__ void gemm_phase(const Sched S, const int lda, const int ldb, const int K, const AddrA addrA,
;                                            const AddrB addrB, const Epi E) {
;     ...
;     for (int t = 0; t < nt; t += 2) {
;       const bool last = (t == nt - 2);
;       const char* a1 = cA + (size_t)(t + 1) * kstep;
;       const char* a2 = last ? nA : cA + (size_t)(t + 2) * kstep;
;       const char* b2 = last ? nB : cB + (size_t)(t + 2) * kstep;
;       const char* a3 = a2 + kstep;
;       const char* b3 = b2 + kstep;
;       PG8_LDB(B0, 0, 0); PG8_SCHED; PG8_LDA(At, 0, 0); PG8_STAGE(PG8_SA(1, 1), a1 + hstepA, voffA);
;       PG8_WAIT_L(8); PG8_BAR; PG8_WAIT_L(0); PG8_MMA(0, 0, At, B0); PG8_BAR; PG8_SCHED;
;       PG8_LDB(B1, 0, 1); PG8_STAGE(PG8_SB(0, 0), b2, voffB);
;       PG8_BAR; PG8_WAIT_L(0); PG8_MMA(0, 1, At, B1); PG8_BAR;
;       PG8_LDA(At, 0, 1); PG8_STAGE(PG8_SA(0, 0), a2, voffA);
;       PG8_BAR; PG8_WAIT_L(0); PG8_MMA(1, 0, At, B0); PG8_BAR; PG8_SCHED;
;       PG8_STAGE(PG8_SB(0, 1), b2 + hstepB, voffB);
;       PG8_WAIT_V(6); PG8_BAR; PG8_MMA(1, 1, At, B1); PG8_BAR;
;       PG8_LDB(B0, 1, 0); PG8_SCHED; PG8_LDA(At, 1, 0); PG8_STAGE(PG8_SA(0, 1), a2 + hstepA, voffA);
;       PG8_WAIT_L(8); PG8_BAR; PG8_WAIT_L(0); PG8_MMA(0, 0, At, B0); PG8_BAR; PG8_SCHED;
;       PG8_LDB(B1, 1, 1); PG8_STAGE(PG8_SB(1, 0), b3, voffB);
;       PG8_BAR; PG8_WAIT_L(0); PG8_MMA(0, 1, At, B1); PG8_BAR;
;       PG8_LDA(At, 1, 1); PG8_STAGE(PG8_SA(1, 0), a3, voffA);
;       PG8_BAR; PG8_WAIT_L(0); PG8_MMA(1, 0, At, B0); PG8_BAR; PG8_SCHED;
;       PG8_STAGE(PG8_SB(1, 1), b3 + hstepB, voffB);
;       PG8_WAIT_V(6); PG8_BAR; PG8_MMA(1, 1, At, B1); PG8_BAR;
	s_waitcnt lgkmcnt(0)
	v_mfma_f32_16x16x32_bf16 v[64:67], v[148:151], v[168:171], v[64:67]
	v_mfma_f32_16x16x32_bf16 v[64:67], v[152:155], v[172:175], v[64:67]
	v_mfma_f32_16x16x32_bf16 v[56:59], v[148:151], v[176:179], v[56:59]
	v_mfma_f32_16x16x32_bf16 v[56:59], v[152:155], v[180:183], v[56:59]
	v_mfma_f32_16x16x32_bf16 v[40:43], v[148:151], v[184:187], v[40:43]
	v_mfma_f32_16x16x32_bf16 v[40:43], v[152:155], v[188:191], v[40:43]
	v_mfma_f32_16x16x32_bf16 v[24:27], v[148:151], v[192:195], v[24:27]
	v_mfma_f32_16x16x32_bf16 v[24:27], v[152:155], v[212:215], v[24:27]
	v_mfma_f32_16x16x32_bf16 v[60:63], v[156:159], v[168:171], v[60:63]
	v_mfma_f32_16x16x32_bf16 v[60:63], v[160:163], v[172:175], v[60:63]
	v_mfma_f32_16x16x32_bf16 v[48:51], v[156:159], v[176:179], v[48:51]
	v_mfma_f32_16x16x32_bf16 v[48:51], v[160:163], v[180:183], v[48:51]
	v_mfma_f32_16x16x32_bf16 v[32:35], v[156:159], v[184:187], v[32:35]
	v_mfma_f32_16x16x32_bf16 v[32:35], v[160:163], v[188:191], v[32:35]
	v_mfma_f32_16x16x32_bf16 v[16:19], v[156:159], v[192:195], v[16:19]
	v_mfma_f32_16x16x32_bf16 v[16:19], v[160:163], v[212:215], v[16:19]
	s_barrier
	s_setprio 0
	s_add_u32 s14, s14, 0x80080
	s_addc_u32 s15, s15, 0
	s_add_i32 s16, s16, s19
	v_lshl_add_u64 v[142:143], s[14:15], 0, v[134:135]
	s_mov_b32 m0, s16
	s_nop 0
	global_load_lds_dwordx4 v[142:143], off
	v_lshl_add_u64 v[142:143], s[14:15], 0, v[0:1]
	s_add_i32 m0, s16, 0x2000
	s_nop 0
	global_load_lds_dwordx4 v[142:143], off
	s_add_i32 s39, s39, 2
	s_add_u32 s37, s37, 0x100
	s_addc_u32 s38, s38, 0
	s_add_u32 s12, s12, 0x100
	s_addc_u32 s13, s13, 0
	s_waitcnt vmcnt(6)
	s_setprio 1
	s_barrier
	v_mfma_f32_16x16x32_bf16 v[52:55], v[216:219], v[168:171], v[52:55]
	v_mfma_f32_16x16x32_bf16 v[52:55], v[220:223], v[172:175], v[52:55]
	v_mfma_f32_16x16x32_bf16 v[36:39], v[216:219], v[176:179], v[36:39]
	v_mfma_f32_16x16x32_bf16 v[36:39], v[220:223], v[180:183], v[36:39]
	v_mfma_f32_16x16x32_bf16 v[20:23], v[216:219], v[184:187], v[20:23]
	v_mfma_f32_16x16x32_bf16 v[20:23], v[220:223], v[188:191], v[20:23]
	v_mfma_f32_16x16x32_bf16 v[8:11], v[216:219], v[192:195], v[8:11]
	v_mfma_f32_16x16x32_bf16 v[8:11], v[220:223], v[212:215], v[8:11]
	v_mfma_f32_16x16x32_bf16 v[44:47], v[224:227], v[168:171], v[44:47]
	v_mfma_f32_16x16x32_bf16 v[44:47], v[228:231], v[172:175], v[44:47]
	v_mfma_f32_16x16x32_bf16 v[28:31], v[224:227], v[176:179], v[28:31]
	v_mfma_f32_16x16x32_bf16 v[28:31], v[228:231], v[180:183], v[28:31]
	v_mfma_f32_16x16x32_bf16 v[12:15], v[224:227], v[184:187], v[12:15]
	v_mfma_f32_16x16x32_bf16 v[12:15], v[228:231], v[188:191], v[12:15]
	v_mfma_f32_16x16x32_bf16 v[4:7], v[224:227], v[192:195], v[4:7]
	v_mfma_f32_16x16x32_bf16 v[4:7], v[228:231], v[212:215], v[4:7]
	s_barrier
	s_setprio 0
	s_cmp_gt_u32 s39, 29
.LBB0_109:
	s_add_i32 s40, 0, 0x10000
	v_add_u32_e32 v142, s40, v145
	ds_read_b128 v[148:151], v142
	ds_read_b128 v[152:155], v142 offset:1024
	ds_read_b128 v[156:159], v142 offset:2048
	ds_read_b128 v[160:163], v142 offset:3072
	v_lshl_add_u64 v[142:143], s[12:13], 0, v[140:141]
	s_add_i32 m0, s24, 0xc000
	ds_read_b128 v[168:171], v146
	ds_read_b128 v[172:175], v146 offset:1024
	ds_read_b128 v[176:179], v146 offset:2048
	ds_read_b128 v[180:183], v146 offset:3072
	ds_read_b128 v[184:187], v146 offset:4096
	ds_read_b128 v[188:191], v146 offset:5120
	ds_read_b128 v[192:195], v146 offset:6144
	ds_read_b128 v[212:215], v146 offset:7168
	global_load_lds_dwordx4 v[142:143], off
	v_lshl_add_u64 v[142:143], s[12:13], 0, v[138:139]
	s_add_i32 m0, s24, 0xe000
	s_nop 0
	global_load_lds_dwordx4 v[142:143], off
	s_waitcnt lgkmcnt(8)
	s_setprio 1
	s_barrier
	s_waitcnt lgkmcnt(0)
	v_mfma_f32_16x16x32_bf16 v[128:131], v[148:151], v[168:171], v[128:131]
	v_mfma_f32_16x16x32_bf16 v[128:131], v[152:155], v[172:175], v[128:131]
	v_mfma_f32_16x16x32_bf16 v[120:123], v[148:151], v[176:179], v[120:123]
	v_mfma_f32_16x16x32_bf16 v[120:123], v[152:155], v[180:183], v[120:123]
	v_mfma_f32_16x16x32_bf16 v[104:107], v[148:151], v[184:187], v[104:107]
	v_mfma_f32_16x16x32_bf16 v[104:107], v[152:155], v[188:191], v[104:107]
	v_mfma_f32_16x16x32_bf16 v[88:91], v[148:151], v[192:195], v[88:91]
	v_mfma_f32_16x16x32_bf16 v[88:91], v[152:155], v[212:215], v[88:91]
	v_mfma_f32_16x16x32_bf16 v[124:127], v[156:159], v[168:171], v[124:127]
	v_mfma_f32_16x16x32_bf16 v[124:127], v[160:163], v[172:175], v[124:127]
	v_mfma_f32_16x16x32_bf16 v[112:115], v[156:159], v[176:179], v[112:115]
	v_mfma_f32_16x16x32_bf16 v[112:115], v[160:163], v[180:183], v[112:115]
	v_mfma_f32_16x16x32_bf16 v[96:99], v[156:159], v[184:187], v[96:99]
	v_mfma_f32_16x16x32_bf16 v[96:99], v[160:163], v[188:191], v[96:99]
	v_mfma_f32_16x16x32_bf16 v[80:83], v[156:159], v[192:195], v[80:83]
	v_mfma_f32_16x16x32_bf16 v[80:83], v[160:163], v[212:215], v[80:83]
	s_barrier
	s_setprio 0
	s_add_u32 s14, s12, 0xfff80080
	s_addc_u32 s15, s13, -1
	s_cmp_eq_u32 s39, 28
	s_cselect_b32 s17, s1, s15
	s_cselect_b32 s16, s11, s14
	s_cselect_b32 s15, s3, s38
	s_cselect_b32 s14, s36, s37
	s_add_i32 s42, 0, 0x14000
	v_add_u32_e32 v142, s42, v145
	s_add_i32 s40, s40, s19
	ds_read_b128 v[216:219], v142
	ds_read_b128 v[220:223], v142 offset:1024
	ds_read_b128 v[224:227], v142 offset:2048
	ds_read_b128 v[228:231], v142 offset:3072
	v_lshl_add_u64 v[142:143], s[14:15], 0, v[134:135]
	s_mov_b32 m0, s40
	v_lshl_add_u64 v[196:197], s[14:15], 0, v[0:1]
	global_load_lds_dwordx4 v[142:143], off
	s_add_i32 m0, s40, 0x2000
	s_nop 0
	global_load_lds_dwordx4 v[196:197], off
	s_mov_b32 m0, s24
	v_lshl_add_u64 v[232:233], s[16:17], 0, v[136:137]
	s_setprio 1
	s_barrier
; #define PG8_WAIT_V(n) asm volatile("s_waitcnt vmcnt(" #n ")" ::: "memory")
; #define PG8_WAIT_L(n) asm volatile("s_waitcnt lgkmcnt(" #n ")" ::: "memory")
; #define PG8_BAR __builtin_amdgcn_s_barrier()
; #define PG8_SCHED __builtin_amdgcn_sched_barrier(0)
; template <class Epi, class AddrA, class AddrB>
; __device__ __forceinline__ void gemm_phase(const Sched S, const int lda, const int ldb, const int K, const AddrA addrA,
;                                            const AddrB addrB, const Epi E) {
;     ...
;       PG8_LDB(B0, 0, 0); PG8_SCHED; PG8_LDA(At, 0, 0); PG8_STAGE(PG8_SA(1, 1), a1 + hstepA, voffA);
;       PG8_WAIT_L(8); PG8_BAR; PG8_WAIT_L(0); PG8_MMA(0, 0, At, B0); PG8_BAR; PG8_SCHED;
;       PG8_LDB(B1, 0, 1); PG8_STAGE(PG8_SB(0, 0), b2, voffB);
;       PG8_BAR; PG8_WAIT_L(0); PG8_MMA(0, 1, At, B1); PG8_BAR;
;       PG8_LDA(At, 0, 1); PG8_STAGE(PG8_SA(0, 0), a2, voffA);
;       PG8_BAR; PG8_WAIT_L(0); PG8_MMA(1, 0, At, B0); PG8_BAR; PG8_SCHED;
;       PG8_STAGE(PG8_SB(0, 1), b2 + hstepB, voffB);
;       PG8_WAIT_V(6); PG8_BAR; PG8_MMA(1, 1, At, B1); PG8_BAR;
;       PG8_LDB(B0, 1, 0); PG8_SCHED; PG8_LDA(At, 1, 0); PG8_STAGE(PG8_SA(0, 1), a2 + hstepA, voffA);
;       PG8_WAIT_L(8); PG8_BAR; PG8_WAIT_L(0); PG8_MMA(0, 0, At, B0); PG8_BAR; PG8_SCHED;
;       PG8_LDB(B1, 1, 1); PG8_STAGE(PG8_SB(1, 0), b3, voffB);
;       PG8_BAR; PG8_WAIT_L(0); PG8_MMA(0, 1, At, B1); PG8_BAR;
;       PG8_LDA(At, 1, 1); PG8_STAGE(PG8_SA(1, 0), a3, voffA);
;       PG8_BAR; PG8_WAIT_L(0); PG8_MMA(1, 0, At, B0); PG8_BAR; PG8_SCHED;
;       PG8_STAGE(PG8_SB(1, 1), b3 + hstepB, voffB);
;       PG8_WAIT_V(6); PG8_BAR; PG8_MMA(1, 1, At, B1); PG8_BAR;
	s_waitcnt lgkmcnt(0)
	v_mfma_f32_16x16x32_bf16 v[116:119], v[216:219], v[168:171], v[116:119]
	v_mfma_f32_16x16x32_bf16 v[116:119], v[220:223], v[172:175], v[116:119]
	v_mfma_f32_16x16x32_bf16 v[100:103], v[216:219], v[176:179], v[100:103]
	v_mfma_f32_16x16x32_bf16 v[100:103], v[220:223], v[180:183], v[100:103]
	v_mfma_f32_16x16x32_bf16 v[84:87], v[216:219], v[184:187], v[84:87]
	v_mfma_f32_16x16x32_bf16 v[84:87], v[220:223], v[188:191], v[84:87]
	v_mfma_f32_16x16x32_bf16 v[72:75], v[216:219], v[192:195], v[72:75]
	v_mfma_f32_16x16x32_bf16 v[72:75], v[220:223], v[212:215], v[72:75]
	v_mfma_f32_16x16x32_bf16 v[108:111], v[224:227], v[168:171], v[108:111]
	v_mfma_f32_16x16x32_bf16 v[108:111], v[228:231], v[172:175], v[108:111]
	v_mfma_f32_16x16x32_bf16 v[92:95], v[224:227], v[176:179], v[92:95]
	v_mfma_f32_16x16x32_bf16 v[92:95], v[228:231], v[180:183], v[92:95]
	v_mfma_f32_16x16x32_bf16 v[76:79], v[224:227], v[184:187], v[76:79]
	v_mfma_f32_16x16x32_bf16 v[76:79], v[228:231], v[188:191], v[76:79]
	v_mfma_f32_16x16x32_bf16 v[68:71], v[224:227], v[192:195], v[68:71]
	v_mfma_f32_16x16x32_bf16 v[68:71], v[228:231], v[212:215], v[68:71]
	s_barrier
	s_setprio 0
	ds_read_b128 v[168:171], v146 offset:16384
	ds_read_b128 v[172:175], v146 offset:17408
	ds_read_b128 v[176:179], v146 offset:18432
	ds_read_b128 v[180:183], v146 offset:19456
	ds_read_b128 v[184:187], v146 offset:20480
	ds_read_b128 v[188:191], v146 offset:21504
	ds_read_b128 v[192:195], v146 offset:22528
	ds_read_b128 v[212:215], v146 offset:23552
	global_load_lds_dwordx4 v[232:233], off
	v_lshl_add_u64 v[234:235], s[16:17], 0, v[132:133]
	s_mov_b32 m0, s25
	s_nop 0
	global_load_lds_dwordx4 v[234:235], off
	s_setprio 1
	s_barrier
	s_waitcnt lgkmcnt(0)
	v_mfma_f32_16x16x32_bf16 v[64:67], v[148:151], v[168:171], v[64:67]
	v_mfma_f32_16x16x32_bf16 v[64:67], v[152:155], v[172:175], v[64:67]
	v_mfma_f32_16x16x32_bf16 v[56:59], v[148:151], v[176:179], v[56:59]
	v_mfma_f32_16x16x32_bf16 v[56:59], v[152:155], v[180:183], v[56:59]
	v_mfma_f32_16x16x32_bf16 v[40:43], v[148:151], v[184:187], v[40:43]
	v_mfma_f32_16x16x32_bf16 v[40:43], v[152:155], v[188:191], v[40:43]
	v_mfma_f32_16x16x32_bf16 v[24:27], v[148:151], v[192:195], v[24:27]
	v_mfma_f32_16x16x32_bf16 v[24:27], v[152:155], v[212:215], v[24:27]
	v_mfma_f32_16x16x32_bf16 v[60:63], v[156:159], v[168:171], v[60:63]
	v_mfma_f32_16x16x32_bf16 v[60:63], v[160:163], v[172:175], v[60:63]
	v_mfma_f32_16x16x32_bf16 v[48:51], v[156:159], v[176:179], v[48:51]
	v_mfma_f32_16x16x32_bf16 v[48:51], v[160:163], v[180:183], v[48:51]
	v_mfma_f32_16x16x32_bf16 v[32:35], v[156:159], v[184:187], v[32:35]
	v_mfma_f32_16x16x32_bf16 v[32:35], v[160:163], v[188:191], v[32:35]
	v_mfma_f32_16x16x32_bf16 v[16:19], v[156:159], v[192:195], v[16:19]
	v_mfma_f32_16x16x32_bf16 v[16:19], v[160:163], v[212:215], v[16:19]
	s_barrier
	s_setprio 0
	s_add_u32 s40, s14, 0x80000
	s_addc_u32 s41, s15, 0
	s_add_i32 s42, s42, s19
	v_lshl_add_u64 v[148:149], s[40:41], 0, v[134:135]
	s_mov_b32 m0, s42
	s_nop 0
	global_load_lds_dwordx4 v[148:149], off
	v_lshl_add_u64 v[148:149], s[40:41], 0, v[0:1]
	s_add_i32 m0, s42, 0x2000
	s_nop 0
	global_load_lds_dwordx4 v[148:149], off
	s_add_i32 s40, 0, 0x18000
	v_add_u32_e32 v147, s40, v145
	s_waitcnt vmcnt(6)
	s_setprio 1
	s_barrier
	v_mfma_f32_16x16x32_bf16 v[52:55], v[216:219], v[168:171], v[52:55]
	v_mfma_f32_16x16x32_bf16 v[52:55], v[220:223], v[172:175], v[52:55]
	v_mfma_f32_16x16x32_bf16 v[36:39], v[216:219], v[176:179], v[36:39]
	v_mfma_f32_16x16x32_bf16 v[36:39], v[220:223], v[180:183], v[36:39]
	v_mfma_f32_16x16x32_bf16 v[20:23], v[216:219], v[184:187], v[20:23]
	v_mfma_f32_16x16x32_bf16 v[20:23], v[220:223], v[188:191], v[20:23]
	v_mfma_f32_16x16x32_bf16 v[8:11], v[216:219], v[192:195], v[8:11]
	v_mfma_f32_16x16x32_bf16 v[8:11], v[220:223], v[212:215], v[8:11]
	v_mfma_f32_16x16x32_bf16 v[44:47], v[224:227], v[168:171], v[44:47]
	v_mfma_f32_16x16x32_bf16 v[44:47], v[228:231], v[172:175], v[44:47]
	v_mfma_f32_16x16x32_bf16 v[28:31], v[224:227], v[176:179], v[28:31]
	v_mfma_f32_16x16x32_bf16 v[28:31], v[228:231], v[180:183], v[28:31]
	v_mfma_f32_16x16x32_bf16 v[12:15], v[224:227], v[184:187], v[12:15]
	v_mfma_f32_16x16x32_bf16 v[12:15], v[228:231], v[188:191], v[12:15]
	v_mfma_f32_16x16x32_bf16 v[4:7], v[224:227], v[192:195], v[4:7]
	v_mfma_f32_16x16x32_bf16 v[4:7], v[228:231], v[212:215], v[4:7]
	s_barrier
	s_setprio 0
	ds_read_b128 v[148:151], v147
	ds_read_b128 v[152:155], v147 offset:1024
	ds_read_b128 v[156:159], v147 offset:2048
	ds_read_b128 v[160:163], v147 offset:3072
	s_add_u32 s16, s16, 0x80000
	s_addc_u32 s17, s17, 0
	s_mov_b32 m0, s26
	v_lshl_add_u64 v[216:217], s[16:17], 0, v[136:137]
	ds_read_b128 v[168:171], v146 offset:32768
	ds_read_b128 v[172:175], v146 offset:33792
	ds_read_b128 v[176:179], v146 offset:34816
	ds_read_b128 v[180:183], v146 offset:35840
	ds_read_b128 v[184:187], v146 offset:36864
	ds_read_b128 v[188:191], v146 offset:37888
	ds_read_b128 v[192:195], v146 offset:38912
	ds_read_b128 v[212:215], v146 offset:39936
	global_load_lds_dwordx4 v[216:217], off
	v_lshl_add_u64 v[216:217], s[16:17], 0, v[132:133]
	s_mov_b32 m0, s27
	s_nop 0
	global_load_lds_dwordx4 v[216:217], off
	s_waitcnt lgkmcnt(8)
	s_setprio 1
	s_barrier
; #define PG8_WAIT_V(n) asm volatile("s_waitcnt vmcnt(" #n ")" ::: "memory")
; #define PG8_WAIT_L(n) asm volatile("s_waitcnt lgkmcnt(" #n ")" ::: "memory")
; #define PG8_BAR __builtin_amdgcn_s_barrier()
; #define PG8_SCHED __builtin_amdgcn_sched_barrier(0)
; template <class Epi, class AddrA, class AddrB>
; __device__ __forceinline__ void gemm_phase(const Sched S, const int lda, const int ldb, const int K, const AddrA addrA,
;                                            const AddrB addrB, const Epi E) {
;     ...
;       PG8_LDB(B0, 0, 0); PG8_SCHED; PG8_LDA(At, 0, 0); PG8_STAGE(PG8_SA(1, 1), a1 + hstepA, voffA);
;       PG8_WAIT_L(8); PG8_BAR; PG8_WAIT_L(0); PG8_MMA(0, 0, At, B0); PG8_BAR; PG8_SCHED;
;       PG8_LDB(B1, 0, 1); PG8_STAGE(PG8_SB(0, 0), b2, voffB);
;       PG8_BAR; PG8_WAIT_L(0); PG8_MMA(0, 1, At, B1); PG8_BAR;
;       PG8_LDA(At, 0, 1); PG8_STAGE(PG8_SA(0, 0), a2, voffA);
;       PG8_BAR; PG8_WAIT_L(0); PG8_MMA(1, 0, At, B0); PG8_BAR; PG8_SCHED;
;       PG8_STAGE(PG8_SB(0, 1), b2 + hstepB, voffB);
;       PG8_WAIT_V(6); PG8_BAR; PG8_MMA(1, 1, At, B1); PG8_BAR;
;       PG8_LDB(B0, 1, 0); PG8_SCHED; PG8_LDA(At, 1, 0); PG8_STAGE(PG8_SA(0, 1), a2 + hstepA, voffA);
;       PG8_WAIT_L(8); PG8_BAR; PG8_WAIT_L(0); PG8_MMA(0, 0, At, B0); PG8_BAR; PG8_SCHED;
;       PG8_LDB(B1, 1, 1); PG8_STAGE(PG8_SB(1, 0), b3, voffB);
;       PG8_BAR; PG8_WAIT_L(0); PG8_MMA(0, 1, At, B1); PG8_BAR;
;       PG8_LDA(At, 1, 1); PG8_STAGE(PG8_SA(1, 0), a3, voffA);
;       PG8_BAR; PG8_WAIT_L(0); PG8_MMA(1, 0, At, B0); PG8_BAR; PG8_SCHED;
;       PG8_STAGE(PG8_SB(1, 1), b3 + hstepB, voffB);
;       PG8_WAIT_V(6); PG8_BAR; PG8_MMA(1, 1, At, B1); PG8_BAR;
	s_waitcnt lgkmcnt(0)
	v_mfma_f32_16x16x32_bf16 v[128:131], v[148:151], v[168:171], v[128:131]
	v_mfma_f32_16x16x32_bf16 v[128:131], v[152:155], v[172:175], v[128:131]
	v_mfma_f32_16x16x32_bf16 v[120:123], v[148:151], v[176:179], v[120:123]
	v_mfma_f32_16x16x32_bf16 v[120:123], v[152:155], v[180:183], v[120:123]
	v_mfma_f32_16x16x32_bf16 v[104:107], v[148:151], v[184:187], v[104:107]
	v_mfma_f32_16x16x32_bf16 v[104:107], v[152:155], v[188:191], v[104:107]
	v_mfma_f32_16x16x32_bf16 v[88:91], v[148:151], v[192:195], v[88:91]
	v_mfma_f32_16x16x32_bf16 v[88:91], v[152:155], v[212:215], v[88:91]
	v_mfma_f32_16x16x32_bf16 v[124:127], v[156:159], v[168:171], v[124:127]
	v_mfma_f32_16x16x32_bf16 v[124:127], v[160:163], v[172:175], v[124:127]
	v_mfma_f32_16x16x32_bf16 v[112:115], v[156:159], v[176:179], v[112:115]
	v_mfma_f32_16x16x32_bf16 v[112:115], v[160:163], v[180:183], v[112:115]
	v_mfma_f32_16x16x32_bf16 v[96:99], v[156:159], v[184:187], v[96:99]
	v_mfma_f32_16x16x32_bf16 v[96:99], v[160:163], v[188:191], v[96:99]
	v_mfma_f32_16x16x32_bf16 v[80:83], v[156:159], v[192:195], v[80:83]
	v_mfma_f32_16x16x32_bf16 v[80:83], v[160:163], v[212:215], v[80:83]
	s_barrier
	s_setprio 0
	s_add_i32 s16, 0, 0x1c000
	s_add_i32 s17, s40, s19
	v_add_u32_e32 v147, s16, v145
	v_lshl_add_u64 v[142:143], v[142:143], 0, s[52:53]
	s_mov_b32 m0, s17
	ds_read_b128 v[216:219], v147
	ds_read_b128 v[220:223], v147 offset:1024
	ds_read_b128 v[224:227], v147 offset:2048
	ds_read_b128 v[228:231], v147 offset:3072
	global_load_lds_dwordx4 v[142:143], off
	v_lshl_add_u64 v[142:143], v[196:197], 0, s[52:53]
	s_add_i32 m0, s17, 0x2000
	s_nop 0
	global_load_lds_dwordx4 v[142:143], off
	s_mov_b32 m0, s30
	v_lshl_add_u64 v[142:143], v[232:233], 0, s[52:53]
	s_setprio 1
	s_barrier
	s_waitcnt lgkmcnt(0)
	v_mfma_f32_16x16x32_bf16 v[116:119], v[216:219], v[168:171], v[116:119]
	v_mfma_f32_16x16x32_bf16 v[116:119], v[220:223], v[172:175], v[116:119]
	v_mfma_f32_16x16x32_bf16 v[100:103], v[216:219], v[176:179], v[100:103]
	v_mfma_f32_16x16x32_bf16 v[100:103], v[220:223], v[180:183], v[100:103]
	v_mfma_f32_16x16x32_bf16 v[84:87], v[216:219], v[184:187], v[84:87]
	v_mfma_f32_16x16x32_bf16 v[84:87], v[220:223], v[188:191], v[84:87]
	v_mfma_f32_16x16x32_bf16 v[72:75], v[216:219], v[192:195], v[72:75]
	v_mfma_f32_16x16x32_bf16 v[72:75], v[220:223], v[212:215], v[72:75]
	v_mfma_f32_16x16x32_bf16 v[108:111], v[224:227], v[168:171], v[108:111]
	v_mfma_f32_16x16x32_bf16 v[108:111], v[228:231], v[172:175], v[108:111]
	v_mfma_f32_16x16x32_bf16 v[92:95], v[224:227], v[176:179], v[92:95]
	v_mfma_f32_16x16x32_bf16 v[92:95], v[228:231], v[180:183], v[92:95]
	v_mfma_f32_16x16x32_bf16 v[76:79], v[224:227], v[184:187], v[76:79]
	v_mfma_f32_16x16x32_bf16 v[76:79], v[228:231], v[188:191], v[76:79]
	v_mfma_f32_16x16x32_bf16 v[68:71], v[224:227], v[192:195], v[68:71]
	v_mfma_f32_16x16x32_bf16 v[68:71], v[228:231], v[212:215], v[68:71]
	s_barrier
	s_setprio 0
	ds_read_b128 v[168:171], v146 offset:49152
	ds_read_b128 v[172:175], v146 offset:50176
	ds_read_b128 v[176:179], v146 offset:51200
	ds_read_b128 v[180:183], v146 offset:52224
	ds_read_b128 v[184:187], v146 offset:53248
	ds_read_b128 v[188:191], v146 offset:54272
	ds_read_b128 v[192:195], v146 offset:55296
	ds_read_b128 v[212:215], v146 offset:56320
	global_load_lds_dwordx4 v[142:143], off
	v_lshl_add_u64 v[142:143], v[234:235], 0, s[52:53]
	s_mov_b32 m0, s31
	s_nop 0
	global_load_lds_dwordx4 v[142:143], off
	s_setprio 1
	s_barrier
	s_waitcnt lgkmcnt(0)
	v_mfma_f32_16x16x32_bf16 v[64:67], v[148:151], v[168:171], v[64:67]
	v_mfma_f32_16x16x32_bf16 v[64:67], v[152:155], v[172:175], v[64:67]
	v_mfma_f32_16x16x32_bf16 v[56:59], v[148:151], v[176:179], v[56:59]
	v_mfma_f32_16x16x32_bf16 v[56:59], v[152:155], v[180:183], v[56:59]
	v_mfma_f32_16x16x32_bf16 v[40:43], v[148:151], v[184:187], v[40:43]
	v_mfma_f32_16x16x32_bf16 v[40:43], v[152:155], v[188:191], v[40:43]
	v_mfma_f32_16x16x32_bf16 v[24:27], v[148:151], v[192:195], v[24:27]
	v_mfma_f32_16x16x32_bf16 v[24:27], v[152:155], v[212:215], v[24:27]
	v_mfma_f32_16x16x32_bf16 v[60:63], v[156:159], v[168:171], v[60:63]
	v_mfma_f32_16x16x32_bf16 v[60:63], v[160:163], v[172:175], v[60:63]
	v_mfma_f32_16x16x32_bf16 v[48:51], v[156:159], v[176:179], v[48:51]
	v_mfma_f32_16x16x32_bf16 v[48:51], v[160:163], v[180:183], v[48:51]
	v_mfma_f32_16x16x32_bf16 v[32:35], v[156:159], v[184:187], v[32:35]
	v_mfma_f32_16x16x32_bf16 v[32:35], v[160:163], v[188:191], v[32:35]
	v_mfma_f32_16x16x32_bf16 v[16:19], v[156:159], v[192:195], v[16:19]
	v_mfma_f32_16x16x32_bf16 v[16:19], v[160:163], v[212:215], v[16:19]
	s_barrier
	s_setprio 0
	s_add_u32 s14, s14, 0x80080
	s_addc_u32 s15, s15, 0
	s_add_i32 s16, s16, s19
	v_lshl_add_u64 v[142:143], s[14:15], 0, v[134:135]
	s_mov_b32 m0, s16
	s_nop 0
	global_load_lds_dwordx4 v[142:143], off
	v_lshl_add_u64 v[142:143], s[14:15], 0, v[0:1]
	s_add_i32 m0, s16, 0x2000
	s_nop 0
	global_load_lds_dwordx4 v[142:143], off
	s_add_i32 s39, s39, 2
	s_add_u32 s37, s37, 0x100
	s_addc_u32 s38, s38, 0
	s_add_u32 s12, s12, 0x100
	s_addc_u32 s13, s13, 0
	s_waitcnt vmcnt(6)
	s_setprio 1
	s_barrier
; #define PG8_WAIT_V(n) asm volatile("s_waitcnt vmcnt(" #n ")" ::: "memory")
; #define PG8_BAR __builtin_amdgcn_s_barrier()
; template <class Epi, class AddrA, class AddrB>
; __device__ __forceinline__ void gemm_phase(const Sched S, const int lda, const int ldb, const int K, const AddrA addrA,
;                                            const AddrB addrB, const Epi E) {
;     ...
;       PG8_WAIT_V(6); PG8_BAR; PG8_MMA(1, 1, At, B1); PG8_BAR;
;     }
;     E(acc, cur, wr, wc, fr, fq);
;     if (!has_next) break;
;   __device__ __forceinline__ void operator()(EPI_ARGS) const {
;     bf16_t* base = proj + ((size_t)u.pn * MTOK + (size_t)(u.pm * 256 + wr * 64 + fr)) * PLD + wc * 32 + 8 * fq;
; #pragma unroll
;     for (int ai = 0; ai < 2; ++ai)
; #pragma unroll
;       for (int m = 0; m < 4; ++m) {
;         bf16_t* rowp = base + (size_t)(ai * HALF + m * 16) * PLD;
; #pragma unroll
;         for (int bj = 0; bj < 2; ++bj) {
;           const f32x4 v0 = acc[ai][bj][m][0], v1 = acc[ai][bj][m][1];
;           u32x4 o;
;           o.x = pack2(v0[0], v0[1]); o.y = pack2(v0[2], v0[3]); o.z = pack2(v1[0], v1[1]); o.w = pack2(v1[2], v1[3]);
;           *(u32x4*)(rowp + bj * HALF) = o;
;         }
;       }
	v_mfma_f32_16x16x32_bf16 v[52:55], v[216:219], v[168:171], v[52:55]
	v_mfma_f32_16x16x32_bf16 v[52:55], v[220:223], v[172:175], v[52:55]
	v_mfma_f32_16x16x32_bf16 v[36:39], v[216:219], v[176:179], v[36:39]
	v_mfma_f32_16x16x32_bf16 v[36:39], v[220:223], v[180:183], v[36:39]
	v_mfma_f32_16x16x32_bf16 v[20:23], v[216:219], v[184:187], v[20:23]
	v_mfma_f32_16x16x32_bf16 v[20:23], v[220:223], v[188:191], v[20:23]
	v_mfma_f32_16x16x32_bf16 v[8:11], v[216:219], v[192:195], v[8:11]
	v_mfma_f32_16x16x32_bf16 v[8:11], v[220:223], v[212:215], v[8:11]
	v_mfma_f32_16x16x32_bf16 v[44:47], v[224:227], v[168:171], v[44:47]
	v_mfma_f32_16x16x32_bf16 v[44:47], v[228:231], v[172:175], v[44:47]
	v_mfma_f32_16x16x32_bf16 v[28:31], v[224:227], v[176:179], v[28:31]
	v_mfma_f32_16x16x32_bf16 v[28:31], v[228:231], v[180:183], v[28:31]
	v_mfma_f32_16x16x32_bf16 v[12:15], v[224:227], v[184:187], v[12:15]
	v_mfma_f32_16x16x32_bf16 v[12:15], v[228:231], v[188:191], v[12:15]
	v_mfma_f32_16x16x32_bf16 v[4:7], v[224:227], v[192:195], v[4:7]
	v_mfma_f32_16x16x32_bf16 v[4:7], v[228:231], v[212:215], v[4:7]
	s_barrier
	s_setprio 0
	s_cmp_gt_u32 s39, 29
	s_cbranch_scc0 .LBB0_109
	s_ashr_i32 s11, s10, 31
	v_lshl_add_u32 v142, s35, 8, v144
	s_lshl_b64 s[10:11], s[10:11], 23
	v_ashrrev_i32_e32 v143, 31, v142
	s_add_u32 s10, s28, s10
	s_addc_u32 s11, s29, s11
	v_lshlrev_b64 v[142:143], 9, v[142:143]
	v_lshl_add_u64 v[142:143], s[10:11], 0, v[142:143]
	v_lshl_add_u64 v[142:143], v[142:143], 0, s[72:73]
	v_lshl_add_u64 v[142:143], v[142:143], 0, v[2:3]
	v_cvt_pk_bf16_f32 v116, v116, v117
	v_cvt_pk_bf16_f32 v117, v118, v119
	v_cvt_pk_bf16_f32 v119, v110, v111
	v_cvt_pk_bf16_f32 v110, v112, v113
	v_add_co_u32_e32 v112, vcc, s96, v142
	s_movk_i32 s1, 0x4000
	s_nop 0
	v_addc_co_u32_e32 v113, vcc, 0, v143, vcc
	v_cvt_pk_bf16_f32 v100, v100, v101
	v_cvt_pk_bf16_f32 v101, v102, v103
	v_cvt_pk_bf16_f32 v103, v94, v95
	v_cvt_pk_bf16_f32 v94, v96, v97
	v_add_co_u32_e32 v96, vcc, s1, v142
	s_movk_i32 s1, 0x6000
	s_nop 0
	v_addc_co_u32_e32 v97, vcc, 0, v143, vcc
	v_cvt_pk_bf16_f32 v84, v84, v85
	v_cvt_pk_bf16_f32 v85, v86, v87
	v_cvt_pk_bf16_f32 v87, v78, v79
	v_cvt_pk_bf16_f32 v78, v80, v81
	v_add_co_u32_e32 v80, vcc, s1, v142
	v_cvt_pk_bf16_f32 v64, v64, v65
	v_cvt_pk_bf16_f32 v65, v66, v67
	v_cvt_pk_bf16_f32 v66, v60, v61
	s_mov_b32 s1, 0x12000
	s_nop 0
	v_addc_co_u32_e32 v81, vcc, 0, v143, vcc
	v_add_co_u32_e32 v60, vcc, s67, v142
	v_cvt_pk_bf16_f32 v52, v52, v53
	v_cvt_pk_bf16_f32 v53, v54, v55
	v_cvt_pk_bf16_f32 v55, v46, v47
	v_cvt_pk_bf16_f32 v46, v48, v49
	s_nop 1
	v_addc_co_u32_e32 v61, vcc, 0, v143, vcc
	v_add_co_u32_e32 v48, vcc, s1, v142
	s_mov_b32 s1, 0x14000
	s_nop 0
	v_addc_co_u32_e32 v49, vcc, 0, v143, vcc
	v_cvt_pk_bf16_f32 v36, v36, v37
	v_cvt_pk_bf16_f32 v37, v38, v39
	v_cvt_pk_bf16_f32 v39, v30, v31
	v_cvt_pk_bf16_f32 v30, v32, v33
	v_add_co_u32_e32 v32, vcc, s1, v142
	s_mov_b32 s1, 0x16000
	s_nop 0
	v_addc_co_u32_e32 v33, vcc, 0, v143, vcc
	v_cvt_pk_bf16_f32 v20, v20, v21
	v_cvt_pk_bf16_f32 v21, v22, v23
	v_cvt_pk_bf16_f32 v23, v14, v15
	v_cvt_pk_bf16_f32 v14, v16, v17
	v_add_co_u32_e32 v16, vcc, s1, v142
	s_mov_b32 s10, s2
	s_nop 0
	v_addc_co_u32_e32 v17, vcc, 0, v143, vcc
	s_and_b64 vcc, exec, s[4:5]
	s_mov_b32 s35, s0
	s_mov_b64 s[12:13], s[8:9]
	s_mov_b64 s[14:15], s[6:7]
	v_cvt_pk_bf16_f32 v128, v128, v129
	v_cvt_pk_bf16_f32 v129, v130, v131
	v_cvt_pk_bf16_f32 v130, v124, v125
	v_cvt_pk_bf16_f32 v131, v126, v127
	flat_store_dwordx4 v[142:143], v[128:131]
	v_cvt_pk_bf16_f32 v118, v108, v109
	flat_store_dwordx4 v[142:143], v[116:119] offset:256
	v_cvt_pk_bf16_f32 v108, v120, v121
	v_cvt_pk_bf16_f32 v109, v122, v123
	v_cvt_pk_bf16_f32 v111, v114, v115
	flat_store_dwordx4 v[112:113], v[108:111]
	v_cvt_pk_bf16_f32 v102, v92, v93
	flat_store_dwordx4 v[112:113], v[100:103] offset:256
	v_cvt_pk_bf16_f32 v92, v104, v105
	v_cvt_pk_bf16_f32 v93, v106, v107
	v_cvt_pk_bf16_f32 v95, v98, v99
	flat_store_dwordx4 v[96:97], v[92:95]
	v_cvt_pk_bf16_f32 v86, v76, v77
	flat_store_dwordx4 v[96:97], v[84:87] offset:256
	v_cvt_pk_bf16_f32 v76, v88, v89
	v_cvt_pk_bf16_f32 v77, v90, v91
	v_cvt_pk_bf16_f32 v79, v82, v83
	flat_store_dwordx4 v[80:81], v[76:79]
	v_cvt_pk_bf16_f32 v72, v72, v73
	v_cvt_pk_bf16_f32 v73, v74, v75
	v_cvt_pk_bf16_f32 v74, v68, v69
	v_cvt_pk_bf16_f32 v75, v70, v71
	flat_store_dwordx4 v[80:81], v[72:75] offset:256
	v_cvt_pk_bf16_f32 v67, v62, v63
	flat_store_dwordx4 v[60:61], v[64:67]
	v_cvt_pk_bf16_f32 v54, v44, v45
	flat_store_dwordx4 v[60:61], v[52:55] offset:256
	v_cvt_pk_bf16_f32 v44, v56, v57
	v_cvt_pk_bf16_f32 v45, v58, v59
	v_cvt_pk_bf16_f32 v47, v50, v51
	flat_store_dwordx4 v[48:49], v[44:47]
	v_cvt_pk_bf16_f32 v38, v28, v29
	flat_store_dwordx4 v[48:49], v[36:39] offset:256
	v_cvt_pk_bf16_f32 v28, v40, v41
	v_cvt_pk_bf16_f32 v29, v42, v43
	v_cvt_pk_bf16_f32 v31, v34, v35
	flat_store_dwordx4 v[32:33], v[28:31]
	v_cvt_pk_bf16_f32 v22, v12, v13
	flat_store_dwordx4 v[32:33], v[20:23] offset:256
	v_cvt_pk_bf16_f32 v12, v24, v25
	v_cvt_pk_bf16_f32 v13, v26, v27
	v_cvt_pk_bf16_f32 v15, v18, v19
	flat_store_dwordx4 v[16:17], v[12:15]
	v_cvt_pk_bf16_f32 v8, v8, v9
	v_cvt_pk_bf16_f32 v9, v10, v11
	v_cvt_pk_bf16_f32 v10, v4, v5
	v_cvt_pk_bf16_f32 v11, v6, v7
	flat_store_dwordx4 v[16:17], v[8:11] offset:256
	s_cbranch_vccz .LBB0_106
	s_waitcnt vmcnt(0)
	s_cmpk_gt_u32 s18, 0xff
	s_cbranch_scc1 .LBB0_113
	s_barrier

; #define PG8_WAIT_V(n) asm volatile("s_waitcnt vmcnt(" #n ")" ::: "memory")
; #define PG8_WAIT_L(n) asm volatile("s_waitcnt lgkmcnt(" #n ")" ::: "memory")
; #define PG8_BAR __builtin_amdgcn_s_barrier()
; #define PG8_SCHED __builtin_amdgcn_sched_barrier(0)
; template <class Epi, class AddrA, class AddrB>
; __device__ __forceinline__ void gemm_phase(const Sched S, const int lda, const int ldb, const int K, const AddrA addrA,
;                                            const AddrB addrB, const Epi E) {
;     ...
;     for (int t = 0; t < nt; t += 2) {
;       const bool last = (t == nt - 2);
;       const char* a1 = cA + (size_t)(t + 1) * kstep;
;       const char* a2 = last ? nA : cA + (size_t)(t + 2) * kstep;
;       const char* b2 = last ? nB : cB + (size_t)(t + 2) * kstep;
;       const char* a3 = a2 + kstep;
;       const char* b3 = b2 + kstep;
;       PG8_LDB(B0, 0, 0); PG8_SCHED; PG8_LDA(At, 0, 0); PG8_STAGE(PG8_SA(1, 1), a1 + hstepA, voffA);
;       PG8_WAIT_L(8); PG8_BAR; PG8_WAIT_L(0); PG8_MMA(0, 0, At, B0); PG8_BAR; PG8_SCHED;
;       PG8_LDB(B1, 0, 1); PG8_STAGE(PG8_SB(0, 0), b2, voffB);
;       PG8_BAR; PG8_WAIT_L(0); PG8_MMA(0, 1, At, B1); PG8_BAR;
;       PG8_LDA(At, 0, 1); PG8_STAGE(PG8_SA(0, 0), a2, voffA);
;       PG8_BAR; PG8_WAIT_L(0); PG8_MMA(1, 0, At, B0); PG8_BAR; PG8_SCHED;
;       PG8_STAGE(PG8_SB(0, 1), b2 + hstepB, voffB);
;       PG8_WAIT_V(6); PG8_BAR; PG8_MMA(1, 1, At, B1); PG8_BAR;
;       PG8_LDB(B0, 1, 0); PG8_SCHED; PG8_LDA(At, 1, 0); PG8_STAGE(PG8_SA(0, 1), a2 + hstepA, voffA);
;       PG8_WAIT_L(8); PG8_BAR; PG8_WAIT_L(0); PG8_MMA(0, 0, At, B0); PG8_BAR; PG8_SCHED;
;       PG8_LDB(B1, 1, 1); PG8_STAGE(PG8_SB(1, 0), b3, voffB);
;       PG8_BAR; PG8_WAIT_L(0); PG8_MMA(0, 1, At, B1); PG8_BAR;
;       PG8_LDA(At, 1, 1); PG8_STAGE(PG8_SA(1, 0), a3, voffA);
;       PG8_BAR; PG8_WAIT_L(0); PG8_MMA(1, 0, At, B0); PG8_BAR; PG8_SCHED;
;       PG8_STAGE(PG8_SB(1, 1), b3 + hstepB, voffB);
;       PG8_WAIT_V(6); PG8_BAR; PG8_MMA(1, 1, At, B1); PG8_BAR;
.LBB0_484:
	s_ashr_i32 s15, s14, 31
	s_lshl_b64 s[20:21], s[14:15], 20
	s_add_u32 s3, s25, s20
	s_addc_u32 s15, s26, s21
	s_lshl_b32 s17, s16, 8
	s_and_b32 s20, s17, 0xfffffe00
	s_ashr_i32 s21, s20, 31
	s_lshl_b64 s[20:21], s[20:21], 1
	s_add_u32 s20, s3, s20
	s_addc_u32 s21, s15, s21
	s_and_b64 s[22:23], s[10:11], exec
	s_cselect_b32 s3, s21, s7
	s_cselect_b32 s15, s20, s6
	s_ashr_i32 s17, s16, 31
	s_lshl_b64 s[22:23], s[16:17], 18
	s_add_u32 s22, s27, s22
	s_addc_u32 s23, s28, s23
	s_and_b64 s[10:11], s[10:11], exec
	s_cselect_b32 s17, s23, s5
	s_cselect_b32 s40, s22, s4
	s_add_u32 s41, s4, 0x100
	s_addc_u32 s42, s5, 0
	s_add_u32 s4, s6, 0x80080
	s_addc_u32 s5, s7, 0
	s_mov_b32 s43, -2
	s_add_i32 s44, 0, 0x10000
	v_add_u32_e32 v2, s44, v167
	ds_read_b128 v[92:95], v2
	ds_read_b128 v[100:103], v2 offset:1024
	ds_read_b128 v[132:135], v2 offset:2048
	ds_read_b128 v[144:147], v2 offset:3072
	v_lshl_add_u64 v[196:197], s[4:5], 0, v[172:173]
	s_add_i32 m0, s30, 0xc000
	ds_read_b128 v[148:151], v169
	ds_read_b128 v[152:155], v169 offset:1024
	ds_read_b128 v[176:179], v169 offset:2048
	ds_read_b128 v[180:183], v169 offset:3072
	ds_read_b128 v[184:187], v169 offset:4096
	ds_read_b128 v[188:191], v169 offset:5120
	ds_read_b128 v[192:195], v169 offset:6144
	ds_read_b128 v[212:215], v169 offset:7168
	global_load_lds_dwordx4 v[196:197], off
	v_lshl_add_u64 v[196:197], s[4:5], 0, v[170:171]
	s_add_i32 m0, s30, 0xe000
	s_nop 0
	global_load_lds_dwordx4 v[196:197], off
	s_waitcnt lgkmcnt(8)
	s_setprio 1
	s_barrier
	s_waitcnt lgkmcnt(0)
	v_mfma_f32_16x16x32_bf16 v[140:143], v[92:95], v[148:151], 0
	v_mfma_f32_16x16x32_bf16 v[140:143], v[100:103], v[152:155], v[140:143]
	v_mfma_f32_16x16x32_bf16 v[128:131], v[92:95], v[176:179], 0
	v_mfma_f32_16x16x32_bf16 v[128:131], v[100:103], v[180:183], v[128:131]
	v_mfma_f32_16x16x32_bf16 v[120:123], v[92:95], v[184:187], 0
	v_mfma_f32_16x16x32_bf16 v[120:123], v[100:103], v[188:191], v[120:123]
	v_mfma_f32_16x16x32_bf16 v[112:115], v[92:95], v[192:195], 0
	v_mfma_f32_16x16x32_bf16 v[112:115], v[100:103], v[212:215], v[112:115]
	v_mfma_f32_16x16x32_bf16 v[136:139], v[132:135], v[148:151], 0
	v_mfma_f32_16x16x32_bf16 v[136:139], v[144:147], v[152:155], v[136:139]
	v_mfma_f32_16x16x32_bf16 v[124:127], v[132:135], v[176:179], 0
	v_mfma_f32_16x16x32_bf16 v[124:127], v[144:147], v[180:183], v[124:127]
	v_mfma_f32_16x16x32_bf16 v[116:119], v[132:135], v[184:187], 0
	v_mfma_f32_16x16x32_bf16 v[116:119], v[144:147], v[188:191], v[116:119]
	v_mfma_f32_16x16x32_bf16 v[108:111], v[132:135], v[192:195], 0
	v_mfma_f32_16x16x32_bf16 v[108:111], v[144:147], v[212:215], v[108:111]
	s_barrier
	s_setprio 0
	s_add_u32 s6, s4, 0xfff80080
	s_addc_u32 s7, s5, -1
	s_cmp_eq_u32 s43, 4
	s_cselect_b32 s11, s3, s7
	s_cselect_b32 s10, s15, s6
	s_cselect_b32 s7, s17, s42
	s_cselect_b32 s6, s40, s41
	s_add_i32 s46, 0, 0x14000
	s_add_i32 s44, s44, s29
	v_add_u32_e32 v2, s46, v167
	v_lshl_add_u64 v[196:197], s[6:7], 0, v[158:159]
	s_mov_b32 m0, s44
	ds_read_b128 v[216:219], v2
	ds_read_b128 v[220:223], v2 offset:1024
	ds_read_b128 v[224:227], v2 offset:2048
	ds_read_b128 v[228:231], v2 offset:3072
	global_load_lds_dwordx4 v[196:197], off
	v_lshl_add_u64 v[232:233], s[6:7], 0, v[0:1]
	s_add_i32 m0, s44, 0x2000
	s_nop 0
	global_load_lds_dwordx4 v[232:233], off
	s_mov_b32 m0, s30
	v_lshl_add_u64 v[234:235], s[10:11], 0, v[160:161]
	s_setprio 1
	s_barrier
	s_waitcnt lgkmcnt(0)
	v_mfma_f32_16x16x32_bf16 v[64:67], v[216:219], v[148:151], 0
	v_mfma_f32_16x16x32_bf16 v[64:67], v[220:223], v[152:155], v[64:67]
	v_mfma_f32_16x16x32_bf16 v[56:59], v[216:219], v[176:179], 0
	v_mfma_f32_16x16x32_bf16 v[56:59], v[220:223], v[180:183], v[56:59]
	v_mfma_f32_16x16x32_bf16 v[48:51], v[216:219], v[184:187], 0
	v_mfma_f32_16x16x32_bf16 v[48:51], v[220:223], v[188:191], v[48:51]
	v_mfma_f32_16x16x32_bf16 v[40:43], v[216:219], v[192:195], 0
	v_mfma_f32_16x16x32_bf16 v[40:43], v[220:223], v[212:215], v[40:43]
	v_mfma_f32_16x16x32_bf16 v[60:63], v[224:227], v[148:151], 0
	v_mfma_f32_16x16x32_bf16 v[60:63], v[228:231], v[152:155], v[60:63]
	v_mfma_f32_16x16x32_bf16 v[52:55], v[224:227], v[176:179], 0
	v_mfma_f32_16x16x32_bf16 v[52:55], v[228:231], v[180:183], v[52:55]
	v_mfma_f32_16x16x32_bf16 v[44:47], v[224:227], v[184:187], 0
	v_mfma_f32_16x16x32_bf16 v[44:47], v[228:231], v[188:191], v[44:47]
	v_mfma_f32_16x16x32_bf16 v[36:39], v[224:227], v[192:195], 0
	v_mfma_f32_16x16x32_bf16 v[36:39], v[228:231], v[212:215], v[36:39]
	s_barrier
	s_setprio 0
	ds_read_b128 v[148:151], v169 offset:16384
	ds_read_b128 v[152:155], v169 offset:17408
	ds_read_b128 v[176:179], v169 offset:18432
	ds_read_b128 v[180:183], v169 offset:19456
	ds_read_b128 v[184:187], v169 offset:20480
	ds_read_b128 v[188:191], v169 offset:21504
	ds_read_b128 v[192:195], v169 offset:22528
	ds_read_b128 v[212:215], v169 offset:23552
	global_load_lds_dwordx4 v[234:235], off
	v_lshl_add_u64 v[236:237], s[10:11], 0, v[156:157]
	s_mov_b32 m0, s31
	s_nop 0
	global_load_lds_dwordx4 v[236:237], off
	s_setprio 1
	s_barrier
	s_waitcnt lgkmcnt(0)
	v_mfma_f32_16x16x32_bf16 v[104:107], v[92:95], v[148:151], 0
	v_mfma_f32_16x16x32_bf16 v[104:107], v[100:103], v[152:155], v[104:107]
	v_mfma_f32_16x16x32_bf16 v[88:91], v[92:95], v[176:179], 0
	v_mfma_f32_16x16x32_bf16 v[88:91], v[100:103], v[180:183], v[88:91]
	v_mfma_f32_16x16x32_bf16 v[80:83], v[92:95], v[184:187], 0
	v_mfma_f32_16x16x32_bf16 v[80:83], v[100:103], v[188:191], v[80:83]
	v_mfma_f32_16x16x32_bf16 v[72:75], v[92:95], v[192:195], 0
	v_mfma_f32_16x16x32_bf16 v[72:75], v[100:103], v[212:215], v[72:75]
	v_mfma_f32_16x16x32_bf16 v[96:99], v[132:135], v[148:151], 0
	v_mfma_f32_16x16x32_bf16 v[96:99], v[144:147], v[152:155], v[96:99]
	v_mfma_f32_16x16x32_bf16 v[84:87], v[132:135], v[176:179], 0
	v_mfma_f32_16x16x32_bf16 v[84:87], v[144:147], v[180:183], v[84:87]
	v_mfma_f32_16x16x32_bf16 v[76:79], v[132:135], v[184:187], 0
	v_mfma_f32_16x16x32_bf16 v[76:79], v[144:147], v[188:191], v[76:79]
	v_mfma_f32_16x16x32_bf16 v[68:71], v[132:135], v[192:195], 0
	v_mfma_f32_16x16x32_bf16 v[68:71], v[144:147], v[212:215], v[68:71]
	s_barrier
; #define PG8_WAIT_V(n) asm volatile("s_waitcnt vmcnt(" #n ")" ::: "memory")
; #define PG8_WAIT_L(n) asm volatile("s_waitcnt lgkmcnt(" #n ")" ::: "memory")
; #define PG8_BAR __builtin_amdgcn_s_barrier()
; #define PG8_SCHED __builtin_amdgcn_sched_barrier(0)
; template <class Epi, class AddrA, class AddrB>
; __device__ __forceinline__ void gemm_phase(const Sched S, const int lda, const int ldb, const int K, const AddrA addrA,
;                                            const AddrB addrB, const Epi E) {
;     ...
;       PG8_LDB(B0, 0, 0); PG8_SCHED; PG8_LDA(At, 0, 0); PG8_STAGE(PG8_SA(1, 1), a1 + hstepA, voffA);
;       PG8_WAIT_L(8); PG8_BAR; PG8_WAIT_L(0); PG8_MMA(0, 0, At, B0); PG8_BAR; PG8_SCHED;
;       PG8_LDB(B1, 0, 1); PG8_STAGE(PG8_SB(0, 0), b2, voffB);
;       PG8_BAR; PG8_WAIT_L(0); PG8_MMA(0, 1, At, B1); PG8_BAR;
;       PG8_LDA(At, 0, 1); PG8_STAGE(PG8_SA(0, 0), a2, voffA);
;       PG8_BAR; PG8_WAIT_L(0); PG8_MMA(1, 0, At, B0); PG8_BAR; PG8_SCHED;
;       PG8_STAGE(PG8_SB(0, 1), b2 + hstepB, voffB);
;       PG8_WAIT_V(6); PG8_BAR; PG8_MMA(1, 1, At, B1); PG8_BAR;
;       PG8_LDB(B0, 1, 0); PG8_SCHED; PG8_LDA(At, 1, 0); PG8_STAGE(PG8_SA(0, 1), a2 + hstepA, voffA);
;       PG8_WAIT_L(8); PG8_BAR; PG8_WAIT_L(0); PG8_MMA(0, 0, At, B0); PG8_BAR; PG8_SCHED;
;       PG8_LDB(B1, 1, 1); PG8_STAGE(PG8_SB(1, 0), b3, voffB);
;       PG8_BAR; PG8_WAIT_L(0); PG8_MMA(0, 1, At, B1); PG8_BAR;
;       PG8_LDA(At, 1, 1); PG8_STAGE(PG8_SA(1, 0), a3, voffA);
;       PG8_BAR; PG8_WAIT_L(0); PG8_MMA(1, 0, At, B0); PG8_BAR; PG8_SCHED;
;       PG8_STAGE(PG8_SB(1, 1), b3 + hstepB, voffB);
;       PG8_WAIT_V(6); PG8_BAR; PG8_MMA(1, 1, At, B1); PG8_BAR;
	s_setprio 0
	s_add_u32 s44, s6, 0x20000
	s_addc_u32 s45, s7, 0
	s_add_i32 s46, s46, s29
	v_lshl_add_u64 v[92:93], s[44:45], 0, v[158:159]
	s_mov_b32 m0, s46
	s_nop 0
	global_load_lds_dwordx4 v[92:93], off
	v_lshl_add_u64 v[92:93], s[44:45], 0, v[0:1]
	s_add_i32 m0, s46, 0x2000
	s_nop 0
	global_load_lds_dwordx4 v[92:93], off
	s_add_i32 s44, 0, 0x18000
	v_add_u32_e32 v2, s44, v167
	s_waitcnt vmcnt(6)
	s_setprio 1
	s_barrier
	v_mfma_f32_16x16x32_bf16 v[32:35], v[216:219], v[148:151], 0
	v_mfma_f32_16x16x32_bf16 v[32:35], v[220:223], v[152:155], v[32:35]
	v_mfma_f32_16x16x32_bf16 v[24:27], v[216:219], v[176:179], 0
	v_mfma_f32_16x16x32_bf16 v[24:27], v[220:223], v[180:183], v[24:27]
	v_mfma_f32_16x16x32_bf16 v[16:19], v[216:219], v[184:187], 0
	v_mfma_f32_16x16x32_bf16 v[16:19], v[220:223], v[188:191], v[16:19]
	v_mfma_f32_16x16x32_bf16 v[8:11], v[216:219], v[192:195], 0
	v_mfma_f32_16x16x32_bf16 v[8:11], v[220:223], v[212:215], v[8:11]
	v_mfma_f32_16x16x32_bf16 v[28:31], v[224:227], v[148:151], 0
	v_mfma_f32_16x16x32_bf16 v[28:31], v[228:231], v[152:155], v[28:31]
	v_mfma_f32_16x16x32_bf16 v[20:23], v[224:227], v[176:179], 0
	v_mfma_f32_16x16x32_bf16 v[20:23], v[228:231], v[180:183], v[20:23]
	v_mfma_f32_16x16x32_bf16 v[12:15], v[224:227], v[184:187], 0
	v_mfma_f32_16x16x32_bf16 v[12:15], v[228:231], v[188:191], v[12:15]
	v_mfma_f32_16x16x32_bf16 v[4:7], v[224:227], v[192:195], 0
	v_mfma_f32_16x16x32_bf16 v[4:7], v[228:231], v[212:215], v[4:7]
	s_barrier
	s_setprio 0
	ds_read_b128 v[92:95], v2
	ds_read_b128 v[100:103], v2 offset:1024
	ds_read_b128 v[132:135], v2 offset:2048
	ds_read_b128 v[144:147], v2 offset:3072
	s_add_u32 s10, s10, 0x80000
	s_addc_u32 s11, s11, 0
	s_mov_b32 m0, s34
	v_lshl_add_u64 v[216:217], s[10:11], 0, v[160:161]
	ds_read_b128 v[148:151], v169 offset:32768
	ds_read_b128 v[152:155], v169 offset:33792
	ds_read_b128 v[176:179], v169 offset:34816
	ds_read_b128 v[180:183], v169 offset:35840
	ds_read_b128 v[184:187], v169 offset:36864
	ds_read_b128 v[188:191], v169 offset:37888
	ds_read_b128 v[192:195], v169 offset:38912
	ds_read_b128 v[212:215], v169 offset:39936
	global_load_lds_dwordx4 v[216:217], off
	v_lshl_add_u64 v[216:217], s[10:11], 0, v[156:157]
	s_mov_b32 m0, s35
	s_nop 0
	global_load_lds_dwordx4 v[216:217], off
	s_waitcnt lgkmcnt(8)
	s_setprio 1
	s_barrier
	s_waitcnt lgkmcnt(0)
	v_mfma_f32_16x16x32_bf16 v[140:143], v[92:95], v[148:151], v[140:143]
	v_mfma_f32_16x16x32_bf16 v[140:143], v[100:103], v[152:155], v[140:143]
	v_mfma_f32_16x16x32_bf16 v[128:131], v[92:95], v[176:179], v[128:131]
	v_mfma_f32_16x16x32_bf16 v[128:131], v[100:103], v[180:183], v[128:131]
	v_mfma_f32_16x16x32_bf16 v[120:123], v[92:95], v[184:187], v[120:123]
	v_mfma_f32_16x16x32_bf16 v[120:123], v[100:103], v[188:191], v[120:123]
	v_mfma_f32_16x16x32_bf16 v[112:115], v[92:95], v[192:195], v[112:115]
	v_mfma_f32_16x16x32_bf16 v[112:115], v[100:103], v[212:215], v[112:115]
	v_mfma_f32_16x16x32_bf16 v[136:139], v[132:135], v[148:151], v[136:139]
	v_mfma_f32_16x16x32_bf16 v[136:139], v[144:147], v[152:155], v[136:139]
	v_mfma_f32_16x16x32_bf16 v[124:127], v[132:135], v[176:179], v[124:127]
	v_mfma_f32_16x16x32_bf16 v[124:127], v[144:147], v[180:183], v[124:127]
	v_mfma_f32_16x16x32_bf16 v[116:119], v[132:135], v[184:187], v[116:119]
	v_mfma_f32_16x16x32_bf16 v[116:119], v[144:147], v[188:191], v[116:119]
	v_mfma_f32_16x16x32_bf16 v[108:111], v[132:135], v[192:195], v[108:111]
	v_mfma_f32_16x16x32_bf16 v[108:111], v[144:147], v[212:215], v[108:111]
	s_barrier
	s_setprio 0
	s_add_i32 s10, 0, 0x1c000
	s_add_i32 s11, s44, s29
	v_add_u32_e32 v2, s10, v167
	v_lshl_add_u64 v[196:197], v[196:197], 0, s[52:53]
	s_mov_b32 m0, s11
	ds_read_b128 v[216:219], v2
	ds_read_b128 v[220:223], v2 offset:1024
	ds_read_b128 v[224:227], v2 offset:2048
	ds_read_b128 v[228:231], v2 offset:3072
	global_load_lds_dwordx4 v[196:197], off
	v_lshl_add_u64 v[196:197], v[232:233], 0, s[52:53]
	s_add_i32 m0, s11, 0x2000
	s_nop 0
	global_load_lds_dwordx4 v[196:197], off
	s_mov_b32 m0, s37
	v_lshl_add_u64 v[196:197], v[234:235], 0, s[52:53]
	s_setprio 1
	s_barrier
	s_waitcnt lgkmcnt(0)
	v_mfma_f32_16x16x32_bf16 v[64:67], v[216:219], v[148:151], v[64:67]
	v_mfma_f32_16x16x32_bf16 v[64:67], v[220:223], v[152:155], v[64:67]
	v_mfma_f32_16x16x32_bf16 v[56:59], v[216:219], v[176:179], v[56:59]
	v_mfma_f32_16x16x32_bf16 v[56:59], v[220:223], v[180:183], v[56:59]
	v_mfma_f32_16x16x32_bf16 v[48:51], v[216:219], v[184:187], v[48:51]
	v_mfma_f32_16x16x32_bf16 v[48:51], v[220:223], v[188:191], v[48:51]
	v_mfma_f32_16x16x32_bf16 v[40:43], v[216:219], v[192:195], v[40:43]
	v_mfma_f32_16x16x32_bf16 v[40:43], v[220:223], v[212:215], v[40:43]
	v_mfma_f32_16x16x32_bf16 v[60:63], v[224:227], v[148:151], v[60:63]
	v_mfma_f32_16x16x32_bf16 v[60:63], v[228:231], v[152:155], v[60:63]
	v_mfma_f32_16x16x32_bf16 v[52:55], v[224:227], v[176:179], v[52:55]
	v_mfma_f32_16x16x32_bf16 v[52:55], v[228:231], v[180:183], v[52:55]
	v_mfma_f32_16x16x32_bf16 v[44:47], v[224:227], v[184:187], v[44:47]
	v_mfma_f32_16x16x32_bf16 v[44:47], v[228:231], v[188:191], v[44:47]
	v_mfma_f32_16x16x32_bf16 v[36:39], v[224:227], v[192:195], v[36:39]
	v_mfma_f32_16x16x32_bf16 v[36:39], v[228:231], v[212:215], v[36:39]
	s_barrier
	s_setprio 0
	ds_read_b128 v[148:151], v169 offset:49152
	ds_read_b128 v[152:155], v169 offset:50176
	ds_read_b128 v[176:179], v169 offset:51200
	ds_read_b128 v[180:183], v169 offset:52224
	ds_read_b128 v[184:187], v169 offset:53248
	ds_read_b128 v[188:191], v169 offset:54272
	ds_read_b128 v[192:195], v169 offset:55296
	ds_read_b128 v[212:215], v169 offset:56320
	global_load_lds_dwordx4 v[196:197], off
	v_lshl_add_u64 v[196:197], v[236:237], 0, s[52:53]
	s_mov_b32 m0, s38
	s_nop 0
	global_load_lds_dwordx4 v[196:197], off
	s_setprio 1
	s_barrier
; #define PG8_WAIT_V(n) asm volatile("s_waitcnt vmcnt(" #n ")" ::: "memory")
; #define PG8_WAIT_L(n) asm volatile("s_waitcnt lgkmcnt(" #n ")" ::: "memory")
; #define PG8_BAR __builtin_amdgcn_s_barrier()
; #define PG8_SCHED __builtin_amdgcn_sched_barrier(0)
; template <class Epi, class AddrA, class AddrB>
; __device__ __forceinline__ void gemm_phase(const Sched S, const int lda, const int ldb, const int K, const AddrA addrA,
;                                            const AddrB addrB, const Epi E) {
;     ...
;       PG8_LDB(B0, 0, 0); PG8_SCHED; PG8_LDA(At, 0, 0); PG8_STAGE(PG8_SA(1, 1), a1 + hstepA, voffA);
;       PG8_WAIT_L(8); PG8_BAR; PG8_WAIT_L(0); PG8_MMA(0, 0, At, B0); PG8_BAR; PG8_SCHED;
;       PG8_LDB(B1, 0, 1); PG8_STAGE(PG8_SB(0, 0), b2, voffB);
;       PG8_BAR; PG8_WAIT_L(0); PG8_MMA(0, 1, At, B1); PG8_BAR;
;       PG8_LDA(At, 0, 1); PG8_STAGE(PG8_SA(0, 0), a2, voffA);
;       PG8_BAR; PG8_WAIT_L(0); PG8_MMA(1, 0, At, B0); PG8_BAR; PG8_SCHED;
;       PG8_STAGE(PG8_SB(0, 1), b2 + hstepB, voffB);
;       PG8_WAIT_V(6); PG8_BAR; PG8_MMA(1, 1, At, B1); PG8_BAR;
;       PG8_LDB(B0, 1, 0); PG8_SCHED; PG8_LDA(At, 1, 0); PG8_STAGE(PG8_SA(0, 1), a2 + hstepA, voffA);
;       PG8_WAIT_L(8); PG8_BAR; PG8_WAIT_L(0); PG8_MMA(0, 0, At, B0); PG8_BAR; PG8_SCHED;
;       PG8_LDB(B1, 1, 1); PG8_STAGE(PG8_SB(1, 0), b3, voffB);
;       PG8_BAR; PG8_WAIT_L(0); PG8_MMA(0, 1, At, B1); PG8_BAR;
;       PG8_LDA(At, 1, 1); PG8_STAGE(PG8_SA(1, 0), a3, voffA);
;       PG8_BAR; PG8_WAIT_L(0); PG8_MMA(1, 0, At, B0); PG8_BAR; PG8_SCHED;
;       PG8_STAGE(PG8_SB(1, 1), b3 + hstepB, voffB);
;       PG8_WAIT_V(6); PG8_BAR; PG8_MMA(1, 1, At, B1); PG8_BAR;
	s_waitcnt lgkmcnt(0)
	v_mfma_f32_16x16x32_bf16 v[104:107], v[92:95], v[148:151], v[104:107]
	v_mfma_f32_16x16x32_bf16 v[104:107], v[100:103], v[152:155], v[104:107]
	v_mfma_f32_16x16x32_bf16 v[88:91], v[92:95], v[176:179], v[88:91]
	v_mfma_f32_16x16x32_bf16 v[88:91], v[100:103], v[180:183], v[88:91]
	v_mfma_f32_16x16x32_bf16 v[80:83], v[92:95], v[184:187], v[80:83]
	v_mfma_f32_16x16x32_bf16 v[80:83], v[100:103], v[188:191], v[80:83]
	v_mfma_f32_16x16x32_bf16 v[72:75], v[92:95], v[192:195], v[72:75]
	v_mfma_f32_16x16x32_bf16 v[72:75], v[100:103], v[212:215], v[72:75]
	v_mfma_f32_16x16x32_bf16 v[96:99], v[132:135], v[148:151], v[96:99]
	v_mfma_f32_16x16x32_bf16 v[96:99], v[144:147], v[152:155], v[96:99]
	v_mfma_f32_16x16x32_bf16 v[84:87], v[132:135], v[176:179], v[84:87]
	v_mfma_f32_16x16x32_bf16 v[84:87], v[144:147], v[180:183], v[84:87]
	v_mfma_f32_16x16x32_bf16 v[76:79], v[132:135], v[184:187], v[76:79]
	v_mfma_f32_16x16x32_bf16 v[76:79], v[144:147], v[188:191], v[76:79]
	v_mfma_f32_16x16x32_bf16 v[68:71], v[132:135], v[192:195], v[68:71]
	v_mfma_f32_16x16x32_bf16 v[68:71], v[144:147], v[212:215], v[68:71]
	s_barrier
	s_setprio 0
	s_add_u32 s6, s6, 0x20080
	s_addc_u32 s7, s7, 0
	s_add_i32 s10, s10, s29
	v_lshl_add_u64 v[92:93], s[6:7], 0, v[158:159]
	s_mov_b32 m0, s10
	s_nop 0
	global_load_lds_dwordx4 v[92:93], off
	v_lshl_add_u64 v[92:93], s[6:7], 0, v[0:1]
	s_add_i32 m0, s10, 0x2000
	s_nop 0
	global_load_lds_dwordx4 v[92:93], off
	s_add_i32 s43, s43, 2
	s_add_u32 s41, s41, 0x100
	s_addc_u32 s42, s42, 0
	s_add_u32 s4, s4, 0x100
	s_addc_u32 s5, s5, 0
	s_waitcnt vmcnt(6)
	s_setprio 1
	s_barrier
	v_mfma_f32_16x16x32_bf16 v[32:35], v[216:219], v[148:151], v[32:35]
	v_mfma_f32_16x16x32_bf16 v[32:35], v[220:223], v[152:155], v[32:35]
	v_mfma_f32_16x16x32_bf16 v[24:27], v[216:219], v[176:179], v[24:27]
	v_mfma_f32_16x16x32_bf16 v[24:27], v[220:223], v[180:183], v[24:27]
	v_mfma_f32_16x16x32_bf16 v[16:19], v[216:219], v[184:187], v[16:19]
	v_mfma_f32_16x16x32_bf16 v[16:19], v[220:223], v[188:191], v[16:19]
	v_mfma_f32_16x16x32_bf16 v[8:11], v[216:219], v[192:195], v[8:11]
	v_mfma_f32_16x16x32_bf16 v[8:11], v[220:223], v[212:215], v[8:11]
	v_mfma_f32_16x16x32_bf16 v[28:31], v[224:227], v[148:151], v[28:31]
	v_mfma_f32_16x16x32_bf16 v[28:31], v[228:231], v[152:155], v[28:31]
	v_mfma_f32_16x16x32_bf16 v[20:23], v[224:227], v[176:179], v[20:23]
	v_mfma_f32_16x16x32_bf16 v[20:23], v[228:231], v[180:183], v[20:23]
	v_mfma_f32_16x16x32_bf16 v[12:15], v[224:227], v[184:187], v[12:15]
	v_mfma_f32_16x16x32_bf16 v[12:15], v[228:231], v[188:191], v[12:15]
	v_mfma_f32_16x16x32_bf16 v[4:7], v[224:227], v[192:195], v[4:7]
	v_mfma_f32_16x16x32_bf16 v[4:7], v[228:231], v[212:215], v[4:7]
	s_barrier
	s_setprio 0
	s_cmp_gt_u32 s43, 5
.LBB0_485:
	s_add_i32 s44, 0, 0x10000
	v_add_u32_e32 v2, s44, v167
	ds_read_b128 v[92:95], v2
	ds_read_b128 v[100:103], v2 offset:1024
	ds_read_b128 v[132:135], v2 offset:2048
	ds_read_b128 v[144:147], v2 offset:3072
	v_lshl_add_u64 v[196:197], s[4:5], 0, v[172:173]
	s_add_i32 m0, s30, 0xc000
	ds_read_b128 v[148:151], v169
	ds_read_b128 v[152:155], v169 offset:1024
	ds_read_b128 v[176:179], v169 offset:2048
	ds_read_b128 v[180:183], v169 offset:3072
	ds_read_b128 v[184:187], v169 offset:4096
	ds_read_b128 v[188:191], v169 offset:5120
	ds_read_b128 v[192:195], v169 offset:6144
	ds_read_b128 v[212:215], v169 offset:7168
	global_load_lds_dwordx4 v[196:197], off
	v_lshl_add_u64 v[196:197], s[4:5], 0, v[170:171]
	s_add_i32 m0, s30, 0xe000
	s_nop 0
	global_load_lds_dwordx4 v[196:197], off
	s_waitcnt lgkmcnt(8)
	s_setprio 1
	s_barrier
	s_waitcnt lgkmcnt(0)
	v_mfma_f32_16x16x32_bf16 v[140:143], v[92:95], v[148:151], v[140:143]
	v_mfma_f32_16x16x32_bf16 v[140:143], v[100:103], v[152:155], v[140:143]
	v_mfma_f32_16x16x32_bf16 v[128:131], v[92:95], v[176:179], v[128:131]
	v_mfma_f32_16x16x32_bf16 v[128:131], v[100:103], v[180:183], v[128:131]
	v_mfma_f32_16x16x32_bf16 v[120:123], v[92:95], v[184:187], v[120:123]
	v_mfma_f32_16x16x32_bf16 v[120:123], v[100:103], v[188:191], v[120:123]
	v_mfma_f32_16x16x32_bf16 v[112:115], v[92:95], v[192:195], v[112:115]
	v_mfma_f32_16x16x32_bf16 v[112:115], v[100:103], v[212:215], v[112:115]
	v_mfma_f32_16x16x32_bf16 v[136:139], v[132:135], v[148:151], v[136:139]
	v_mfma_f32_16x16x32_bf16 v[136:139], v[144:147], v[152:155], v[136:139]
	v_mfma_f32_16x16x32_bf16 v[124:127], v[132:135], v[176:179], v[124:127]
	v_mfma_f32_16x16x32_bf16 v[124:127], v[144:147], v[180:183], v[124:127]
	v_mfma_f32_16x16x32_bf16 v[116:119], v[132:135], v[184:187], v[116:119]
	v_mfma_f32_16x16x32_bf16 v[116:119], v[144:147], v[188:191], v[116:119]
	v_mfma_f32_16x16x32_bf16 v[108:111], v[132:135], v[192:195], v[108:111]
	v_mfma_f32_16x16x32_bf16 v[108:111], v[144:147], v[212:215], v[108:111]
	s_barrier
	s_setprio 0
	s_add_u32 s6, s4, 0xfff80080
	s_addc_u32 s7, s5, -1
	s_cmp_eq_u32 s43, 4
	s_cselect_b32 s11, s3, s7
	s_cselect_b32 s10, s15, s6
	s_cselect_b32 s7, s17, s42
	s_cselect_b32 s6, s40, s41
	s_add_i32 s46, 0, 0x14000
	s_add_i32 s44, s44, s29
	v_add_u32_e32 v2, s46, v167
	v_lshl_add_u64 v[196:197], s[6:7], 0, v[158:159]
	s_mov_b32 m0, s44
	ds_read_b128 v[216:219], v2
	ds_read_b128 v[220:223], v2 offset:1024
	ds_read_b128 v[224:227], v2 offset:2048
	ds_read_b128 v[228:231], v2 offset:3072
	global_load_lds_dwordx4 v[196:197], off
	v_lshl_add_u64 v[232:233], s[6:7], 0, v[0:1]
	s_add_i32 m0, s44, 0x2000
	s_nop 0
	global_load_lds_dwordx4 v[232:233], off
	s_mov_b32 m0, s30
	v_lshl_add_u64 v[234:235], s[10:11], 0, v[160:161]
	s_setprio 1
	s_barrier
; #define PG8_WAIT_V(n) asm volatile("s_waitcnt vmcnt(" #n ")" ::: "memory")
; #define PG8_WAIT_L(n) asm volatile("s_waitcnt lgkmcnt(" #n ")" ::: "memory")
; #define PG8_BAR __builtin_amdgcn_s_barrier()
; #define PG8_SCHED __builtin_amdgcn_sched_barrier(0)
; template <class Epi, class AddrA, class AddrB>
; __device__ __forceinline__ void gemm_phase(const Sched S, const int lda, const int ldb, const int K, const AddrA addrA,
;                                            const AddrB addrB, const Epi E) {
;     ...
;       PG8_LDB(B0, 0, 0); PG8_SCHED; PG8_LDA(At, 0, 0); PG8_STAGE(PG8_SA(1, 1), a1 + hstepA, voffA);
;       PG8_WAIT_L(8); PG8_BAR; PG8_WAIT_L(0); PG8_MMA(0, 0, At, B0); PG8_BAR; PG8_SCHED;
;       PG8_LDB(B1, 0, 1); PG8_STAGE(PG8_SB(0, 0), b2, voffB);
;       PG8_BAR; PG8_WAIT_L(0); PG8_MMA(0, 1, At, B1); PG8_BAR;
;       PG8_LDA(At, 0, 1); PG8_STAGE(PG8_SA(0, 0), a2, voffA);
;       PG8_BAR; PG8_WAIT_L(0); PG8_MMA(1, 0, At, B0); PG8_BAR; PG8_SCHED;
;       PG8_STAGE(PG8_SB(0, 1), b2 + hstepB, voffB);
;       PG8_WAIT_V(6); PG8_BAR; PG8_MMA(1, 1, At, B1); PG8_BAR;
;       PG8_LDB(B0, 1, 0); PG8_SCHED; PG8_LDA(At, 1, 0); PG8_STAGE(PG8_SA(0, 1), a2 + hstepA, voffA);
;       PG8_WAIT_L(8); PG8_BAR; PG8_WAIT_L(0); PG8_MMA(0, 0, At, B0); PG8_BAR; PG8_SCHED;
;       PG8_LDB(B1, 1, 1); PG8_STAGE(PG8_SB(1, 0), b3, voffB);
;       PG8_BAR; PG8_WAIT_L(0); PG8_MMA(0, 1, At, B1); PG8_BAR;
;       PG8_LDA(At, 1, 1); PG8_STAGE(PG8_SA(1, 0), a3, voffA);
;       PG8_BAR; PG8_WAIT_L(0); PG8_MMA(1, 0, At, B0); PG8_BAR; PG8_SCHED;
;       PG8_STAGE(PG8_SB(1, 1), b3 + hstepB, voffB);
;       PG8_WAIT_V(6); PG8_BAR; PG8_MMA(1, 1, At, B1); PG8_BAR;
	s_waitcnt lgkmcnt(0)
	v_mfma_f32_16x16x32_bf16 v[64:67], v[216:219], v[148:151], v[64:67]
	v_mfma_f32_16x16x32_bf16 v[64:67], v[220:223], v[152:155], v[64:67]
	v_mfma_f32_16x16x32_bf16 v[56:59], v[216:219], v[176:179], v[56:59]
	v_mfma_f32_16x16x32_bf16 v[56:59], v[220:223], v[180:183], v[56:59]
	v_mfma_f32_16x16x32_bf16 v[48:51], v[216:219], v[184:187], v[48:51]
	v_mfma_f32_16x16x32_bf16 v[48:51], v[220:223], v[188:191], v[48:51]
	v_mfma_f32_16x16x32_bf16 v[40:43], v[216:219], v[192:195], v[40:43]
	v_mfma_f32_16x16x32_bf16 v[40:43], v[220:223], v[212:215], v[40:43]
	v_mfma_f32_16x16x32_bf16 v[60:63], v[224:227], v[148:151], v[60:63]
	v_mfma_f32_16x16x32_bf16 v[60:63], v[228:231], v[152:155], v[60:63]
	v_mfma_f32_16x16x32_bf16 v[52:55], v[224:227], v[176:179], v[52:55]
	v_mfma_f32_16x16x32_bf16 v[52:55], v[228:231], v[180:183], v[52:55]
	v_mfma_f32_16x16x32_bf16 v[44:47], v[224:227], v[184:187], v[44:47]
	v_mfma_f32_16x16x32_bf16 v[44:47], v[228:231], v[188:191], v[44:47]
	v_mfma_f32_16x16x32_bf16 v[36:39], v[224:227], v[192:195], v[36:39]
	v_mfma_f32_16x16x32_bf16 v[36:39], v[228:231], v[212:215], v[36:39]
	s_barrier
	s_setprio 0
	ds_read_b128 v[148:151], v169 offset:16384
	ds_read_b128 v[152:155], v169 offset:17408
	ds_read_b128 v[176:179], v169 offset:18432
	ds_read_b128 v[180:183], v169 offset:19456
	ds_read_b128 v[184:187], v169 offset:20480
	ds_read_b128 v[188:191], v169 offset:21504
	ds_read_b128 v[192:195], v169 offset:22528
	ds_read_b128 v[212:215], v169 offset:23552
	global_load_lds_dwordx4 v[234:235], off
	v_lshl_add_u64 v[236:237], s[10:11], 0, v[156:157]
	s_mov_b32 m0, s31
	s_nop 0
	global_load_lds_dwordx4 v[236:237], off
	s_setprio 1
	s_barrier
	s_waitcnt lgkmcnt(0)
	v_mfma_f32_16x16x32_bf16 v[104:107], v[92:95], v[148:151], v[104:107]
	v_mfma_f32_16x16x32_bf16 v[104:107], v[100:103], v[152:155], v[104:107]
	v_mfma_f32_16x16x32_bf16 v[88:91], v[92:95], v[176:179], v[88:91]
	v_mfma_f32_16x16x32_bf16 v[88:91], v[100:103], v[180:183], v[88:91]
	v_mfma_f32_16x16x32_bf16 v[80:83], v[92:95], v[184:187], v[80:83]
	v_mfma_f32_16x16x32_bf16 v[80:83], v[100:103], v[188:191], v[80:83]
	v_mfma_f32_16x16x32_bf16 v[72:75], v[92:95], v[192:195], v[72:75]
	v_mfma_f32_16x16x32_bf16 v[72:75], v[100:103], v[212:215], v[72:75]
	v_mfma_f32_16x16x32_bf16 v[96:99], v[132:135], v[148:151], v[96:99]
	v_mfma_f32_16x16x32_bf16 v[96:99], v[144:147], v[152:155], v[96:99]
	v_mfma_f32_16x16x32_bf16 v[84:87], v[132:135], v[176:179], v[84:87]
	v_mfma_f32_16x16x32_bf16 v[84:87], v[144:147], v[180:183], v[84:87]
	v_mfma_f32_16x16x32_bf16 v[76:79], v[132:135], v[184:187], v[76:79]
	v_mfma_f32_16x16x32_bf16 v[76:79], v[144:147], v[188:191], v[76:79]
	v_mfma_f32_16x16x32_bf16 v[68:71], v[132:135], v[192:195], v[68:71]
	v_mfma_f32_16x16x32_bf16 v[68:71], v[144:147], v[212:215], v[68:71]
	s_barrier
	s_setprio 0
	s_add_u32 s44, s6, 0x20000
	s_addc_u32 s45, s7, 0
	s_add_i32 s46, s46, s29
	v_lshl_add_u64 v[92:93], s[44:45], 0, v[158:159]
	s_mov_b32 m0, s46
	s_nop 0
	global_load_lds_dwordx4 v[92:93], off
	v_lshl_add_u64 v[92:93], s[44:45], 0, v[0:1]
	s_add_i32 m0, s46, 0x2000
	s_nop 0
	global_load_lds_dwordx4 v[92:93], off
	s_add_i32 s44, 0, 0x18000
	v_add_u32_e32 v2, s44, v167
	s_waitcnt vmcnt(6)
	s_setprio 1
	s_barrier
	v_mfma_f32_16x16x32_bf16 v[32:35], v[216:219], v[148:151], v[32:35]
	v_mfma_f32_16x16x32_bf16 v[32:35], v[220:223], v[152:155], v[32:35]
	v_mfma_f32_16x16x32_bf16 v[24:27], v[216:219], v[176:179], v[24:27]
	v_mfma_f32_16x16x32_bf16 v[24:27], v[220:223], v[180:183], v[24:27]
	v_mfma_f32_16x16x32_bf16 v[16:19], v[216:219], v[184:187], v[16:19]
	v_mfma_f32_16x16x32_bf16 v[16:19], v[220:223], v[188:191], v[16:19]
	v_mfma_f32_16x16x32_bf16 v[8:11], v[216:219], v[192:195], v[8:11]
	v_mfma_f32_16x16x32_bf16 v[8:11], v[220:223], v[212:215], v[8:11]
	v_mfma_f32_16x16x32_bf16 v[28:31], v[224:227], v[148:151], v[28:31]
	v_mfma_f32_16x16x32_bf16 v[28:31], v[228:231], v[152:155], v[28:31]
	v_mfma_f32_16x16x32_bf16 v[20:23], v[224:227], v[176:179], v[20:23]
	v_mfma_f32_16x16x32_bf16 v[20:23], v[228:231], v[180:183], v[20:23]
	v_mfma_f32_16x16x32_bf16 v[12:15], v[224:227], v[184:187], v[12:15]
	v_mfma_f32_16x16x32_bf16 v[12:15], v[228:231], v[188:191], v[12:15]
	v_mfma_f32_16x16x32_bf16 v[4:7], v[224:227], v[192:195], v[4:7]
	v_mfma_f32_16x16x32_bf16 v[4:7], v[228:231], v[212:215], v[4:7]
	s_barrier
	s_setprio 0
	ds_read_b128 v[92:95], v2
	ds_read_b128 v[100:103], v2 offset:1024
	ds_read_b128 v[132:135], v2 offset:2048
	ds_read_b128 v[144:147], v2 offset:3072
	s_add_u32 s10, s10, 0x80000
	s_addc_u32 s11, s11, 0
	s_mov_b32 m0, s34
	v_lshl_add_u64 v[216:217], s[10:11], 0, v[160:161]
	ds_read_b128 v[148:151], v169 offset:32768
	ds_read_b128 v[152:155], v169 offset:33792
	ds_read_b128 v[176:179], v169 offset:34816
	ds_read_b128 v[180:183], v169 offset:35840
	ds_read_b128 v[184:187], v169 offset:36864
	ds_read_b128 v[188:191], v169 offset:37888
	ds_read_b128 v[192:195], v169 offset:38912
	ds_read_b128 v[212:215], v169 offset:39936
	global_load_lds_dwordx4 v[216:217], off
	v_lshl_add_u64 v[216:217], s[10:11], 0, v[156:157]
	s_mov_b32 m0, s35
	s_nop 0
	global_load_lds_dwordx4 v[216:217], off
	s_waitcnt lgkmcnt(8)
	s_setprio 1
	s_barrier
; #define PG8_WAIT_V(n) asm volatile("s_waitcnt vmcnt(" #n ")" ::: "memory")
; #define PG8_WAIT_L(n) asm volatile("s_waitcnt lgkmcnt(" #n ")" ::: "memory")
; #define PG8_BAR __builtin_amdgcn_s_barrier()
; #define PG8_SCHED __builtin_amdgcn_sched_barrier(0)
; template <class Epi, class AddrA, class AddrB>
; __device__ __forceinline__ void gemm_phase(const Sched S, const int lda, const int ldb, const int K, const AddrA addrA,
;                                            const AddrB addrB, const Epi E) {
;     ...
;       PG8_LDB(B0, 0, 0); PG8_SCHED; PG8_LDA(At, 0, 0); PG8_STAGE(PG8_SA(1, 1), a1 + hstepA, voffA);
;       PG8_WAIT_L(8); PG8_BAR; PG8_WAIT_L(0); PG8_MMA(0, 0, At, B0); PG8_BAR; PG8_SCHED;
;       PG8_LDB(B1, 0, 1); PG8_STAGE(PG8_SB(0, 0), b2, voffB);
;       PG8_BAR; PG8_WAIT_L(0); PG8_MMA(0, 1, At, B1); PG8_BAR;
;       PG8_LDA(At, 0, 1); PG8_STAGE(PG8_SA(0, 0), a2, voffA);
;       PG8_BAR; PG8_WAIT_L(0); PG8_MMA(1, 0, At, B0); PG8_BAR; PG8_SCHED;
;       PG8_STAGE(PG8_SB(0, 1), b2 + hstepB, voffB);
;       PG8_WAIT_V(6); PG8_BAR; PG8_MMA(1, 1, At, B1); PG8_BAR;
;       PG8_LDB(B0, 1, 0); PG8_SCHED; PG8_LDA(At, 1, 0); PG8_STAGE(PG8_SA(0, 1), a2 + hstepA, voffA);
;       PG8_WAIT_L(8); PG8_BAR; PG8_WAIT_L(0); PG8_MMA(0, 0, At, B0); PG8_BAR; PG8_SCHED;
;       PG8_LDB(B1, 1, 1); PG8_STAGE(PG8_SB(1, 0), b3, voffB);
;       PG8_BAR; PG8_WAIT_L(0); PG8_MMA(0, 1, At, B1); PG8_BAR;
;       PG8_LDA(At, 1, 1); PG8_STAGE(PG8_SA(1, 0), a3, voffA);
;       PG8_BAR; PG8_WAIT_L(0); PG8_MMA(1, 0, At, B0); PG8_BAR; PG8_SCHED;
;       PG8_STAGE(PG8_SB(1, 1), b3 + hstepB, voffB);
;       PG8_WAIT_V(6); PG8_BAR; PG8_MMA(1, 1, At, B1); PG8_BAR;
	s_waitcnt lgkmcnt(0)
	v_mfma_f32_16x16x32_bf16 v[140:143], v[92:95], v[148:151], v[140:143]
	v_mfma_f32_16x16x32_bf16 v[140:143], v[100:103], v[152:155], v[140:143]
	v_mfma_f32_16x16x32_bf16 v[128:131], v[92:95], v[176:179], v[128:131]
	v_mfma_f32_16x16x32_bf16 v[128:131], v[100:103], v[180:183], v[128:131]
	v_mfma_f32_16x16x32_bf16 v[120:123], v[92:95], v[184:187], v[120:123]
	v_mfma_f32_16x16x32_bf16 v[120:123], v[100:103], v[188:191], v[120:123]
	v_mfma_f32_16x16x32_bf16 v[112:115], v[92:95], v[192:195], v[112:115]
	v_mfma_f32_16x16x32_bf16 v[112:115], v[100:103], v[212:215], v[112:115]
	v_mfma_f32_16x16x32_bf16 v[136:139], v[132:135], v[148:151], v[136:139]
	v_mfma_f32_16x16x32_bf16 v[136:139], v[144:147], v[152:155], v[136:139]
	v_mfma_f32_16x16x32_bf16 v[124:127], v[132:135], v[176:179], v[124:127]
	v_mfma_f32_16x16x32_bf16 v[124:127], v[144:147], v[180:183], v[124:127]
	v_mfma_f32_16x16x32_bf16 v[116:119], v[132:135], v[184:187], v[116:119]
	v_mfma_f32_16x16x32_bf16 v[116:119], v[144:147], v[188:191], v[116:119]
	v_mfma_f32_16x16x32_bf16 v[108:111], v[132:135], v[192:195], v[108:111]
	v_mfma_f32_16x16x32_bf16 v[108:111], v[144:147], v[212:215], v[108:111]
	s_barrier
	s_setprio 0
	s_add_i32 s10, 0, 0x1c000
	s_add_i32 s11, s44, s29
	v_add_u32_e32 v2, s10, v167
	v_lshl_add_u64 v[196:197], v[196:197], 0, s[52:53]
	s_mov_b32 m0, s11
	ds_read_b128 v[216:219], v2
	ds_read_b128 v[220:223], v2 offset:1024
	ds_read_b128 v[224:227], v2 offset:2048
	ds_read_b128 v[228:231], v2 offset:3072
	global_load_lds_dwordx4 v[196:197], off
	v_lshl_add_u64 v[196:197], v[232:233], 0, s[52:53]
	s_add_i32 m0, s11, 0x2000
	s_nop 0
	global_load_lds_dwordx4 v[196:197], off
	s_mov_b32 m0, s37
	v_lshl_add_u64 v[196:197], v[234:235], 0, s[52:53]
	s_setprio 1
	s_barrier
	s_waitcnt lgkmcnt(0)
	v_mfma_f32_16x16x32_bf16 v[64:67], v[216:219], v[148:151], v[64:67]
	v_mfma_f32_16x16x32_bf16 v[64:67], v[220:223], v[152:155], v[64:67]
	v_mfma_f32_16x16x32_bf16 v[56:59], v[216:219], v[176:179], v[56:59]
	v_mfma_f32_16x16x32_bf16 v[56:59], v[220:223], v[180:183], v[56:59]
	v_mfma_f32_16x16x32_bf16 v[48:51], v[216:219], v[184:187], v[48:51]
	v_mfma_f32_16x16x32_bf16 v[48:51], v[220:223], v[188:191], v[48:51]
	v_mfma_f32_16x16x32_bf16 v[40:43], v[216:219], v[192:195], v[40:43]
	v_mfma_f32_16x16x32_bf16 v[40:43], v[220:223], v[212:215], v[40:43]
	v_mfma_f32_16x16x32_bf16 v[60:63], v[224:227], v[148:151], v[60:63]
	v_mfma_f32_16x16x32_bf16 v[60:63], v[228:231], v[152:155], v[60:63]
	v_mfma_f32_16x16x32_bf16 v[52:55], v[224:227], v[176:179], v[52:55]
	v_mfma_f32_16x16x32_bf16 v[52:55], v[228:231], v[180:183], v[52:55]
	v_mfma_f32_16x16x32_bf16 v[44:47], v[224:227], v[184:187], v[44:47]
	v_mfma_f32_16x16x32_bf16 v[44:47], v[228:231], v[188:191], v[44:47]
	v_mfma_f32_16x16x32_bf16 v[36:39], v[224:227], v[192:195], v[36:39]
	v_mfma_f32_16x16x32_bf16 v[36:39], v[228:231], v[212:215], v[36:39]
	s_barrier
	s_setprio 0
	ds_read_b128 v[148:151], v169 offset:49152
	ds_read_b128 v[152:155], v169 offset:50176
	ds_read_b128 v[176:179], v169 offset:51200
	ds_read_b128 v[180:183], v169 offset:52224
	ds_read_b128 v[184:187], v169 offset:53248
	ds_read_b128 v[188:191], v169 offset:54272
	ds_read_b128 v[192:195], v169 offset:55296
	ds_read_b128 v[212:215], v169 offset:56320
	global_load_lds_dwordx4 v[196:197], off
	v_lshl_add_u64 v[196:197], v[236:237], 0, s[52:53]
	s_mov_b32 m0, s38
	s_nop 0
	global_load_lds_dwordx4 v[196:197], off
	s_setprio 1
	s_barrier
	s_waitcnt lgkmcnt(0)
	v_mfma_f32_16x16x32_bf16 v[104:107], v[92:95], v[148:151], v[104:107]
	v_mfma_f32_16x16x32_bf16 v[104:107], v[100:103], v[152:155], v[104:107]
	v_mfma_f32_16x16x32_bf16 v[88:91], v[92:95], v[176:179], v[88:91]
	v_mfma_f32_16x16x32_bf16 v[88:91], v[100:103], v[180:183], v[88:91]
	v_mfma_f32_16x16x32_bf16 v[80:83], v[92:95], v[184:187], v[80:83]
	v_mfma_f32_16x16x32_bf16 v[80:83], v[100:103], v[188:191], v[80:83]
	v_mfma_f32_16x16x32_bf16 v[72:75], v[92:95], v[192:195], v[72:75]
	v_mfma_f32_16x16x32_bf16 v[72:75], v[100:103], v[212:215], v[72:75]
	v_mfma_f32_16x16x32_bf16 v[96:99], v[132:135], v[148:151], v[96:99]
	v_mfma_f32_16x16x32_bf16 v[96:99], v[144:147], v[152:155], v[96:99]
	v_mfma_f32_16x16x32_bf16 v[84:87], v[132:135], v[176:179], v[84:87]
	v_mfma_f32_16x16x32_bf16 v[84:87], v[144:147], v[180:183], v[84:87]
	v_mfma_f32_16x16x32_bf16 v[76:79], v[132:135], v[184:187], v[76:79]
	v_mfma_f32_16x16x32_bf16 v[76:79], v[144:147], v[188:191], v[76:79]
	v_mfma_f32_16x16x32_bf16 v[68:71], v[132:135], v[192:195], v[68:71]
	v_mfma_f32_16x16x32_bf16 v[68:71], v[144:147], v[212:215], v[68:71]
	s_barrier
	s_setprio 0
	s_add_u32 s6, s6, 0x20080
	s_addc_u32 s7, s7, 0
	s_add_i32 s10, s10, s29
	v_lshl_add_u64 v[92:93], s[6:7], 0, v[158:159]
	s_mov_b32 m0, s10
	s_nop 0
	global_load_lds_dwordx4 v[92:93], off
	v_lshl_add_u64 v[92:93], s[6:7], 0, v[0:1]
	s_add_i32 m0, s10, 0x2000
	s_nop 0
	global_load_lds_dwordx4 v[92:93], off
	s_add_i32 s43, s43, 2
	s_add_u32 s41, s41, 0x100
	s_addc_u32 s42, s42, 0
	s_add_u32 s4, s4, 0x100
	s_addc_u32 s5, s5, 0
	s_waitcnt vmcnt(6)
	s_setprio 1
	s_barrier
	v_mfma_f32_16x16x32_bf16 v[32:35], v[216:219], v[148:151], v[32:35]
	v_mfma_f32_16x16x32_bf16 v[32:35], v[220:223], v[152:155], v[32:35]
	v_mfma_f32_16x16x32_bf16 v[24:27], v[216:219], v[176:179], v[24:27]
	v_mfma_f32_16x16x32_bf16 v[24:27], v[220:223], v[180:183], v[24:27]
	v_mfma_f32_16x16x32_bf16 v[16:19], v[216:219], v[184:187], v[16:19]
	v_mfma_f32_16x16x32_bf16 v[16:19], v[220:223], v[188:191], v[16:19]
	v_mfma_f32_16x16x32_bf16 v[8:11], v[216:219], v[192:195], v[8:11]
	v_mfma_f32_16x16x32_bf16 v[8:11], v[220:223], v[212:215], v[8:11]
	v_mfma_f32_16x16x32_bf16 v[28:31], v[224:227], v[148:151], v[28:31]
	v_mfma_f32_16x16x32_bf16 v[28:31], v[228:231], v[152:155], v[28:31]
	v_mfma_f32_16x16x32_bf16 v[20:23], v[224:227], v[176:179], v[20:23]
	v_mfma_f32_16x16x32_bf16 v[20:23], v[228:231], v[180:183], v[20:23]
	v_mfma_f32_16x16x32_bf16 v[12:15], v[224:227], v[184:187], v[12:15]
	v_mfma_f32_16x16x32_bf16 v[12:15], v[228:231], v[188:191], v[12:15]
	v_mfma_f32_16x16x32_bf16 v[4:7], v[224:227], v[192:195], v[4:7]
	v_mfma_f32_16x16x32_bf16 v[4:7], v[228:231], v[212:215], v[4:7]
	s_barrier
; __device__ __forceinline__ size_t pidx(size_t row, int col) { return ((size_t)(col >> 8) * MTOK + row) * PLD + (col & 255); }
; __device__ __forceinline__ float bflo(unsigned v) { return __uint_as_float(v << 16); }
; __device__ __forceinline__ float bfhi(unsigned v) { return __uint_as_float(v & 0xffff0000u); }
; __device__ __forceinline__ float siluf_(float x) { return x * __builtin_amdgcn_rcpf(1.0f + __expf(-x)); }
;   __device__ __forceinline__ void operator()(EPI_ARGS) const {
;     const size_t row0 = (size_t)u.pm * 256 + wr * 64 + fr;
;     const int col0 = u.pn * 256 + wc * 32 + 8 * fq;
; #pragma unroll
;     for (int bj = 0; bj < 2; ++bj) {
;       const int c = col0 + bj * HALF;
;       const f32x4 s0 = *(const f32x4*)(psc + c), s1 = *(const f32x4*)(psc + c + 4);
; #pragma unroll
;       for (int ai = 0; ai < 2; ++ai) {
;         u32x4 z[4];
; #pragma unroll
;         for (int m = 0; m < 4; ++m) z[m] = *(const u32x4*)(proj + pidx(row0 + ai * HALF + m * 16, PZ + c));
;         __builtin_amdgcn_sched_barrier(0);
; #pragma unroll
;         for (int m = 0; m < 4; ++m) {
;           const size_t row = row0 + ai * HALF + m * 16;
;           const f32x4 v0 = acc[ai][bj][m][0], v1 = acc[ai][bj][m][1];
;           u32x4 o;
;           o.x = pack2(v0[0] * s0[0] * siluf_(bflo(z[m].x)), v0[1] * s0[1] * siluf_(bfhi(z[m].x)));
;           o.y = pack2(v0[2] * s0[2] * siluf_(bflo(z[m].y)), v0[3] * s0[3] * siluf_(bfhi(z[m].y)));
;           o.z = pack2(v1[0] * s1[0] * siluf_(bflo(z[m].z)), v1[1] * s1[1] * siluf_(bfhi(z[m].z)));
;           o.w = pack2(v1[2] * s1[2] * siluf_(bflo(z[m].w)), v1[3] * s1[3] * siluf_(bfhi(z[m].w)));
;           *(u32x4*)(y0 + row * DM + c) = o;
;         }
	s_setprio 0
	s_cmp_gt_u32 s43, 5
	s_cbranch_scc0 .LBB0_485
	s_ashr_i32 s3, s2, 31
	s_lshl_b64 s[2:3], s[2:3], 8
	v_lshl_add_u64 v[186:187], s[2:3], 0, v[162:163]
	s_lshl_b32 s2, s33, 8
	v_or_b32_e32 v196, s2, v168
	s_addk_i32 s2, 0x800
	s_ashr_i32 s2, s2, 8
	s_ashr_i32 s3, s2, 31
	s_lshl_b64 s[2:3], s[2:3], 23
	s_add_u32 s2, s0, s2
	s_addc_u32 s3, s1, s3
	v_lshlrev_b32_e32 v2, 1, v168
	v_or_b32_e32 v194, 16, v186
	v_mov_b32_e32 v195, v187
	v_ashrrev_i32_e32 v197, 31, v196
	v_lshl_add_u64 v[188:189], s[2:3], 0, v[2:3]
	v_lshlrev_b64 v[178:179], 9, v[186:187]
	v_lshlrev_b64 v[180:181], 9, v[194:195]
	v_or_b32_e32 v192, 32, v186
	v_mov_b32_e32 v193, v187
	v_or_b32_e32 v190, 48, v186
	v_mov_b32_e32 v191, v187
	v_lshl_add_u64 v[176:177], v[196:197], 2, s[12:13]
	v_lshl_add_u64 v[132:133], v[188:189], 0, v[178:179]
	v_lshl_add_u64 v[134:135], v[188:189], 0, v[180:181]
	v_lshlrev_b64 v[182:183], 9, v[192:193]
	v_lshlrev_b64 v[184:185], 9, v[190:191]
	global_load_dwordx4 v[92:95], v[176:177], off offset:16
	global_load_dwordx4 v[100:103], v[176:177], off
	flat_load_dwordx4 v[152:155], v[132:133]
	flat_load_dwordx4 v[148:151], v[134:135]
	v_lshl_add_u64 v[132:133], v[188:189], 0, v[182:183]
	v_lshl_add_u64 v[134:135], v[188:189], 0, v[184:185]
	flat_load_dwordx4 v[144:147], v[132:133]
	s_nop 0
	flat_load_dwordx4 v[132:135], v[134:135]
	s_waitcnt vmcnt(0) lgkmcnt(0)
	v_lshlrev_b32_e32 v213, 16, v152
	v_mul_f32_e32 v2, 0xbfb8aa3b, v213
	v_exp_f32_e32 v2, v2
	v_mov_b32_e32 v214, v140
	v_mov_b32_e32 v212, v100
	s_mov_b64 s[4:5], 0x90
	v_add_f32_e32 v2, 1.0, v2
	v_rcp_f32_e32 v215, v2
	s_nop 0
	v_pk_mul_f32 v[212:213], v[214:215], v[212:213]
	s_nop 0
	v_mul_f32_e32 v2, v212, v213
	v_and_b32_e32 v213, 0xffff0000, v152
	v_mul_f32_e32 v140, 0xbfb8aa3b, v213
	v_exp_f32_e32 v140, v140
	v_mov_b32_e32 v214, v141
	v_mov_b32_e32 v212, v101
	v_add_f32_e32 v140, 1.0, v140
	v_rcp_f32_e32 v215, v140
	s_nop 0
	v_pk_mul_f32 v[140:141], v[214:215], v[212:213]
	s_nop 0
	v_mul_f32_e32 v140, v140, v141
	v_lshlrev_b32_e32 v141, 16, v153
	v_cvt_pk_bf16_f32 v152, v2, v140
	v_mul_f32_e32 v2, 0xbfb8aa3b, v141
	v_exp_f32_e32 v2, v2
	v_mov_b32_e32 v212, v142
	v_mov_b32_e32 v140, v102
	v_mov_b32_e32 v142, v136
	v_add_f32_e32 v2, 1.0, v2
	v_rcp_f32_e32 v213, v2
	s_nop 0
	v_pk_mul_f32 v[140:141], v[212:213], v[140:141]
	s_nop 0
	v_mul_f32_e32 v2, v140, v141
	v_and_b32_e32 v141, 0xffff0000, v153
	v_mul_f32_e32 v140, 0xbfb8aa3b, v141
	v_exp_f32_e32 v140, v140
	v_mov_b32_e32 v212, v143
	v_add_f32_e32 v140, 1.0, v140
	v_rcp_f32_e32 v213, v140
	v_mov_b32_e32 v140, v103
	v_pk_mul_f32 v[140:141], v[212:213], v[140:141]
	s_nop 0
	v_mul_f32_e32 v140, v140, v141
	v_lshlrev_b32_e32 v141, 16, v154
	v_cvt_pk_bf16_f32 v153, v2, v140
	v_mul_f32_e32 v2, 0xbfb8aa3b, v141
	v_exp_f32_e32 v2, v2
	v_mov_b32_e32 v140, v92
	v_add_f32_e32 v2, 1.0, v2
	v_rcp_f32_e32 v143, v2
	s_nop 0
	v_pk_mul_f32 v[140:141], v[142:143], v[140:141]
	s_nop 0
	v_mul_f32_e32 v2, v140, v141
	v_and_b32_e32 v141, 0xffff0000, v154
	v_mul_f32_e32 v136, 0xbfb8aa3b, v141
	v_exp_f32_e32 v136, v136
	v_mov_b32_e32 v142, v137
	v_mov_b32_e32 v140, v93
	v_add_f32_e32 v136, 1.0, v136
	v_rcp_f32_e32 v143, v136
	s_nop 0
	v_pk_mul_f32 v[136:137], v[142:143], v[140:141]
	s_nop 0
	v_mul_f32_e32 v136, v136, v137
	v_lshlrev_b32_e32 v137, 16, v155
	v_cvt_pk_bf16_f32 v154, v2, v136
	v_mul_f32_e32 v2, 0xbfb8aa3b, v137
	v_exp_f32_e32 v2, v2
	v_mov_b32_e32 v140, v138
	v_mov_b32_e32 v136, v94
	v_mov_b32_e32 v142, v128
	v_add_f32_e32 v2, 1.0, v2
	v_rcp_f32_e32 v141, v2
	v_mov_b32_e32 v138, v100
	v_pk_mul_f32 v[136:137], v[140:141], v[136:137]
	s_nop 0
	v_mul_f32_e32 v2, v136, v137
	v_and_b32_e32 v137, 0xffff0000, v155
	v_mul_f32_e32 v136, 0xbfb8aa3b, v137
	v_exp_f32_e32 v136, v136
	v_mov_b32_e32 v140, v139
	v_lshlrev_b32_e32 v139, 16, v148
	v_add_f32_e32 v136, 1.0, v136
	v_rcp_f32_e32 v141, v136
	v_mov_b32_e32 v136, v95
	v_pk_mul_f32 v[136:137], v[140:141], v[136:137]
	s_nop 0
	v_mul_f32_e32 v136, v136, v137
	v_cvt_pk_bf16_f32 v155, v2, v136
	v_mul_f32_e32 v2, 0xbfb8aa3b, v139
	v_exp_f32_e32 v2, v2
	v_lshlrev_b64 v[140:141], 1, v[196:197]
	v_lshlrev_b64 v[136:137], 12, v[186:187]
	v_lshl_add_u64 v[136:137], s[8:9], 0, v[136:137]
	v_add_f32_e32 v2, 1.0, v2
	v_rcp_f32_e32 v143, v2
	v_lshl_add_u64 v[136:137], v[136:137], 0, v[140:141]
	flat_store_dwordx4 v[136:137], v[152:155]
	v_pk_mul_f32 v[138:139], v[142:143], v[138:139]
	s_nop 0
	v_mul_f32_e32 v2, v138, v139
	v_and_b32_e32 v139, 0xffff0000, v148
	v_mul_f32_e32 v128, 0xbfb8aa3b, v139
	v_exp_f32_e32 v128, v128
	v_mov_b32_e32 v142, v129
	v_mov_b32_e32 v138, v101
	v_add_f32_e32 v128, 1.0, v128
	v_rcp_f32_e32 v143, v128
	s_nop 0
	v_pk_mul_f32 v[128:129], v[142:143], v[138:139]
	s_nop 0
	v_mul_f32_e32 v128, v128, v129
	v_lshlrev_b32_e32 v139, 16, v149
	v_cvt_pk_bf16_f32 v128, v2, v128
	v_mul_f32_e32 v2, 0xbfb8aa3b, v139
	v_exp_f32_e32 v2, v2
	v_mov_b32_e32 v142, v130
	v_mov_b32_e32 v138, v102
	v_add_f32_e32 v2, 1.0, v2
	v_rcp_f32_e32 v143, v2
	s_nop 0
	v_pk_mul_f32 v[138:139], v[142:143], v[138:139]
	s_nop 0
	v_mul_f32_e32 v2, v138, v139
	v_and_b32_e32 v139, 0xffff0000, v149
	v_mul_f32_e32 v129, 0xbfb8aa3b, v139
	v_exp_f32_e32 v129, v129
	v_mov_b32_e32 v142, v131
	v_mov_b32_e32 v138, v103
	v_lshl_add_u64 v[148:149], v[186:187], 0, s[52:53]
	v_add_f32_e32 v129, 1.0, v129
	v_rcp_f32_e32 v143, v129
	s_nop 0
	v_pk_mul_f32 v[130:131], v[142:143], v[138:139]
	s_nop 0
	v_mul_f32_e32 v129, v130, v131
	v_lshlrev_b32_e32 v131, 16, v150
	v_cvt_pk_bf16_f32 v129, v2, v129
	v_mul_f32_e32 v2, 0xbfb8aa3b, v131
	v_exp_f32_e32 v2, v2
	v_mov_b32_e32 v138, v124
	v_mov_b32_e32 v130, v92
	v_add_f32_e32 v2, 1.0, v2
; __device__ __forceinline__ float bflo(unsigned v) { return __uint_as_float(v << 16); }
; __device__ __forceinline__ float bfhi(unsigned v) { return __uint_as_float(v & 0xffff0000u); }
; __device__ __forceinline__ float siluf_(float x) { return x * __builtin_amdgcn_rcpf(1.0f + __expf(-x)); }
;   __device__ __forceinline__ void operator()(EPI_ARGS) const {
;     ...
;         for (int m = 0; m < 4; ++m) {
;           const size_t row = row0 + ai * HALF + m * 16;
;           const f32x4 v0 = acc[ai][bj][m][0], v1 = acc[ai][bj][m][1];
;           u32x4 o;
;           o.x = pack2(v0[0] * s0[0] * siluf_(bflo(z[m].x)), v0[1] * s0[1] * siluf_(bfhi(z[m].x)));
;           o.y = pack2(v0[2] * s0[2] * siluf_(bflo(z[m].y)), v0[3] * s0[3] * siluf_(bfhi(z[m].y)));
;           o.z = pack2(v1[0] * s1[0] * siluf_(bflo(z[m].z)), v1[1] * s1[1] * siluf_(bfhi(z[m].z)));
;           o.w = pack2(v1[2] * s1[2] * siluf_(bflo(z[m].w)), v1[3] * s1[3] * siluf_(bfhi(z[m].w)));
;           *(u32x4*)(y0 + row * DM + c) = o;
;         }
	v_rcp_f32_e32 v139, v2
	s_nop 0
	v_pk_mul_f32 v[130:131], v[138:139], v[130:131]
	s_nop 0
	v_mul_f32_e32 v2, v130, v131
	v_and_b32_e32 v131, 0xffff0000, v150
	v_mul_f32_e32 v124, 0xbfb8aa3b, v131
	v_exp_f32_e32 v124, v124
	v_mov_b32_e32 v138, v125
	v_mov_b32_e32 v130, v93
	v_add_f32_e32 v124, 1.0, v124
	v_rcp_f32_e32 v139, v124
	s_nop 0
	v_pk_mul_f32 v[124:125], v[138:139], v[130:131]
	s_nop 0
	v_mul_f32_e32 v124, v124, v125
	v_lshlrev_b32_e32 v125, 16, v151
	v_cvt_pk_bf16_f32 v130, v2, v124
	v_mul_f32_e32 v2, 0xbfb8aa3b, v125
	v_exp_f32_e32 v2, v2
	v_mov_b32_e32 v138, v126
	v_mov_b32_e32 v124, v94
	v_mov_b32_e32 v126, v100
	v_add_f32_e32 v2, 1.0, v2
	v_rcp_f32_e32 v139, v2
	s_nop 0
	v_pk_mul_f32 v[124:125], v[138:139], v[124:125]
	s_nop 0
	v_mul_f32_e32 v2, v124, v125
	v_and_b32_e32 v125, 0xffff0000, v151
	v_mul_f32_e32 v124, 0xbfb8aa3b, v125
	v_exp_f32_e32 v124, v124
	v_mov_b32_e32 v138, v127
	v_lshlrev_b32_e32 v127, 16, v144
	v_add_f32_e32 v124, 1.0, v124
	v_rcp_f32_e32 v139, v124
	v_mov_b32_e32 v124, v95
	v_pk_mul_f32 v[124:125], v[138:139], v[124:125]
	s_nop 0
	v_mul_f32_e32 v124, v124, v125
	v_cvt_pk_bf16_f32 v131, v2, v124
	v_mul_f32_e32 v2, 0xbfb8aa3b, v127
	v_exp_f32_e32 v2, v2
	v_lshlrev_b64 v[124:125], 12, v[194:195]
	v_lshl_add_u64 v[124:125], s[8:9], 0, v[124:125]
	v_lshl_add_u64 v[124:125], v[124:125], 0, v[140:141]
	v_add_f32_e32 v2, 1.0, v2
	flat_store_dwordx4 v[124:125], v[128:131]
	s_nop 1
	v_rcp_f32_e32 v129, v2
	v_mov_b32_e32 v128, v120
	v_lshlrev_b64 v[130:131], 9, v[148:149]
	v_pk_mul_f32 v[126:127], v[128:129], v[126:127]
	s_nop 0
	v_mul_f32_e32 v2, v126, v127
	v_and_b32_e32 v127, 0xffff0000, v144
	v_mul_f32_e32 v120, 0xbfb8aa3b, v127
	v_exp_f32_e32 v120, v120
	v_mov_b32_e32 v128, v121
	v_mov_b32_e32 v126, v101
	v_add_f32_e32 v120, 1.0, v120
	v_rcp_f32_e32 v129, v120
	s_nop 0
	v_pk_mul_f32 v[120:121], v[128:129], v[126:127]
	s_nop 0
	v_mul_f32_e32 v120, v120, v121
	v_lshlrev_b32_e32 v127, 16, v145
	v_cvt_pk_bf16_f32 v120, v2, v120
	v_mul_f32_e32 v2, 0xbfb8aa3b, v127
	v_exp_f32_e32 v2, v2
	v_mov_b32_e32 v128, v122
	v_mov_b32_e32 v126, v102
	v_add_f32_e32 v2, 1.0, v2
	v_rcp_f32_e32 v129, v2
	s_nop 0
	v_pk_mul_f32 v[126:127], v[128:129], v[126:127]
	s_nop 0
	v_mul_f32_e32 v2, v126, v127
	v_and_b32_e32 v127, 0xffff0000, v145
	v_mul_f32_e32 v121, 0xbfb8aa3b, v127
	v_exp_f32_e32 v121, v121
	v_mov_b32_e32 v128, v123
	v_mov_b32_e32 v126, v103
	v_add_f32_e32 v121, 1.0, v121
	v_rcp_f32_e32 v129, v121
	s_nop 0
	v_pk_mul_f32 v[122:123], v[128:129], v[126:127]
	s_nop 0
	v_mul_f32_e32 v121, v122, v123
	v_lshlrev_b32_e32 v123, 16, v146
	v_cvt_pk_bf16_f32 v121, v2, v121
	v_mul_f32_e32 v2, 0xbfb8aa3b, v123
	v_exp_f32_e32 v2, v2
	v_mov_b32_e32 v126, v116
	v_mov_b32_e32 v122, v92
	v_add_f32_e32 v2, 1.0, v2
	v_rcp_f32_e32 v127, v2
	s_nop 0
	v_pk_mul_f32 v[122:123], v[126:127], v[122:123]
	s_nop 0
	v_mul_f32_e32 v2, v122, v123
	v_and_b32_e32 v123, 0xffff0000, v146
	v_mul_f32_e32 v116, 0xbfb8aa3b, v123
	v_exp_f32_e32 v116, v116
	v_mov_b32_e32 v126, v117
	v_mov_b32_e32 v122, v93
	v_add_f32_e32 v116, 1.0, v116
	v_rcp_f32_e32 v127, v116
	s_nop 0
	v_pk_mul_f32 v[116:117], v[126:127], v[122:123]
	s_nop 0
	v_mul_f32_e32 v116, v116, v117
	v_lshlrev_b32_e32 v117, 16, v147
	v_cvt_pk_bf16_f32 v122, v2, v116
	v_mul_f32_e32 v2, 0xbfb8aa3b, v117
	v_exp_f32_e32 v2, v2
	v_mov_b32_e32 v126, v118
	v_mov_b32_e32 v116, v94
	v_mov_b32_e32 v118, v112
	v_add_f32_e32 v2, 1.0, v2
	v_rcp_f32_e32 v127, v2
	s_nop 0
	v_pk_mul_f32 v[116:117], v[126:127], v[116:117]
	s_nop 0
	v_mul_f32_e32 v2, v116, v117
	v_and_b32_e32 v117, 0xffff0000, v147
	v_mul_f32_e32 v116, 0xbfb8aa3b, v117
	v_exp_f32_e32 v116, v116
	v_mov_b32_e32 v126, v119
	v_lshl_add_u64 v[146:147], v[186:187], 0, s[4:5]
	s_mov_b64 s[4:5], 0xa0
	v_add_f32_e32 v116, 1.0, v116
	v_rcp_f32_e32 v127, v116
	v_mov_b32_e32 v116, v95
	v_lshl_add_u64 v[144:145], v[186:187], 0, s[4:5]
	s_mov_b64 s[4:5], 0xb0
	v_pk_mul_f32 v[116:117], v[126:127], v[116:117]
	v_lshl_add_u64 v[142:143], v[186:187], 0, s[4:5]
	v_mul_f32_e32 v116, v116, v117
	v_cvt_pk_bf16_f32 v123, v2, v116
	v_lshlrev_b64 v[116:117], 12, v[192:193]
	v_lshl_add_u64 v[116:117], s[8:9], 0, v[116:117]
	v_lshl_add_u64 v[128:129], v[116:117], 0, v[140:141]
	v_lshlrev_b32_e32 v117, 16, v132
	v_mul_f32_e32 v2, 0xbfb8aa3b, v117
	v_exp_f32_e32 v2, v2
	v_mov_b32_e32 v116, v100
	flat_store_dwordx4 v[128:129], v[120:123]
	v_lshlrev_b64 v[138:139], 9, v[142:143]
	v_add_f32_e32 v2, 1.0, v2
	v_rcp_f32_e32 v119, v2
	s_nop 0
	v_pk_mul_f32 v[116:117], v[118:119], v[116:117]
	s_nop 0
	v_mul_f32_e32 v2, v116, v117
	v_and_b32_e32 v117, 0xffff0000, v132
	v_mul_f32_e32 v112, 0xbfb8aa3b, v117
	v_exp_f32_e32 v112, v112
	v_mov_b32_e32 v118, v113
	v_mov_b32_e32 v116, v101
	v_add_f32_e32 v112, 1.0, v112
	v_rcp_f32_e32 v119, v112
	s_nop 0
	v_pk_mul_f32 v[112:113], v[118:119], v[116:117]
	s_nop 0
	v_mul_f32_e32 v112, v112, v113
	v_lshlrev_b32_e32 v117, 16, v133
	v_cvt_pk_bf16_f32 v112, v2, v112
	v_mul_f32_e32 v2, 0xbfb8aa3b, v117
	v_exp_f32_e32 v2, v2
	v_mov_b32_e32 v118, v114
	v_mov_b32_e32 v116, v102
	v_add_f32_e32 v2, 1.0, v2
	v_rcp_f32_e32 v119, v2
	s_nop 0
	v_pk_mul_f32 v[116:117], v[118:119], v[116:117]
	s_nop 0
	v_mul_f32_e32 v2, v116, v117
	v_and_b32_e32 v117, 0xffff0000, v133
	v_mul_f32_e32 v113, 0xbfb8aa3b, v117
	v_exp_f32_e32 v113, v113
	v_mov_b32_e32 v118, v115
	v_mov_b32_e32 v116, v103
	v_lshlrev_b64 v[132:133], 9, v[146:147]
	v_add_f32_e32 v113, 1.0, v113
	v_rcp_f32_e32 v119, v113
	s_nop 0
	v_pk_mul_f32 v[114:115], v[118:119], v[116:117]
	s_nop 0
	v_mul_f32_e32 v113, v114, v115
	v_lshlrev_b32_e32 v115, 16, v134
	v_cvt_pk_bf16_f32 v113, v2, v113
	v_mul_f32_e32 v2, 0xbfb8aa3b, v115
; __device__ __forceinline__ size_t pidx(size_t row, int col) { return ((size_t)(col >> 8) * MTOK + row) * PLD + (col & 255); }
; __device__ __forceinline__ float bflo(unsigned v) { return __uint_as_float(v << 16); }
; __device__ __forceinline__ float bfhi(unsigned v) { return __uint_as_float(v & 0xffff0000u); }
; __device__ __forceinline__ float siluf_(float x) { return x * __builtin_amdgcn_rcpf(1.0f + __expf(-x)); }
;   __device__ __forceinline__ void operator()(EPI_ARGS) const {
;     ...
;       for (int ai = 0; ai < 2; ++ai) {
;         u32x4 z[4];
; #pragma unroll
;         for (int m = 0; m < 4; ++m) z[m] = *(const u32x4*)(proj + pidx(row0 + ai * HALF + m * 16, PZ + c));
;         __builtin_amdgcn_sched_barrier(0);
; #pragma unroll
;         for (int m = 0; m < 4; ++m) {
;           const size_t row = row0 + ai * HALF + m * 16;
;           const f32x4 v0 = acc[ai][bj][m][0], v1 = acc[ai][bj][m][1];
;           u32x4 o;
;           o.x = pack2(v0[0] * s0[0] * siluf_(bflo(z[m].x)), v0[1] * s0[1] * siluf_(bfhi(z[m].x)));
;           o.y = pack2(v0[2] * s0[2] * siluf_(bflo(z[m].y)), v0[3] * s0[3] * siluf_(bfhi(z[m].y)));
;           o.z = pack2(v1[0] * s1[0] * siluf_(bflo(z[m].z)), v1[1] * s1[1] * siluf_(bfhi(z[m].z)));
;           o.w = pack2(v1[2] * s1[2] * siluf_(bflo(z[m].w)), v1[3] * s1[3] * siluf_(bfhi(z[m].w)));
;           *(u32x4*)(y0 + row * DM + c) = o;
;         }
	v_exp_f32_e32 v2, v2
	v_mov_b32_e32 v116, v108
	v_mov_b32_e32 v114, v92
	v_add_f32_e32 v2, 1.0, v2
	v_rcp_f32_e32 v117, v2
	s_nop 0
	v_pk_mul_f32 v[114:115], v[116:117], v[114:115]
	s_nop 0
	v_mul_f32_e32 v2, v114, v115
	v_and_b32_e32 v115, 0xffff0000, v134
	v_mul_f32_e32 v108, 0xbfb8aa3b, v115
	v_exp_f32_e32 v108, v108
	v_mov_b32_e32 v116, v109
	v_mov_b32_e32 v114, v93
	v_add_f32_e32 v108, 1.0, v108
	v_rcp_f32_e32 v117, v108
	s_nop 0
	v_pk_mul_f32 v[108:109], v[116:117], v[114:115]
	s_nop 0
	v_mul_f32_e32 v108, v108, v109
	v_lshlrev_b32_e32 v109, 16, v135
	v_cvt_pk_bf16_f32 v114, v2, v108
	v_mul_f32_e32 v2, 0xbfb8aa3b, v109
	v_exp_f32_e32 v2, v2
	v_mov_b32_e32 v116, v110
	v_mov_b32_e32 v108, v94
	v_add_f32_e32 v2, 1.0, v2
	v_rcp_f32_e32 v117, v2
	s_nop 0
	v_pk_mul_f32 v[108:109], v[116:117], v[108:109]
	s_nop 0
	v_mul_f32_e32 v2, v108, v109
	v_and_b32_e32 v109, 0xffff0000, v135
	v_mul_f32_e32 v108, 0xbfb8aa3b, v109
	v_exp_f32_e32 v108, v108
	v_mov_b32_e32 v116, v111
	v_lshlrev_b64 v[134:135], 9, v[144:145]
	v_add_f32_e32 v108, 1.0, v108
	v_rcp_f32_e32 v117, v108
	v_mov_b32_e32 v108, v95
	v_pk_mul_f32 v[108:109], v[116:117], v[108:109]
	s_nop 0
	v_mul_f32_e32 v108, v108, v109
	v_cvt_pk_bf16_f32 v115, v2, v108
	v_lshlrev_b64 v[108:109], 12, v[190:191]
	v_lshl_add_u64 v[108:109], s[8:9], 0, v[108:109]
	v_lshl_add_u64 v[126:127], v[108:109], 0, v[140:141]
	flat_store_dwordx4 v[126:127], v[112:115]
	v_lshl_add_u64 v[108:109], v[188:189], 0, v[130:131]
	flat_load_dwordx4 v[120:123], v[108:109]
	v_lshl_add_u64 v[108:109], v[188:189], 0, v[132:133]
	flat_load_dwordx4 v[116:119], v[108:109]
	v_lshl_add_u64 v[108:109], v[188:189], 0, v[134:135]
	flat_load_dwordx4 v[112:115], v[108:109]
	v_lshl_add_u64 v[108:109], v[188:189], 0, v[138:139]
	flat_load_dwordx4 v[108:111], v[108:109]
	s_waitcnt vmcnt(0) lgkmcnt(0)
	v_lshlrev_b32_e32 v151, 16, v120
	v_mul_f32_e32 v2, 0xbfb8aa3b, v151
	v_exp_f32_e32 v2, v2
	v_mov_b32_e32 v152, v104
	v_mov_b32_e32 v150, v100
	v_mov_b32_e32 v175, v3
	v_add_f32_e32 v2, 1.0, v2
	v_rcp_f32_e32 v153, v2
	s_nop 0
	v_pk_mul_f32 v[150:151], v[152:153], v[150:151]
	s_nop 0
	v_mul_f32_e32 v2, v150, v151
	v_and_b32_e32 v151, 0xffff0000, v120
	v_mul_f32_e32 v104, 0xbfb8aa3b, v151
	v_exp_f32_e32 v104, v104
	v_mov_b32_e32 v152, v105
	v_mov_b32_e32 v150, v101
	v_mov_b32_e32 v120, v103
	v_add_f32_e32 v104, 1.0, v104
	v_rcp_f32_e32 v153, v104
	s_nop 0
	v_pk_mul_f32 v[104:105], v[152:153], v[150:151]
	s_nop 0
	v_mul_f32_e32 v104, v104, v105
	v_lshlrev_b32_e32 v151, 16, v121
	v_cvt_pk_bf16_f32 v104, v2, v104
	v_mul_f32_e32 v2, 0xbfb8aa3b, v151
	v_exp_f32_e32 v2, v2
	v_and_b32_e32 v121, 0xffff0000, v121
	v_mul_f32_e32 v105, 0xbfb8aa3b, v121
	v_exp_f32_e32 v105, v105
	v_add_f32_e32 v2, 1.0, v2
	v_rcp_f32_e32 v153, v2
	v_mov_b32_e32 v152, v106
	v_mov_b32_e32 v150, v102
	v_add_f32_e32 v105, 1.0, v105
	v_pk_mul_f32 v[150:151], v[152:153], v[150:151]
	s_nop 0
	v_mul_f32_e32 v2, v150, v151
	v_rcp_f32_e32 v151, v105
	v_mov_b32_e32 v150, v107
	v_pk_mul_f32 v[106:107], v[150:151], v[120:121]
	s_nop 0
	v_mul_f32_e32 v105, v106, v107
	v_lshlrev_b32_e32 v107, 16, v122
	v_cvt_pk_bf16_f32 v105, v2, v105
	v_mul_f32_e32 v2, 0xbfb8aa3b, v107
	v_exp_f32_e32 v2, v2
	v_mov_b32_e32 v120, v96
	v_mov_b32_e32 v106, v92
	v_add_f32_e32 v2, 1.0, v2
	v_rcp_f32_e32 v121, v2
	s_nop 0
	v_pk_mul_f32 v[106:107], v[120:121], v[106:107]
	s_nop 0
	v_mul_f32_e32 v2, v106, v107
	v_and_b32_e32 v107, 0xffff0000, v122
	v_mul_f32_e32 v96, 0xbfb8aa3b, v107
	v_exp_f32_e32 v96, v96
	v_mov_b32_e32 v120, v97
	v_mov_b32_e32 v106, v93
	v_add_f32_e32 v96, 1.0, v96
	v_rcp_f32_e32 v121, v96
	s_nop 0
	v_pk_mul_f32 v[96:97], v[120:121], v[106:107]
	s_nop 0
	v_mul_f32_e32 v96, v96, v97
	v_lshlrev_b32_e32 v97, 16, v123
	v_cvt_pk_bf16_f32 v106, v2, v96
	v_mul_f32_e32 v2, 0xbfb8aa3b, v97
	v_exp_f32_e32 v2, v2
	v_mov_b32_e32 v120, v98
	v_mov_b32_e32 v96, v94
	v_mov_b32_e32 v98, v100
	v_add_f32_e32 v2, 1.0, v2
	v_rcp_f32_e32 v121, v2
	s_nop 0
	v_pk_mul_f32 v[96:97], v[120:121], v[96:97]
	s_nop 0
	v_mul_f32_e32 v2, v96, v97
	v_and_b32_e32 v97, 0xffff0000, v123
	v_mul_f32_e32 v96, 0xbfb8aa3b, v97
	v_exp_f32_e32 v96, v96
	v_mov_b32_e32 v120, v99
	v_lshlrev_b32_e32 v99, 16, v116
	v_add_f32_e32 v96, 1.0, v96
	v_rcp_f32_e32 v121, v96
	v_mov_b32_e32 v96, v95
	v_pk_mul_f32 v[96:97], v[120:121], v[96:97]
	s_nop 0
	v_mul_f32_e32 v96, v96, v97
	v_cvt_pk_bf16_f32 v107, v2, v96
	v_mul_f32_e32 v2, 0xbfb8aa3b, v99
	v_exp_f32_e32 v2, v2
	v_lshlrev_b64 v[96:97], 12, v[148:149]
	v_lshl_add_u64 v[96:97], s[8:9], 0, v[96:97]
	v_lshl_add_u64 v[96:97], v[96:97], 0, v[140:141]
	v_add_f32_e32 v2, 1.0, v2
	flat_store_dwordx4 v[96:97], v[104:107]
	s_nop 1
	v_rcp_f32_e32 v105, v2
	v_mov_b32_e32 v104, v88
	v_pk_mul_f32 v[98:99], v[104:105], v[98:99]
	s_nop 0
	v_mul_f32_e32 v2, v98, v99
	v_and_b32_e32 v99, 0xffff0000, v116
	v_mul_f32_e32 v88, 0xbfb8aa3b, v99
	v_exp_f32_e32 v88, v88
	v_mov_b32_e32 v104, v89
	v_mov_b32_e32 v98, v101
	v_add_f32_e32 v88, 1.0, v88
	v_rcp_f32_e32 v105, v88
	s_nop 0
	v_pk_mul_f32 v[88:89], v[104:105], v[98:99]
	s_nop 0
	v_mul_f32_e32 v88, v88, v89
	v_lshlrev_b32_e32 v99, 16, v117
	v_cvt_pk_bf16_f32 v88, v2, v88
	v_mul_f32_e32 v2, 0xbfb8aa3b, v99
	v_exp_f32_e32 v2, v2
	v_mov_b32_e32 v104, v90
	v_mov_b32_e32 v98, v102
	v_add_f32_e32 v2, 1.0, v2
	v_rcp_f32_e32 v105, v2
	s_nop 0
	v_pk_mul_f32 v[98:99], v[104:105], v[98:99]
	s_nop 0
	v_mul_f32_e32 v2, v98, v99
	v_and_b32_e32 v99, 0xffff0000, v117
	v_mul_f32_e32 v89, 0xbfb8aa3b, v99
	v_exp_f32_e32 v89, v89
	v_mov_b32_e32 v104, v91
	v_mov_b32_e32 v98, v103
	v_add_f32_e32 v89, 1.0, v89
	v_rcp_f32_e32 v105, v89
	s_nop 0
	v_pk_mul_f32 v[90:91], v[104:105], v[98:99]
; __device__ __forceinline__ float bflo(unsigned v) { return __uint_as_float(v << 16); }
; __device__ __forceinline__ float bfhi(unsigned v) { return __uint_as_float(v & 0xffff0000u); }
; __device__ __forceinline__ float siluf_(float x) { return x * __builtin_amdgcn_rcpf(1.0f + __expf(-x)); }
;   __device__ __forceinline__ void operator()(EPI_ARGS) const {
;     ...
;         for (int m = 0; m < 4; ++m) {
;           const size_t row = row0 + ai * HALF + m * 16;
;           const f32x4 v0 = acc[ai][bj][m][0], v1 = acc[ai][bj][m][1];
;           u32x4 o;
;           o.x = pack2(v0[0] * s0[0] * siluf_(bflo(z[m].x)), v0[1] * s0[1] * siluf_(bfhi(z[m].x)));
;           o.y = pack2(v0[2] * s0[2] * siluf_(bflo(z[m].y)), v0[3] * s0[3] * siluf_(bfhi(z[m].y)));
;           o.z = pack2(v1[0] * s1[0] * siluf_(bflo(z[m].z)), v1[1] * s1[1] * siluf_(bfhi(z[m].z)));
;           o.w = pack2(v1[2] * s1[2] * siluf_(bflo(z[m].w)), v1[3] * s1[3] * siluf_(bfhi(z[m].w)));
;           *(u32x4*)(y0 + row * DM + c) = o;
;         }
	s_nop 0
	v_mul_f32_e32 v89, v90, v91
	v_lshlrev_b32_e32 v91, 16, v118
	v_cvt_pk_bf16_f32 v89, v2, v89
	v_mul_f32_e32 v2, 0xbfb8aa3b, v91
	v_exp_f32_e32 v2, v2
	v_mov_b32_e32 v98, v84
	v_mov_b32_e32 v90, v92
	v_add_f32_e32 v2, 1.0, v2
	v_rcp_f32_e32 v99, v2
	s_nop 0
	v_pk_mul_f32 v[90:91], v[98:99], v[90:91]
	s_nop 0
	v_mul_f32_e32 v2, v90, v91
	v_and_b32_e32 v91, 0xffff0000, v118
	v_mul_f32_e32 v84, 0xbfb8aa3b, v91
	v_exp_f32_e32 v84, v84
	v_mov_b32_e32 v98, v85
	v_mov_b32_e32 v90, v93
	v_add_f32_e32 v84, 1.0, v84
	v_rcp_f32_e32 v99, v84
	s_nop 0
	v_pk_mul_f32 v[84:85], v[98:99], v[90:91]
	s_nop 0
	v_mul_f32_e32 v84, v84, v85
	v_lshlrev_b32_e32 v85, 16, v119
	v_cvt_pk_bf16_f32 v90, v2, v84
	v_mul_f32_e32 v2, 0xbfb8aa3b, v85
	v_exp_f32_e32 v2, v2
	v_mov_b32_e32 v98, v86
	v_mov_b32_e32 v84, v94
	v_mov_b32_e32 v86, v80
	v_add_f32_e32 v2, 1.0, v2
	v_rcp_f32_e32 v99, v2
	s_nop 0
	v_pk_mul_f32 v[84:85], v[98:99], v[84:85]
	s_nop 0
	v_mul_f32_e32 v2, v84, v85
	v_and_b32_e32 v85, 0xffff0000, v119
	v_mul_f32_e32 v84, 0xbfb8aa3b, v85
	v_exp_f32_e32 v84, v84
	v_mov_b32_e32 v98, v87
	v_add_f32_e32 v84, 1.0, v84
	v_rcp_f32_e32 v99, v84
	v_mov_b32_e32 v84, v95
	v_pk_mul_f32 v[84:85], v[98:99], v[84:85]
	s_nop 0
	v_mul_f32_e32 v84, v84, v85
	v_cvt_pk_bf16_f32 v91, v2, v84
	v_lshlrev_b64 v[84:85], 12, v[146:147]
	v_lshl_add_u64 v[84:85], s[8:9], 0, v[84:85]
	v_lshl_add_u64 v[98:99], v[84:85], 0, v[140:141]
	v_lshlrev_b32_e32 v85, 16, v112
	v_mul_f32_e32 v2, 0xbfb8aa3b, v85
	v_exp_f32_e32 v2, v2
	v_mov_b32_e32 v84, v100
	flat_store_dwordx4 v[98:99], v[88:91]
	v_add_f32_e32 v2, 1.0, v2
	v_rcp_f32_e32 v87, v2
	s_nop 0
	v_pk_mul_f32 v[84:85], v[86:87], v[84:85]
	s_nop 0
	v_mul_f32_e32 v2, v84, v85
	v_and_b32_e32 v85, 0xffff0000, v112
	v_mul_f32_e32 v80, 0xbfb8aa3b, v85
	v_exp_f32_e32 v80, v80
	v_mov_b32_e32 v86, v81
	v_mov_b32_e32 v84, v101
	v_add_f32_e32 v80, 1.0, v80
	v_rcp_f32_e32 v87, v80
	s_nop 0
	v_pk_mul_f32 v[80:81], v[86:87], v[84:85]
	s_nop 0
	v_mul_f32_e32 v80, v80, v81
	v_lshlrev_b32_e32 v85, 16, v113
	v_cvt_pk_bf16_f32 v80, v2, v80
	v_mul_f32_e32 v2, 0xbfb8aa3b, v85
	v_exp_f32_e32 v2, v2
	v_mov_b32_e32 v86, v82
	v_mov_b32_e32 v84, v102
	v_add_f32_e32 v2, 1.0, v2
	v_rcp_f32_e32 v87, v2
	s_nop 0
	v_pk_mul_f32 v[84:85], v[86:87], v[84:85]
	s_nop 0
	v_mul_f32_e32 v2, v84, v85
	v_and_b32_e32 v85, 0xffff0000, v113
	v_mul_f32_e32 v81, 0xbfb8aa3b, v85
	v_exp_f32_e32 v81, v81
	v_mov_b32_e32 v86, v83
	v_mov_b32_e32 v84, v103
	v_add_f32_e32 v81, 1.0, v81
	v_rcp_f32_e32 v87, v81
	s_nop 0
	v_pk_mul_f32 v[82:83], v[86:87], v[84:85]
	s_nop 0
	v_mul_f32_e32 v81, v82, v83
	v_lshlrev_b32_e32 v83, 16, v114
	v_cvt_pk_bf16_f32 v81, v2, v81
	v_mul_f32_e32 v2, 0xbfb8aa3b, v83
	v_exp_f32_e32 v2, v2
	v_mov_b32_e32 v84, v76
	v_mov_b32_e32 v82, v92
	v_add_f32_e32 v2, 1.0, v2
	v_rcp_f32_e32 v85, v2
	s_nop 0
	v_pk_mul_f32 v[82:83], v[84:85], v[82:83]
	s_nop 0
	v_mul_f32_e32 v2, v82, v83
	v_and_b32_e32 v83, 0xffff0000, v114
	v_mul_f32_e32 v76, 0xbfb8aa3b, v83
	v_exp_f32_e32 v76, v76
	v_mov_b32_e32 v84, v77
	v_mov_b32_e32 v82, v93
	v_add_f32_e32 v76, 1.0, v76
	v_rcp_f32_e32 v85, v76
	s_nop 0
	v_pk_mul_f32 v[76:77], v[84:85], v[82:83]
	s_nop 0
	v_mul_f32_e32 v76, v76, v77
	v_lshlrev_b32_e32 v77, 16, v115
	v_cvt_pk_bf16_f32 v82, v2, v76
	v_mul_f32_e32 v2, 0xbfb8aa3b, v77
	v_exp_f32_e32 v2, v2
	v_mov_b32_e32 v84, v78
	v_mov_b32_e32 v76, v94
	v_mov_b32_e32 v78, v72
	v_add_f32_e32 v2, 1.0, v2
	v_rcp_f32_e32 v85, v2
	s_nop 0
	v_pk_mul_f32 v[76:77], v[84:85], v[76:77]
	s_nop 0
	v_mul_f32_e32 v2, v76, v77
	v_and_b32_e32 v77, 0xffff0000, v115
	v_mul_f32_e32 v76, 0xbfb8aa3b, v77
	v_exp_f32_e32 v76, v76
	v_mov_b32_e32 v84, v79
	v_add_f32_e32 v76, 1.0, v76
	v_rcp_f32_e32 v85, v76
	v_mov_b32_e32 v76, v95
	v_pk_mul_f32 v[76:77], v[84:85], v[76:77]
	s_nop 0
	v_mul_f32_e32 v76, v76, v77
	v_cvt_pk_bf16_f32 v83, v2, v76
	v_lshlrev_b64 v[76:77], 12, v[144:145]
	v_lshl_add_u64 v[76:77], s[8:9], 0, v[76:77]
	v_lshl_add_u64 v[104:105], v[76:77], 0, v[140:141]
	v_lshlrev_b32_e32 v77, 16, v108
	v_mul_f32_e32 v2, 0xbfb8aa3b, v77
	v_exp_f32_e32 v2, v2
	v_mov_b32_e32 v76, v100
	flat_store_dwordx4 v[104:105], v[80:83]
	v_add_f32_e32 v2, 1.0, v2
	v_rcp_f32_e32 v79, v2
	s_nop 0
	v_pk_mul_f32 v[76:77], v[78:79], v[76:77]
	s_nop 0
	v_mul_f32_e32 v2, v76, v77
	v_and_b32_e32 v77, 0xffff0000, v108
	v_mul_f32_e32 v72, 0xbfb8aa3b, v77
	v_exp_f32_e32 v72, v72
	v_mov_b32_e32 v78, v73
	v_mov_b32_e32 v76, v101
	v_add_f32_e32 v72, 1.0, v72
	v_rcp_f32_e32 v79, v72
	s_nop 0
	v_pk_mul_f32 v[72:73], v[78:79], v[76:77]
	s_nop 0
	v_mul_f32_e32 v72, v72, v73
	v_lshlrev_b32_e32 v77, 16, v109
	v_cvt_pk_bf16_f32 v72, v2, v72
	v_mul_f32_e32 v2, 0xbfb8aa3b, v77
	v_exp_f32_e32 v2, v2
	v_mov_b32_e32 v78, v74
	v_mov_b32_e32 v76, v102
	v_add_f32_e32 v2, 1.0, v2
	v_rcp_f32_e32 v79, v2
	s_nop 0
	v_pk_mul_f32 v[76:77], v[78:79], v[76:77]
	s_nop 0
	v_mul_f32_e32 v2, v76, v77
	v_and_b32_e32 v77, 0xffff0000, v109
	v_mul_f32_e32 v73, 0xbfb8aa3b, v77
	v_exp_f32_e32 v73, v73
	v_mov_b32_e32 v78, v75
	v_mov_b32_e32 v76, v103
	v_add_f32_e32 v73, 1.0, v73
	v_rcp_f32_e32 v79, v73
	s_nop 0
	v_pk_mul_f32 v[74:75], v[78:79], v[76:77]
	s_nop 0
	v_mul_f32_e32 v73, v74, v75
	v_lshlrev_b32_e32 v75, 16, v110
	v_cvt_pk_bf16_f32 v73, v2, v73
	v_mul_f32_e32 v2, 0xbfb8aa3b, v75
	v_exp_f32_e32 v2, v2
	v_mov_b32_e32 v76, v68
	v_mov_b32_e32 v74, v92
	v_add_f32_e32 v2, 1.0, v2
	v_rcp_f32_e32 v77, v2
	s_nop 0
	v_pk_mul_f32 v[74:75], v[76:77], v[74:75]
	s_nop 0
	v_mul_f32_e32 v2, v74, v75
	v_and_b32_e32 v75, 0xffff0000, v110
	v_mul_f32_e32 v68, 0xbfb8aa3b, v75
	v_exp_f32_e32 v68, v68
	v_mov_b32_e32 v76, v69
	v_mov_b32_e32 v74, v93
	v_add_f32_e32 v68, 1.0, v68
; __device__ __forceinline__ size_t pidx(size_t row, int col) { return ((size_t)(col >> 8) * MTOK + row) * PLD + (col & 255); }
; __device__ __forceinline__ float bflo(unsigned v) { return __uint_as_float(v << 16); }
; __device__ __forceinline__ float bfhi(unsigned v) { return __uint_as_float(v & 0xffff0000u); }
; __device__ __forceinline__ float siluf_(float x) { return x * __builtin_amdgcn_rcpf(1.0f + __expf(-x)); }
;   __device__ __forceinline__ void operator()(EPI_ARGS) const {
;     ...
;     for (int bj = 0; bj < 2; ++bj) {
;       const int c = col0 + bj * HALF;
;       const f32x4 s0 = *(const f32x4*)(psc + c), s1 = *(const f32x4*)(psc + c + 4);
; #pragma unroll
;       for (int ai = 0; ai < 2; ++ai) {
;         u32x4 z[4];
; #pragma unroll
;         for (int m = 0; m < 4; ++m) z[m] = *(const u32x4*)(proj + pidx(row0 + ai * HALF + m * 16, PZ + c));
;         __builtin_amdgcn_sched_barrier(0);
; #pragma unroll
;         for (int m = 0; m < 4; ++m) {
;           const size_t row = row0 + ai * HALF + m * 16;
;           const f32x4 v0 = acc[ai][bj][m][0], v1 = acc[ai][bj][m][1];
;           u32x4 o;
;           o.x = pack2(v0[0] * s0[0] * siluf_(bflo(z[m].x)), v0[1] * s0[1] * siluf_(bfhi(z[m].x)));
;           o.y = pack2(v0[2] * s0[2] * siluf_(bflo(z[m].y)), v0[3] * s0[3] * siluf_(bfhi(z[m].y)));
;           o.z = pack2(v1[0] * s1[0] * siluf_(bflo(z[m].z)), v1[1] * s1[1] * siluf_(bfhi(z[m].z)));
;           o.w = pack2(v1[2] * s1[2] * siluf_(bflo(z[m].w)), v1[3] * s1[3] * siluf_(bfhi(z[m].w)));
;           *(u32x4*)(y0 + row * DM + c) = o;
;         }
	v_rcp_f32_e32 v77, v68
	s_nop 0
	v_pk_mul_f32 v[68:69], v[76:77], v[74:75]
	s_nop 0
	v_mul_f32_e32 v68, v68, v69
	v_lshlrev_b32_e32 v69, 16, v111
	v_cvt_pk_bf16_f32 v74, v2, v68
	v_mul_f32_e32 v2, 0xbfb8aa3b, v69
	v_exp_f32_e32 v2, v2
	v_mov_b32_e32 v76, v70
	v_mov_b32_e32 v68, v94
	v_add_f32_e32 v2, 1.0, v2
	v_rcp_f32_e32 v77, v2
	s_nop 0
	v_pk_mul_f32 v[68:69], v[76:77], v[68:69]
	s_nop 0
	v_mul_f32_e32 v2, v68, v69
	v_and_b32_e32 v69, 0xffff0000, v111
	v_mul_f32_e32 v68, 0xbfb8aa3b, v69
	v_exp_f32_e32 v68, v68
	v_mov_b32_e32 v76, v71
	v_add_f32_e32 v68, 1.0, v68
	v_rcp_f32_e32 v77, v68
	v_mov_b32_e32 v68, v95
	v_lshl_add_u64 v[94:95], s[2:3], 0, v[174:175]
	v_pk_mul_f32 v[68:69], v[76:77], v[68:69]
	s_nop 0
	v_mul_f32_e32 v68, v68, v69
	v_cvt_pk_bf16_f32 v75, v2, v68
	v_lshlrev_b64 v[68:69], 12, v[142:143]
	v_lshl_add_u64 v[68:69], s[8:9], 0, v[68:69]
	v_lshl_add_u64 v[92:93], v[68:69], 0, v[140:141]
	flat_store_dwordx4 v[92:93], v[72:75]
	v_lshl_add_u64 v[76:77], v[94:95], 0, v[178:179]
	global_load_dwordx4 v[68:71], v[176:177], off offset:528
	global_load_dwordx4 v[72:75], v[176:177], off offset:512
	flat_load_dwordx4 v[88:91], v[76:77]
	v_lshl_add_u64 v[76:77], v[94:95], 0, v[180:181]
	flat_load_dwordx4 v[84:87], v[76:77]
	v_lshl_add_u64 v[76:77], v[94:95], 0, v[182:183]
	flat_load_dwordx4 v[80:83], v[76:77]
	v_lshl_add_u64 v[76:77], v[94:95], 0, v[184:185]
	flat_load_dwordx4 v[76:79], v[76:77]
	s_waitcnt vmcnt(0) lgkmcnt(0)
	v_lshlrev_b32_e32 v101, 16, v88
	v_mul_f32_e32 v2, 0xbfb8aa3b, v101
	v_exp_f32_e32 v2, v2
	v_mov_b32_e32 v102, v64
	v_mov_b32_e32 v100, v72
	v_add_f32_e32 v2, 1.0, v2
	v_rcp_f32_e32 v103, v2
	s_nop 0
	v_pk_mul_f32 v[100:101], v[102:103], v[100:101]
	s_nop 0
	v_mul_f32_e32 v2, v100, v101
	v_and_b32_e32 v101, 0xffff0000, v88
	v_mul_f32_e32 v64, 0xbfb8aa3b, v101
	v_exp_f32_e32 v64, v64
	v_mov_b32_e32 v102, v65
	v_mov_b32_e32 v100, v73
	v_mov_b32_e32 v88, v75
	v_add_f32_e32 v64, 1.0, v64
	v_rcp_f32_e32 v103, v64
	s_nop 0
	v_pk_mul_f32 v[64:65], v[102:103], v[100:101]
	s_nop 0
	v_mul_f32_e32 v64, v64, v65
	v_lshlrev_b32_e32 v101, 16, v89
	v_cvt_pk_bf16_f32 v64, v2, v64
	v_mul_f32_e32 v2, 0xbfb8aa3b, v101
	v_exp_f32_e32 v2, v2
	v_and_b32_e32 v89, 0xffff0000, v89
	v_mul_f32_e32 v65, 0xbfb8aa3b, v89
	v_exp_f32_e32 v65, v65
	v_add_f32_e32 v2, 1.0, v2
	v_rcp_f32_e32 v103, v2
	v_mov_b32_e32 v102, v66
	v_mov_b32_e32 v100, v74
	v_add_f32_e32 v65, 1.0, v65
	v_pk_mul_f32 v[100:101], v[102:103], v[100:101]
	s_nop 0
	v_mul_f32_e32 v2, v100, v101
	v_rcp_f32_e32 v101, v65
	v_mov_b32_e32 v100, v67
	v_pk_mul_f32 v[66:67], v[100:101], v[88:89]
	s_nop 0
	v_mul_f32_e32 v65, v66, v67
	v_lshlrev_b32_e32 v67, 16, v90
	v_cvt_pk_bf16_f32 v65, v2, v65
	v_mul_f32_e32 v2, 0xbfb8aa3b, v67
	v_exp_f32_e32 v2, v2
	v_mov_b32_e32 v88, v60
	v_mov_b32_e32 v66, v68
	v_add_f32_e32 v2, 1.0, v2
	v_rcp_f32_e32 v89, v2
	s_nop 0
	v_pk_mul_f32 v[66:67], v[88:89], v[66:67]
	s_nop 0
	v_mul_f32_e32 v2, v66, v67
	v_and_b32_e32 v67, 0xffff0000, v90
	v_mul_f32_e32 v60, 0xbfb8aa3b, v67
	v_exp_f32_e32 v60, v60
	v_mov_b32_e32 v88, v61
	v_mov_b32_e32 v66, v69
	v_add_f32_e32 v60, 1.0, v60
	v_rcp_f32_e32 v89, v60
	s_nop 0
	v_pk_mul_f32 v[60:61], v[88:89], v[66:67]
	s_nop 0
	v_mul_f32_e32 v60, v60, v61
	v_lshlrev_b32_e32 v61, 16, v91
	v_cvt_pk_bf16_f32 v66, v2, v60
	v_mul_f32_e32 v2, 0xbfb8aa3b, v61
	v_exp_f32_e32 v2, v2
	v_mov_b32_e32 v88, v62
	v_mov_b32_e32 v60, v70
	v_mov_b32_e32 v62, v56
	v_add_f32_e32 v2, 1.0, v2
	v_rcp_f32_e32 v89, v2
	s_nop 0
	v_pk_mul_f32 v[60:61], v[88:89], v[60:61]
	s_nop 0
	v_mul_f32_e32 v2, v60, v61
	v_and_b32_e32 v61, 0xffff0000, v91
	v_mul_f32_e32 v60, 0xbfb8aa3b, v61
	v_exp_f32_e32 v60, v60
	v_mov_b32_e32 v88, v63
	v_add_f32_e32 v60, 1.0, v60
	v_rcp_f32_e32 v89, v60
	v_mov_b32_e32 v60, v71
	v_pk_mul_f32 v[60:61], v[88:89], v[60:61]
	s_nop 0
	v_mul_f32_e32 v60, v60, v61
	v_lshlrev_b32_e32 v61, 16, v84
	v_cvt_pk_bf16_f32 v67, v2, v60
	v_mul_f32_e32 v2, 0xbfb8aa3b, v61
	v_exp_f32_e32 v2, v2
	v_mov_b32_e32 v60, v72
	flat_store_dwordx4 v[136:137], v[64:67] offset:256
	v_add_f32_e32 v2, 1.0, v2
	v_rcp_f32_e32 v63, v2
	s_nop 0
	v_pk_mul_f32 v[60:61], v[62:63], v[60:61]
	s_nop 0
	v_mul_f32_e32 v2, v60, v61
	v_and_b32_e32 v61, 0xffff0000, v84
	v_mul_f32_e32 v56, 0xbfb8aa3b, v61
	v_exp_f32_e32 v56, v56
	v_mov_b32_e32 v62, v57
	v_mov_b32_e32 v60, v73
	v_add_f32_e32 v56, 1.0, v56
	v_rcp_f32_e32 v63, v56
	s_nop 0
	v_pk_mul_f32 v[56:57], v[62:63], v[60:61]
	s_nop 0
	v_mul_f32_e32 v56, v56, v57
	v_lshlrev_b32_e32 v61, 16, v85
	v_cvt_pk_bf16_f32 v56, v2, v56
	v_mul_f32_e32 v2, 0xbfb8aa3b, v61
	v_exp_f32_e32 v2, v2
	v_mov_b32_e32 v62, v58
	v_mov_b32_e32 v60, v74
	v_add_f32_e32 v2, 1.0, v2
	v_rcp_f32_e32 v63, v2
	s_nop 0
	v_pk_mul_f32 v[60:61], v[62:63], v[60:61]
	s_nop 0
	v_mul_f32_e32 v2, v60, v61
	v_and_b32_e32 v61, 0xffff0000, v85
	v_mul_f32_e32 v57, 0xbfb8aa3b, v61
	v_exp_f32_e32 v57, v57
	v_mov_b32_e32 v62, v59
	v_mov_b32_e32 v60, v75
	v_add_f32_e32 v57, 1.0, v57
	v_rcp_f32_e32 v63, v57
	s_nop 0
	v_pk_mul_f32 v[58:59], v[62:63], v[60:61]
	s_nop 0
	v_mul_f32_e32 v57, v58, v59
	v_lshlrev_b32_e32 v59, 16, v86
	v_cvt_pk_bf16_f32 v57, v2, v57
	v_mul_f32_e32 v2, 0xbfb8aa3b, v59
	v_exp_f32_e32 v2, v2
	v_mov_b32_e32 v60, v52
	v_mov_b32_e32 v58, v68
	v_add_f32_e32 v2, 1.0, v2
	v_rcp_f32_e32 v61, v2
	s_nop 0
	v_pk_mul_f32 v[58:59], v[60:61], v[58:59]
	s_nop 0
	v_mul_f32_e32 v2, v58, v59
	v_and_b32_e32 v59, 0xffff0000, v86
	v_mul_f32_e32 v52, 0xbfb8aa3b, v59
	v_exp_f32_e32 v52, v52
	v_mov_b32_e32 v60, v53
	v_mov_b32_e32 v58, v69
	v_add_f32_e32 v52, 1.0, v52
	v_rcp_f32_e32 v61, v52
	s_nop 0
	v_pk_mul_f32 v[52:53], v[60:61], v[58:59]
	s_nop 0
	v_mul_f32_e32 v52, v52, v53
; __device__ __forceinline__ size_t pidx(size_t row, int col) { return ((size_t)(col >> 8) * MTOK + row) * PLD + (col & 255); }
; __device__ __forceinline__ float bflo(unsigned v) { return __uint_as_float(v << 16); }
; __device__ __forceinline__ float bfhi(unsigned v) { return __uint_as_float(v & 0xffff0000u); }
; __device__ __forceinline__ float siluf_(float x) { return x * __builtin_amdgcn_rcpf(1.0f + __expf(-x)); }
;   __device__ __forceinline__ void operator()(EPI_ARGS) const {
;     ...
;       for (int ai = 0; ai < 2; ++ai) {
;         u32x4 z[4];
; #pragma unroll
;         for (int m = 0; m < 4; ++m) z[m] = *(const u32x4*)(proj + pidx(row0 + ai * HALF + m * 16, PZ + c));
;         __builtin_amdgcn_sched_barrier(0);
; #pragma unroll
;         for (int m = 0; m < 4; ++m) {
;           const size_t row = row0 + ai * HALF + m * 16;
;           const f32x4 v0 = acc[ai][bj][m][0], v1 = acc[ai][bj][m][1];
;           u32x4 o;
;           o.x = pack2(v0[0] * s0[0] * siluf_(bflo(z[m].x)), v0[1] * s0[1] * siluf_(bfhi(z[m].x)));
;           o.y = pack2(v0[2] * s0[2] * siluf_(bflo(z[m].y)), v0[3] * s0[3] * siluf_(bfhi(z[m].y)));
;           o.z = pack2(v1[0] * s1[0] * siluf_(bflo(z[m].z)), v1[1] * s1[1] * siluf_(bfhi(z[m].z)));
;           o.w = pack2(v1[2] * s1[2] * siluf_(bflo(z[m].w)), v1[3] * s1[3] * siluf_(bfhi(z[m].w)));
;           *(u32x4*)(y0 + row * DM + c) = o;
;         }
	v_lshlrev_b32_e32 v53, 16, v87
	v_cvt_pk_bf16_f32 v58, v2, v52
	v_mul_f32_e32 v2, 0xbfb8aa3b, v53
	v_exp_f32_e32 v2, v2
	v_mov_b32_e32 v60, v54
	v_mov_b32_e32 v52, v70
	v_mov_b32_e32 v54, v48
	v_add_f32_e32 v2, 1.0, v2
	v_rcp_f32_e32 v61, v2
	s_nop 0
	v_pk_mul_f32 v[52:53], v[60:61], v[52:53]
	s_nop 0
	v_mul_f32_e32 v2, v52, v53
	v_and_b32_e32 v53, 0xffff0000, v87
	v_mul_f32_e32 v52, 0xbfb8aa3b, v53
	v_exp_f32_e32 v52, v52
	v_mov_b32_e32 v60, v55
	v_add_f32_e32 v52, 1.0, v52
	v_rcp_f32_e32 v61, v52
	v_mov_b32_e32 v52, v71
	v_pk_mul_f32 v[52:53], v[60:61], v[52:53]
	s_nop 0
	v_mul_f32_e32 v52, v52, v53
	v_lshlrev_b32_e32 v53, 16, v80
	v_cvt_pk_bf16_f32 v59, v2, v52
	v_mul_f32_e32 v2, 0xbfb8aa3b, v53
	v_exp_f32_e32 v2, v2
	v_mov_b32_e32 v52, v72
	flat_store_dwordx4 v[124:125], v[56:59] offset:256
	v_add_f32_e32 v2, 1.0, v2
	v_rcp_f32_e32 v55, v2
	s_nop 0
	v_pk_mul_f32 v[52:53], v[54:55], v[52:53]
	s_nop 0
	v_mul_f32_e32 v2, v52, v53
	v_and_b32_e32 v53, 0xffff0000, v80
	v_mul_f32_e32 v48, 0xbfb8aa3b, v53
	v_exp_f32_e32 v48, v48
	v_mov_b32_e32 v54, v49
	v_mov_b32_e32 v52, v73
	v_add_f32_e32 v48, 1.0, v48
	v_rcp_f32_e32 v55, v48
	s_nop 0
	v_pk_mul_f32 v[48:49], v[54:55], v[52:53]
	s_nop 0
	v_mul_f32_e32 v48, v48, v49
	v_lshlrev_b32_e32 v53, 16, v81
	v_cvt_pk_bf16_f32 v48, v2, v48
	v_mul_f32_e32 v2, 0xbfb8aa3b, v53
	v_exp_f32_e32 v2, v2
	v_mov_b32_e32 v54, v50
	v_mov_b32_e32 v52, v74
	v_add_f32_e32 v2, 1.0, v2
	v_rcp_f32_e32 v55, v2
	s_nop 0
	v_pk_mul_f32 v[52:53], v[54:55], v[52:53]
	s_nop 0
	v_mul_f32_e32 v2, v52, v53
	v_and_b32_e32 v53, 0xffff0000, v81
	v_mul_f32_e32 v49, 0xbfb8aa3b, v53
	v_exp_f32_e32 v49, v49
	v_mov_b32_e32 v54, v51
	v_mov_b32_e32 v52, v75
	v_add_f32_e32 v49, 1.0, v49
	v_rcp_f32_e32 v55, v49
	s_nop 0
	v_pk_mul_f32 v[50:51], v[54:55], v[52:53]
	s_nop 0
	v_mul_f32_e32 v49, v50, v51
	v_lshlrev_b32_e32 v51, 16, v82
	v_cvt_pk_bf16_f32 v49, v2, v49
	v_mul_f32_e32 v2, 0xbfb8aa3b, v51
	v_exp_f32_e32 v2, v2
	v_mov_b32_e32 v52, v44
	v_mov_b32_e32 v50, v68
	v_add_f32_e32 v2, 1.0, v2
	v_rcp_f32_e32 v53, v2
	s_nop 0
	v_pk_mul_f32 v[50:51], v[52:53], v[50:51]
	s_nop 0
	v_mul_f32_e32 v2, v50, v51
	v_and_b32_e32 v51, 0xffff0000, v82
	v_mul_f32_e32 v44, 0xbfb8aa3b, v51
	v_exp_f32_e32 v44, v44
	v_mov_b32_e32 v52, v45
	v_mov_b32_e32 v50, v69
	v_add_f32_e32 v44, 1.0, v44
	v_rcp_f32_e32 v53, v44
	s_nop 0
	v_pk_mul_f32 v[44:45], v[52:53], v[50:51]
	s_nop 0
	v_mul_f32_e32 v44, v44, v45
	v_lshlrev_b32_e32 v45, 16, v83
	v_cvt_pk_bf16_f32 v50, v2, v44
	v_mul_f32_e32 v2, 0xbfb8aa3b, v45
	v_exp_f32_e32 v2, v2
	v_mov_b32_e32 v52, v46
	v_mov_b32_e32 v44, v70
	v_mov_b32_e32 v46, v40
	v_add_f32_e32 v2, 1.0, v2
	v_rcp_f32_e32 v53, v2
	s_nop 0
	v_pk_mul_f32 v[44:45], v[52:53], v[44:45]
	s_nop 0
	v_mul_f32_e32 v2, v44, v45
	v_and_b32_e32 v45, 0xffff0000, v83
	v_mul_f32_e32 v44, 0xbfb8aa3b, v45
	v_exp_f32_e32 v44, v44
	v_mov_b32_e32 v52, v47
	v_add_f32_e32 v44, 1.0, v44
	v_rcp_f32_e32 v53, v44
	v_mov_b32_e32 v44, v71
	v_pk_mul_f32 v[44:45], v[52:53], v[44:45]
	s_nop 0
	v_mul_f32_e32 v44, v44, v45
	v_lshlrev_b32_e32 v45, 16, v76
	v_cvt_pk_bf16_f32 v51, v2, v44
	v_mul_f32_e32 v2, 0xbfb8aa3b, v45
	v_exp_f32_e32 v2, v2
	v_mov_b32_e32 v44, v72
	flat_store_dwordx4 v[128:129], v[48:51] offset:256
	v_add_f32_e32 v2, 1.0, v2
	v_rcp_f32_e32 v47, v2
	s_nop 0
	v_pk_mul_f32 v[44:45], v[46:47], v[44:45]
	s_nop 0
	v_mul_f32_e32 v2, v44, v45
	v_and_b32_e32 v45, 0xffff0000, v76
	v_mul_f32_e32 v40, 0xbfb8aa3b, v45
	v_exp_f32_e32 v40, v40
	v_mov_b32_e32 v46, v41
	v_mov_b32_e32 v44, v73
	v_add_f32_e32 v40, 1.0, v40
	v_rcp_f32_e32 v47, v40
	s_nop 0
	v_pk_mul_f32 v[40:41], v[46:47], v[44:45]
	s_nop 0
	v_mul_f32_e32 v40, v40, v41
	v_lshlrev_b32_e32 v45, 16, v77
	v_cvt_pk_bf16_f32 v40, v2, v40
	v_mul_f32_e32 v2, 0xbfb8aa3b, v45
	v_exp_f32_e32 v2, v2
	v_mov_b32_e32 v46, v42
	v_mov_b32_e32 v44, v74
	v_add_f32_e32 v2, 1.0, v2
	v_rcp_f32_e32 v47, v2
	s_nop 0
	v_pk_mul_f32 v[44:45], v[46:47], v[44:45]
	s_nop 0
	v_mul_f32_e32 v2, v44, v45
	v_and_b32_e32 v45, 0xffff0000, v77
	v_mul_f32_e32 v41, 0xbfb8aa3b, v45
	v_exp_f32_e32 v41, v41
	v_mov_b32_e32 v46, v43
	v_mov_b32_e32 v44, v75
	v_add_f32_e32 v41, 1.0, v41
	v_rcp_f32_e32 v47, v41
	s_nop 0
	v_pk_mul_f32 v[42:43], v[46:47], v[44:45]
	s_nop 0
	v_mul_f32_e32 v41, v42, v43
	v_lshlrev_b32_e32 v43, 16, v78
	v_cvt_pk_bf16_f32 v41, v2, v41
	v_mul_f32_e32 v2, 0xbfb8aa3b, v43
	v_exp_f32_e32 v2, v2
	v_mov_b32_e32 v44, v36
	v_mov_b32_e32 v42, v68
	v_add_f32_e32 v2, 1.0, v2
	v_rcp_f32_e32 v45, v2
	s_nop 0
	v_pk_mul_f32 v[42:43], v[44:45], v[42:43]
	s_nop 0
	v_mul_f32_e32 v2, v42, v43
	v_and_b32_e32 v43, 0xffff0000, v78
	v_mul_f32_e32 v36, 0xbfb8aa3b, v43
	v_exp_f32_e32 v36, v36
	v_mov_b32_e32 v44, v37
	v_mov_b32_e32 v42, v69
	v_add_f32_e32 v36, 1.0, v36
	v_rcp_f32_e32 v45, v36
	s_nop 0
	v_pk_mul_f32 v[36:37], v[44:45], v[42:43]
	s_nop 0
	v_mul_f32_e32 v36, v36, v37
	v_lshlrev_b32_e32 v37, 16, v79
	v_cvt_pk_bf16_f32 v42, v2, v36
	v_mul_f32_e32 v2, 0xbfb8aa3b, v37
	v_exp_f32_e32 v2, v2
	v_mov_b32_e32 v44, v38
	v_mov_b32_e32 v36, v70
	v_add_f32_e32 v2, 1.0, v2
	v_rcp_f32_e32 v45, v2
	s_nop 0
	v_pk_mul_f32 v[36:37], v[44:45], v[36:37]
	s_nop 0
	v_mul_f32_e32 v2, v36, v37
	v_and_b32_e32 v37, 0xffff0000, v79
	v_mul_f32_e32 v36, 0xbfb8aa3b, v37
	v_exp_f32_e32 v36, v36
	v_mov_b32_e32 v44, v39
	v_add_f32_e32 v36, 1.0, v36
	v_rcp_f32_e32 v45, v36
	v_mov_b32_e32 v36, v71
	v_pk_mul_f32 v[36:37], v[44:45], v[36:37]
	s_nop 0
	v_mul_f32_e32 v36, v36, v37
	v_cvt_pk_bf16_f32 v43, v2, v36
	flat_store_dwordx4 v[126:127], v[40:43] offset:256
	v_lshl_add_u64 v[36:37], v[94:95], 0, v[130:131]
	flat_load_dwordx4 v[48:51], v[36:37]
	v_lshl_add_u64 v[36:37], v[94:95], 0, v[132:133]
	flat_load_dwordx4 v[44:47], v[36:37]
	v_lshl_add_u64 v[36:37], v[94:95], 0, v[134:135]
	flat_load_dwordx4 v[40:43], v[36:37]
	v_lshl_add_u64 v[36:37], v[94:95], 0, v[138:139]
	flat_load_dwordx4 v[36:39], v[36:37]
	s_waitcnt vmcnt(0) lgkmcnt(0)
; __device__ __forceinline__ float bflo(unsigned v) { return __uint_as_float(v << 16); }
; __device__ __forceinline__ float bfhi(unsigned v) { return __uint_as_float(v & 0xffff0000u); }
; __device__ __forceinline__ float siluf_(float x) { return x * __builtin_amdgcn_rcpf(1.0f + __expf(-x)); }
;   __device__ __forceinline__ void operator()(EPI_ARGS) const {
;     ...
;         for (int m = 0; m < 4; ++m) {
;           const size_t row = row0 + ai * HALF + m * 16;
;           const f32x4 v0 = acc[ai][bj][m][0], v1 = acc[ai][bj][m][1];
;           u32x4 o;
;           o.x = pack2(v0[0] * s0[0] * siluf_(bflo(z[m].x)), v0[1] * s0[1] * siluf_(bfhi(z[m].x)));
;           o.y = pack2(v0[2] * s0[2] * siluf_(bflo(z[m].y)), v0[3] * s0[3] * siluf_(bfhi(z[m].y)));
;           o.z = pack2(v1[0] * s1[0] * siluf_(bflo(z[m].z)), v1[1] * s1[1] * siluf_(bfhi(z[m].z)));
;           o.w = pack2(v1[2] * s1[2] * siluf_(bflo(z[m].w)), v1[3] * s1[3] * siluf_(bfhi(z[m].w)));
;           *(u32x4*)(y0 + row * DM + c) = o;
;         }
	v_lshlrev_b32_e32 v53, 16, v48
	v_mul_f32_e32 v2, 0xbfb8aa3b, v53
	v_exp_f32_e32 v2, v2
	v_mov_b32_e32 v54, v32
	v_mov_b32_e32 v52, v72
	s_and_b64 vcc, exec, s[18:19]
	v_add_f32_e32 v2, 1.0, v2
	v_rcp_f32_e32 v55, v2
	s_mov_b32 s33, s16
	s_mov_b32 s2, s14
	s_mov_b64 s[4:5], s[22:23]
	v_pk_mul_f32 v[52:53], v[54:55], v[52:53]
	v_mov_b32_e32 v54, v33
	v_mul_f32_e32 v2, v52, v53
	v_and_b32_e32 v53, 0xffff0000, v48
	v_mul_f32_e32 v32, 0xbfb8aa3b, v53
	v_exp_f32_e32 v32, v32
	v_mov_b32_e32 v52, v73
	v_mov_b32_e32 v48, v75
	s_mov_b64 s[6:7], s[20:21]
	v_add_f32_e32 v32, 1.0, v32
	v_rcp_f32_e32 v55, v32
	s_nop 0
	v_pk_mul_f32 v[32:33], v[54:55], v[52:53]
	s_nop 0
	v_mul_f32_e32 v32, v32, v33
	v_lshlrev_b32_e32 v53, 16, v49
	v_cvt_pk_bf16_f32 v32, v2, v32
	v_mul_f32_e32 v2, 0xbfb8aa3b, v53
	v_exp_f32_e32 v2, v2
	v_and_b32_e32 v49, 0xffff0000, v49
	v_mul_f32_e32 v33, 0xbfb8aa3b, v49
	v_exp_f32_e32 v33, v33
	v_add_f32_e32 v2, 1.0, v2
	v_rcp_f32_e32 v55, v2
	v_mov_b32_e32 v54, v34
	v_mov_b32_e32 v52, v74
	v_add_f32_e32 v33, 1.0, v33
	v_pk_mul_f32 v[52:53], v[54:55], v[52:53]
	s_nop 0
	v_mul_f32_e32 v2, v52, v53
	v_rcp_f32_e32 v53, v33
	v_mov_b32_e32 v52, v35
	v_pk_mul_f32 v[34:35], v[52:53], v[48:49]
	s_nop 0
	v_mul_f32_e32 v33, v34, v35
	v_lshlrev_b32_e32 v35, 16, v50
	v_cvt_pk_bf16_f32 v33, v2, v33
	v_mul_f32_e32 v2, 0xbfb8aa3b, v35
	v_exp_f32_e32 v2, v2
	v_mov_b32_e32 v48, v28
	v_mov_b32_e32 v34, v68
	v_add_f32_e32 v2, 1.0, v2
	v_rcp_f32_e32 v49, v2
	s_nop 0
	v_pk_mul_f32 v[34:35], v[48:49], v[34:35]
	s_nop 0
	v_mul_f32_e32 v2, v34, v35
	v_and_b32_e32 v35, 0xffff0000, v50
	v_mul_f32_e32 v28, 0xbfb8aa3b, v35
	v_exp_f32_e32 v28, v28
	v_mov_b32_e32 v48, v29
	v_mov_b32_e32 v34, v69
	v_add_f32_e32 v28, 1.0, v28
	v_rcp_f32_e32 v49, v28
	s_nop 0
	v_pk_mul_f32 v[28:29], v[48:49], v[34:35]
	s_nop 0
	v_mul_f32_e32 v28, v28, v29
	v_lshlrev_b32_e32 v29, 16, v51
	v_cvt_pk_bf16_f32 v34, v2, v28
	v_mul_f32_e32 v2, 0xbfb8aa3b, v29
	v_exp_f32_e32 v2, v2
	v_mov_b32_e32 v48, v30
	v_mov_b32_e32 v28, v70
	v_mov_b32_e32 v30, v24
	v_add_f32_e32 v2, 1.0, v2
	v_rcp_f32_e32 v49, v2
	s_nop 0
	v_pk_mul_f32 v[28:29], v[48:49], v[28:29]
	s_nop 0
	v_mul_f32_e32 v2, v28, v29
	v_and_b32_e32 v29, 0xffff0000, v51
	v_mul_f32_e32 v28, 0xbfb8aa3b, v29
	v_exp_f32_e32 v28, v28
	v_mov_b32_e32 v48, v31
	v_add_f32_e32 v28, 1.0, v28
	v_rcp_f32_e32 v49, v28
	v_mov_b32_e32 v28, v71
	v_pk_mul_f32 v[28:29], v[48:49], v[28:29]
	s_nop 0
	v_mul_f32_e32 v28, v28, v29
	v_lshlrev_b32_e32 v29, 16, v44
	v_cvt_pk_bf16_f32 v35, v2, v28
	v_mul_f32_e32 v2, 0xbfb8aa3b, v29
	v_exp_f32_e32 v2, v2
	v_mov_b32_e32 v28, v72
	flat_store_dwordx4 v[96:97], v[32:35] offset:256
	v_add_f32_e32 v2, 1.0, v2
	v_rcp_f32_e32 v31, v2
	s_nop 0
	v_pk_mul_f32 v[28:29], v[30:31], v[28:29]
	s_nop 0
	v_mul_f32_e32 v2, v28, v29
	v_and_b32_e32 v29, 0xffff0000, v44
	v_mul_f32_e32 v24, 0xbfb8aa3b, v29
	v_exp_f32_e32 v24, v24
	v_mov_b32_e32 v30, v25
	v_mov_b32_e32 v28, v73
	v_add_f32_e32 v24, 1.0, v24
	v_rcp_f32_e32 v31, v24
	s_nop 0
	v_pk_mul_f32 v[24:25], v[30:31], v[28:29]
	s_nop 0
	v_mul_f32_e32 v24, v24, v25
	v_lshlrev_b32_e32 v29, 16, v45
	v_cvt_pk_bf16_f32 v24, v2, v24
	v_mul_f32_e32 v2, 0xbfb8aa3b, v29
	v_exp_f32_e32 v2, v2
	v_mov_b32_e32 v30, v26
	v_mov_b32_e32 v28, v74
	v_add_f32_e32 v2, 1.0, v2
	v_rcp_f32_e32 v31, v2
	s_nop 0
	v_pk_mul_f32 v[28:29], v[30:31], v[28:29]
	s_nop 0
	v_mul_f32_e32 v2, v28, v29
	v_and_b32_e32 v29, 0xffff0000, v45
	v_mul_f32_e32 v25, 0xbfb8aa3b, v29
	v_exp_f32_e32 v25, v25
	v_mov_b32_e32 v30, v27
	v_mov_b32_e32 v28, v75
	v_add_f32_e32 v25, 1.0, v25
	v_rcp_f32_e32 v31, v25
	s_nop 0
	v_pk_mul_f32 v[26:27], v[30:31], v[28:29]
	s_nop 0
	v_mul_f32_e32 v25, v26, v27
	v_lshlrev_b32_e32 v27, 16, v46
	v_cvt_pk_bf16_f32 v25, v2, v25
	v_mul_f32_e32 v2, 0xbfb8aa3b, v27
	v_exp_f32_e32 v2, v2
	v_mov_b32_e32 v28, v20
	v_mov_b32_e32 v26, v68
	v_add_f32_e32 v2, 1.0, v2
	v_rcp_f32_e32 v29, v2
	s_nop 0
	v_pk_mul_f32 v[26:27], v[28:29], v[26:27]
	s_nop 0
	v_mul_f32_e32 v2, v26, v27
	v_and_b32_e32 v27, 0xffff0000, v46
	v_mul_f32_e32 v20, 0xbfb8aa3b, v27
	v_exp_f32_e32 v20, v20
	v_mov_b32_e32 v28, v21
	v_mov_b32_e32 v26, v69
	v_add_f32_e32 v20, 1.0, v20
	v_rcp_f32_e32 v29, v20
	s_nop 0
	v_pk_mul_f32 v[20:21], v[28:29], v[26:27]
	s_nop 0
	v_mul_f32_e32 v20, v20, v21
	v_lshlrev_b32_e32 v21, 16, v47
	v_cvt_pk_bf16_f32 v26, v2, v20
	v_mul_f32_e32 v2, 0xbfb8aa3b, v21
	v_exp_f32_e32 v2, v2
	v_mov_b32_e32 v28, v22
	v_mov_b32_e32 v20, v70
	v_mov_b32_e32 v22, v16
	v_add_f32_e32 v2, 1.0, v2
	v_rcp_f32_e32 v29, v2
	s_nop 0
	v_pk_mul_f32 v[20:21], v[28:29], v[20:21]
	s_nop 0
	v_mul_f32_e32 v2, v20, v21
	v_and_b32_e32 v21, 0xffff0000, v47
	v_mul_f32_e32 v20, 0xbfb8aa3b, v21
	v_exp_f32_e32 v20, v20
	v_mov_b32_e32 v28, v23
	v_add_f32_e32 v20, 1.0, v20
	v_rcp_f32_e32 v29, v20
	v_mov_b32_e32 v20, v71
	v_pk_mul_f32 v[20:21], v[28:29], v[20:21]
	s_nop 0
	v_mul_f32_e32 v20, v20, v21
	v_lshlrev_b32_e32 v21, 16, v40
	v_cvt_pk_bf16_f32 v27, v2, v20
	v_mul_f32_e32 v2, 0xbfb8aa3b, v21
	v_exp_f32_e32 v2, v2
	v_mov_b32_e32 v20, v72
	flat_store_dwordx4 v[98:99], v[24:27] offset:256
; __device__ __forceinline__ float bflo(unsigned v) { return __uint_as_float(v << 16); }
; __device__ __forceinline__ float bfhi(unsigned v) { return __uint_as_float(v & 0xffff0000u); }
; __device__ __forceinline__ float siluf_(float x) { return x * __builtin_amdgcn_rcpf(1.0f + __expf(-x)); }
; #define PG8_WAIT_V(n) asm volatile("s_waitcnt vmcnt(" #n ")" ::: "memory")
; #define PG8_BAR __builtin_amdgcn_s_barrier()
; template <class Epi, class AddrA, class AddrB>
; __device__ __forceinline__ void gemm_phase(const Sched S, const int lda, const int ldb, const int K, const AddrA addrA,
;                                            const AddrB addrB, const Epi E) {
;     ...
;     cur = nxt; cA = nA; cB = nB; ++ui;
;   }
;   PG8_WAIT_V(0);
;   if (wr == 0) PG8_BAR;
;   PG8_BAR;
;   __device__ __forceinline__ void operator()(EPI_ARGS) const {
;     ...
;         for (int m = 0; m < 4; ++m) {
;           const size_t row = row0 + ai * HALF + m * 16;
;           const f32x4 v0 = acc[ai][bj][m][0], v1 = acc[ai][bj][m][1];
;           u32x4 o;
;           o.x = pack2(v0[0] * s0[0] * siluf_(bflo(z[m].x)), v0[1] * s0[1] * siluf_(bfhi(z[m].x)));
;           o.y = pack2(v0[2] * s0[2] * siluf_(bflo(z[m].y)), v0[3] * s0[3] * siluf_(bfhi(z[m].y)));
;           o.z = pack2(v1[0] * s1[0] * siluf_(bflo(z[m].z)), v1[1] * s1[1] * siluf_(bfhi(z[m].z)));
;           o.w = pack2(v1[2] * s1[2] * siluf_(bflo(z[m].w)), v1[3] * s1[3] * siluf_(bfhi(z[m].w)));
;           *(u32x4*)(y0 + row * DM + c) = o;
;         }
	v_add_f32_e32 v2, 1.0, v2
	v_rcp_f32_e32 v23, v2
	s_nop 0
	v_pk_mul_f32 v[20:21], v[22:23], v[20:21]
	s_nop 0
	v_mul_f32_e32 v2, v20, v21
	v_and_b32_e32 v21, 0xffff0000, v40
	v_mul_f32_e32 v16, 0xbfb8aa3b, v21
	v_exp_f32_e32 v16, v16
	v_mov_b32_e32 v22, v17
	v_mov_b32_e32 v20, v73
	v_add_f32_e32 v16, 1.0, v16
	v_rcp_f32_e32 v23, v16
	s_nop 0
	v_pk_mul_f32 v[16:17], v[22:23], v[20:21]
	s_nop 0
	v_mul_f32_e32 v16, v16, v17
	v_lshlrev_b32_e32 v21, 16, v41
	v_cvt_pk_bf16_f32 v16, v2, v16
	v_mul_f32_e32 v2, 0xbfb8aa3b, v21
	v_exp_f32_e32 v2, v2
	v_mov_b32_e32 v22, v18
	v_mov_b32_e32 v20, v74
	v_add_f32_e32 v2, 1.0, v2
	v_rcp_f32_e32 v23, v2
	s_nop 0
	v_pk_mul_f32 v[20:21], v[22:23], v[20:21]
	s_nop 0
	v_mul_f32_e32 v2, v20, v21
	v_and_b32_e32 v21, 0xffff0000, v41
	v_mul_f32_e32 v17, 0xbfb8aa3b, v21
	v_exp_f32_e32 v17, v17
	v_mov_b32_e32 v22, v19
	v_mov_b32_e32 v20, v75
	v_add_f32_e32 v17, 1.0, v17
	v_rcp_f32_e32 v23, v17
	s_nop 0
	v_pk_mul_f32 v[18:19], v[22:23], v[20:21]
	s_nop 0
	v_mul_f32_e32 v17, v18, v19
	v_lshlrev_b32_e32 v19, 16, v42
	v_cvt_pk_bf16_f32 v17, v2, v17
	v_mul_f32_e32 v2, 0xbfb8aa3b, v19
	v_exp_f32_e32 v2, v2
	v_mov_b32_e32 v20, v12
	v_mov_b32_e32 v18, v68
	v_add_f32_e32 v2, 1.0, v2
	v_rcp_f32_e32 v21, v2
	s_nop 0
	v_pk_mul_f32 v[18:19], v[20:21], v[18:19]
	s_nop 0
	v_mul_f32_e32 v2, v18, v19
	v_and_b32_e32 v19, 0xffff0000, v42
	v_mul_f32_e32 v12, 0xbfb8aa3b, v19
	v_exp_f32_e32 v12, v12
	v_mov_b32_e32 v20, v13
	v_mov_b32_e32 v18, v69
	v_add_f32_e32 v12, 1.0, v12
	v_rcp_f32_e32 v21, v12
	s_nop 0
	v_pk_mul_f32 v[12:13], v[20:21], v[18:19]
	s_nop 0
	v_mul_f32_e32 v12, v12, v13
	v_lshlrev_b32_e32 v13, 16, v43
	v_cvt_pk_bf16_f32 v18, v2, v12
	v_mul_f32_e32 v2, 0xbfb8aa3b, v13
	v_exp_f32_e32 v2, v2
	v_mov_b32_e32 v20, v14
	v_mov_b32_e32 v12, v70
	v_mov_b32_e32 v14, v8
	v_add_f32_e32 v2, 1.0, v2
	v_rcp_f32_e32 v21, v2
	s_nop 0
	v_pk_mul_f32 v[12:13], v[20:21], v[12:13]
	s_nop 0
	v_mul_f32_e32 v2, v12, v13
	v_and_b32_e32 v13, 0xffff0000, v43
	v_mul_f32_e32 v12, 0xbfb8aa3b, v13
	v_exp_f32_e32 v12, v12
	v_mov_b32_e32 v20, v15
	v_add_f32_e32 v12, 1.0, v12
	v_rcp_f32_e32 v21, v12
	v_mov_b32_e32 v12, v71
	v_pk_mul_f32 v[12:13], v[20:21], v[12:13]
	s_nop 0
	v_mul_f32_e32 v12, v12, v13
	v_lshlrev_b32_e32 v13, 16, v36
	v_cvt_pk_bf16_f32 v19, v2, v12
	v_mul_f32_e32 v2, 0xbfb8aa3b, v13
	v_exp_f32_e32 v2, v2
	v_mov_b32_e32 v12, v72
	flat_store_dwordx4 v[104:105], v[16:19] offset:256
	v_add_f32_e32 v2, 1.0, v2
	v_rcp_f32_e32 v15, v2
	s_nop 0
	v_pk_mul_f32 v[12:13], v[14:15], v[12:13]
	s_nop 0
	v_mul_f32_e32 v2, v12, v13
	v_and_b32_e32 v13, 0xffff0000, v36
	v_mul_f32_e32 v8, 0xbfb8aa3b, v13
	v_exp_f32_e32 v8, v8
	v_mov_b32_e32 v14, v9
	v_mov_b32_e32 v12, v73
	v_add_f32_e32 v8, 1.0, v8
	v_rcp_f32_e32 v15, v8
	s_nop 0
	v_pk_mul_f32 v[8:9], v[14:15], v[12:13]
	s_nop 0
	v_mul_f32_e32 v8, v8, v9
	v_lshlrev_b32_e32 v13, 16, v37
	v_cvt_pk_bf16_f32 v8, v2, v8
	v_mul_f32_e32 v2, 0xbfb8aa3b, v13
	v_exp_f32_e32 v2, v2
	v_mov_b32_e32 v14, v10
	v_mov_b32_e32 v12, v74
	v_add_f32_e32 v2, 1.0, v2
	v_rcp_f32_e32 v15, v2
	s_nop 0
	v_pk_mul_f32 v[12:13], v[14:15], v[12:13]
	s_nop 0
	v_mul_f32_e32 v2, v12, v13
	v_and_b32_e32 v13, 0xffff0000, v37
	v_mul_f32_e32 v9, 0xbfb8aa3b, v13
	v_exp_f32_e32 v9, v9
	v_mov_b32_e32 v14, v11
	v_mov_b32_e32 v12, v75
	v_add_f32_e32 v9, 1.0, v9
	v_rcp_f32_e32 v15, v9
	s_nop 0
	v_pk_mul_f32 v[10:11], v[14:15], v[12:13]
	s_nop 0
	v_mul_f32_e32 v9, v10, v11
	v_lshlrev_b32_e32 v11, 16, v38
	v_cvt_pk_bf16_f32 v9, v2, v9
	v_mul_f32_e32 v2, 0xbfb8aa3b, v11
	v_exp_f32_e32 v2, v2
	v_mov_b32_e32 v12, v4
	v_mov_b32_e32 v10, v68
	v_add_f32_e32 v2, 1.0, v2
	v_rcp_f32_e32 v13, v2
	s_nop 0
	v_pk_mul_f32 v[10:11], v[12:13], v[10:11]
	s_nop 0
	v_mul_f32_e32 v2, v10, v11
	v_and_b32_e32 v11, 0xffff0000, v38
	v_mul_f32_e32 v4, 0xbfb8aa3b, v11
	v_exp_f32_e32 v4, v4
	v_mov_b32_e32 v12, v5
	v_mov_b32_e32 v10, v69
	v_add_f32_e32 v4, 1.0, v4
	v_rcp_f32_e32 v13, v4
	s_nop 0
	v_pk_mul_f32 v[4:5], v[12:13], v[10:11]
	s_nop 0
	v_mul_f32_e32 v4, v4, v5
	v_lshlrev_b32_e32 v5, 16, v39
	v_cvt_pk_bf16_f32 v10, v2, v4
	v_mul_f32_e32 v2, 0xbfb8aa3b, v5
	v_exp_f32_e32 v2, v2
	v_mov_b32_e32 v12, v6
	v_mov_b32_e32 v4, v70
	v_add_f32_e32 v2, 1.0, v2
	v_rcp_f32_e32 v13, v2
	s_nop 0
	v_pk_mul_f32 v[4:5], v[12:13], v[4:5]
	s_nop 0
	v_mul_f32_e32 v2, v4, v5
	v_and_b32_e32 v5, 0xffff0000, v39
	v_mul_f32_e32 v4, 0xbfb8aa3b, v5
	v_exp_f32_e32 v4, v4
	v_mov_b32_e32 v12, v7
	v_add_f32_e32 v4, 1.0, v4
	v_rcp_f32_e32 v13, v4
	v_mov_b32_e32 v4, v71
	v_pk_mul_f32 v[4:5], v[12:13], v[4:5]
	s_nop 0
	v_mul_f32_e32 v4, v4, v5
	v_cvt_pk_bf16_f32 v11, v2, v4
	flat_store_dwordx4 v[92:93], v[8:11] offset:256
	s_cbranch_vccz .LBB0_482
	s_waitcnt vmcnt(0)
	v_readlane_b32 s44, v244, 59
	v_readlane_b32 s40, v243, 18
	s_cmpk_gt_u32 s24, 0xff
	s_mov_b32 s43, 0x800000
	v_readlane_b32 s45, v244, 60
	v_readlane_b32 s46, v244, 61
	v_readlane_b32 s47, v244, 62
	v_readlane_b32 s48, v244, 63
	v_readlane_b32 s49, v243, 0
	v_readlane_b32 s50, v243, 1
	v_readlane_b32 s51, v243, 2
	v_readlane_b32 s41, v243, 19
	s_cbranch_scc1 .LBB0_489
	s_barrier

; #define PG8_WAIT_V(n) asm volatile("s_waitcnt vmcnt(" #n ")" ::: "memory")
; #define PG8_WAIT_L(n) asm volatile("s_waitcnt lgkmcnt(" #n ")" ::: "memory")
; #define PG8_BAR __builtin_amdgcn_s_barrier()
; #define PG8_SCHED __builtin_amdgcn_sched_barrier(0)
; template <class Epi, class AddrA, class AddrB>
; __device__ __forceinline__ void gemm_phase(const Sched S, const int lda, const int ldb, const int K, const AddrA addrA,
;                                            const AddrB addrB, const Epi E) {
;     ...
;     for (int t = 0; t < nt; t += 2) {
;       const bool last = (t == nt - 2);
;       const char* a1 = cA + (size_t)(t + 1) * kstep;
;       const char* a2 = last ? nA : cA + (size_t)(t + 2) * kstep;
;       const char* b2 = last ? nB : cB + (size_t)(t + 2) * kstep;
;       const char* a3 = a2 + kstep;
;       const char* b3 = b2 + kstep;
;       PG8_LDB(B0, 0, 0); PG8_SCHED; PG8_LDA(At, 0, 0); PG8_STAGE(PG8_SA(1, 1), a1 + hstepA, voffA);
;       PG8_WAIT_L(8); PG8_BAR; PG8_WAIT_L(0); PG8_MMA(0, 0, At, B0); PG8_BAR; PG8_SCHED;
;       PG8_LDB(B1, 0, 1); PG8_STAGE(PG8_SB(0, 0), b2, voffB);
;       PG8_BAR; PG8_WAIT_L(0); PG8_MMA(0, 1, At, B1); PG8_BAR;
;       PG8_LDA(At, 0, 1); PG8_STAGE(PG8_SA(0, 0), a2, voffA);
;       PG8_BAR; PG8_WAIT_L(0); PG8_MMA(1, 0, At, B0); PG8_BAR; PG8_SCHED;
;       PG8_STAGE(PG8_SB(0, 1), b2 + hstepB, voffB);
;       PG8_WAIT_V(6); PG8_BAR; PG8_MMA(1, 1, At, B1); PG8_BAR;
;       PG8_LDB(B0, 1, 0); PG8_SCHED; PG8_LDA(At, 1, 0); PG8_STAGE(PG8_SA(0, 1), a2 + hstepA, voffA);
;       PG8_WAIT_L(8); PG8_BAR; PG8_WAIT_L(0); PG8_MMA(0, 0, At, B0); PG8_BAR; PG8_SCHED;
;       PG8_LDB(B1, 1, 1); PG8_STAGE(PG8_SB(1, 0), b3, voffB);
;       PG8_BAR; PG8_WAIT_L(0); PG8_MMA(0, 1, At, B1); PG8_BAR;
;       PG8_LDA(At, 1, 1); PG8_STAGE(PG8_SA(1, 0), a3, voffA);
;       PG8_BAR; PG8_WAIT_L(0); PG8_MMA(1, 0, At, B0); PG8_BAR; PG8_SCHED;
;       PG8_STAGE(PG8_SB(1, 1), b3 + hstepB, voffB);
;       PG8_WAIT_V(6); PG8_BAR; PG8_MMA(1, 1, At, B1); PG8_BAR;
.LBB0_543:
	s_add_i32 s43, 0, 0x10000
	v_add_u32_e32 v0, s43, v167
	ds_read_b128 v[132:135], v0
	ds_read_b128 v[136:139], v0 offset:1024
	ds_read_b128 v[140:143], v0 offset:2048
	ds_read_b128 v[144:147], v0 offset:3072
	v_lshl_add_u64 v[0:1], s[2:3], 0, v[180:181]
	s_add_i32 m0, s28, 0xc000
	ds_read_b128 v[148:151], v188
	ds_read_b128 v[152:155], v188 offset:1024
	ds_read_b128 v[156:159], v188 offset:2048
	ds_read_b128 v[160:163], v188 offset:3072
	ds_read_b128 v[182:185], v188 offset:4096
	ds_read_b128 v[190:193], v188 offset:5120
	ds_read_b128 v[194:197], v188 offset:6144
	ds_read_b128 v[212:215], v188 offset:7168
	global_load_lds_dwordx4 v[0:1], off
	v_lshl_add_u64 v[0:1], s[2:3], 0, v[178:179]
	s_add_i32 m0, s28, 0xe000
	s_nop 0
	global_load_lds_dwordx4 v[0:1], off
	s_waitcnt lgkmcnt(8)
	s_setprio 1
	s_barrier
	s_waitcnt lgkmcnt(0)
	v_mfma_f32_16x16x32_bf16 v[128:131], v[132:135], v[148:151], v[128:131]
	v_mfma_f32_16x16x32_bf16 v[128:131], v[136:139], v[152:155], v[128:131]
	v_mfma_f32_16x16x32_bf16 v[120:123], v[132:135], v[156:159], v[120:123]
	v_mfma_f32_16x16x32_bf16 v[120:123], v[136:139], v[160:163], v[120:123]
	v_mfma_f32_16x16x32_bf16 v[112:115], v[132:135], v[182:185], v[112:115]
	v_mfma_f32_16x16x32_bf16 v[112:115], v[136:139], v[190:193], v[112:115]
	v_mfma_f32_16x16x32_bf16 v[104:107], v[132:135], v[194:197], v[104:107]
	v_mfma_f32_16x16x32_bf16 v[104:107], v[136:139], v[212:215], v[104:107]
	v_mfma_f32_16x16x32_bf16 v[124:127], v[140:143], v[148:151], v[124:127]
	v_mfma_f32_16x16x32_bf16 v[124:127], v[144:147], v[152:155], v[124:127]
	v_mfma_f32_16x16x32_bf16 v[116:119], v[140:143], v[156:159], v[116:119]
	v_mfma_f32_16x16x32_bf16 v[116:119], v[144:147], v[160:163], v[116:119]
	v_mfma_f32_16x16x32_bf16 v[108:111], v[140:143], v[182:185], v[108:111]
	v_mfma_f32_16x16x32_bf16 v[108:111], v[144:147], v[190:193], v[108:111]
	v_mfma_f32_16x16x32_bf16 v[100:103], v[140:143], v[194:197], v[100:103]
	v_mfma_f32_16x16x32_bf16 v[100:103], v[144:147], v[212:215], v[100:103]
	s_barrier
	s_setprio 0
	s_add_u32 s4, s2, 0xfff80080
	s_addc_u32 s5, s3, -1
	s_cmp_eq_u32 s42, 28
	s_cselect_b32 s7, s1, s5
	s_cselect_b32 s6, s9, s4
	s_cselect_b32 s5, s13, s41
	s_cselect_b32 s4, s15, s33
	s_add_i32 s46, 0, 0x14000
	v_add_u32_e32 v0, s46, v167
	s_add_i32 s43, s43, s27
	ds_read_b128 v[216:219], v0
	ds_read_b128 v[220:223], v0 offset:1024
	ds_read_b128 v[224:227], v0 offset:2048
	ds_read_b128 v[228:231], v0 offset:3072
	v_lshl_add_u64 v[0:1], s[4:5], 0, v[172:173]
	s_mov_b32 m0, s43
	v_lshl_add_u64 v[232:233], s[4:5], 0, v[168:169]
	global_load_lds_dwordx4 v[0:1], off
	s_add_i32 m0, s43, 0x2000
	s_nop 0
	global_load_lds_dwordx4 v[232:233], off
	s_mov_b32 m0, s28
	v_lshl_add_u64 v[234:235], s[6:7], 0, v[174:175]
	s_setprio 1
	s_barrier
	s_waitcnt lgkmcnt(0)
	v_mfma_f32_16x16x32_bf16 v[96:99], v[216:219], v[148:151], v[96:99]
	v_mfma_f32_16x16x32_bf16 v[96:99], v[220:223], v[152:155], v[96:99]
	v_mfma_f32_16x16x32_bf16 v[88:91], v[216:219], v[156:159], v[88:91]
	v_mfma_f32_16x16x32_bf16 v[88:91], v[220:223], v[160:163], v[88:91]
	v_mfma_f32_16x16x32_bf16 v[80:83], v[216:219], v[182:185], v[80:83]
	v_mfma_f32_16x16x32_bf16 v[80:83], v[220:223], v[190:193], v[80:83]
	v_mfma_f32_16x16x32_bf16 v[72:75], v[216:219], v[194:197], v[72:75]
	v_mfma_f32_16x16x32_bf16 v[72:75], v[220:223], v[212:215], v[72:75]
	v_mfma_f32_16x16x32_bf16 v[92:95], v[224:227], v[148:151], v[92:95]
	v_mfma_f32_16x16x32_bf16 v[92:95], v[228:231], v[152:155], v[92:95]
	v_mfma_f32_16x16x32_bf16 v[84:87], v[224:227], v[156:159], v[84:87]
	v_mfma_f32_16x16x32_bf16 v[84:87], v[228:231], v[160:163], v[84:87]
	v_mfma_f32_16x16x32_bf16 v[76:79], v[224:227], v[182:185], v[76:79]
	v_mfma_f32_16x16x32_bf16 v[76:79], v[228:231], v[190:193], v[76:79]
	v_mfma_f32_16x16x32_bf16 v[68:71], v[224:227], v[194:197], v[68:71]
	v_mfma_f32_16x16x32_bf16 v[68:71], v[228:231], v[212:215], v[68:71]
	s_barrier
	s_setprio 0
	ds_read_b128 v[148:151], v188 offset:16384
	ds_read_b128 v[152:155], v188 offset:17408
	ds_read_b128 v[156:159], v188 offset:18432
	ds_read_b128 v[160:163], v188 offset:19456
	ds_read_b128 v[182:185], v188 offset:20480
	ds_read_b128 v[190:193], v188 offset:21504
	ds_read_b128 v[194:197], v188 offset:22528
	ds_read_b128 v[212:215], v188 offset:23552
	global_load_lds_dwordx4 v[234:235], off
	v_lshl_add_u64 v[236:237], s[6:7], 0, v[170:171]
	s_mov_b32 m0, s29
	s_nop 0
	global_load_lds_dwordx4 v[236:237], off
	s_setprio 1
	s_barrier
	s_waitcnt lgkmcnt(0)
	v_mfma_f32_16x16x32_bf16 v[64:67], v[132:135], v[148:151], v[64:67]
	v_mfma_f32_16x16x32_bf16 v[64:67], v[136:139], v[152:155], v[64:67]
	v_mfma_f32_16x16x32_bf16 v[56:59], v[132:135], v[156:159], v[56:59]
	v_mfma_f32_16x16x32_bf16 v[56:59], v[136:139], v[160:163], v[56:59]
	v_mfma_f32_16x16x32_bf16 v[48:51], v[132:135], v[182:185], v[48:51]
	v_mfma_f32_16x16x32_bf16 v[48:51], v[136:139], v[190:193], v[48:51]
	v_mfma_f32_16x16x32_bf16 v[40:43], v[132:135], v[194:197], v[40:43]
	v_mfma_f32_16x16x32_bf16 v[40:43], v[136:139], v[212:215], v[40:43]
	v_mfma_f32_16x16x32_bf16 v[60:63], v[140:143], v[148:151], v[60:63]
	v_mfma_f32_16x16x32_bf16 v[60:63], v[144:147], v[152:155], v[60:63]
	v_mfma_f32_16x16x32_bf16 v[52:55], v[140:143], v[156:159], v[52:55]
	v_mfma_f32_16x16x32_bf16 v[52:55], v[144:147], v[160:163], v[52:55]
	v_mfma_f32_16x16x32_bf16 v[44:47], v[140:143], v[182:185], v[44:47]
	v_mfma_f32_16x16x32_bf16 v[44:47], v[144:147], v[190:193], v[44:47]
	v_mfma_f32_16x16x32_bf16 v[36:39], v[140:143], v[194:197], v[36:39]
	v_mfma_f32_16x16x32_bf16 v[36:39], v[144:147], v[212:215], v[36:39]
	s_barrier
; #define PG8_WAIT_V(n) asm volatile("s_waitcnt vmcnt(" #n ")" ::: "memory")
; #define PG8_WAIT_L(n) asm volatile("s_waitcnt lgkmcnt(" #n ")" ::: "memory")
; #define PG8_BAR __builtin_amdgcn_s_barrier()
; #define PG8_SCHED __builtin_amdgcn_sched_barrier(0)
; template <class Epi, class AddrA, class AddrB>
; __device__ __forceinline__ void gemm_phase(const Sched S, const int lda, const int ldb, const int K, const AddrA addrA,
;                                            const AddrB addrB, const Epi E) {
;     ...
;       PG8_LDB(B0, 0, 0); PG8_SCHED; PG8_LDA(At, 0, 0); PG8_STAGE(PG8_SA(1, 1), a1 + hstepA, voffA);
;       PG8_WAIT_L(8); PG8_BAR; PG8_WAIT_L(0); PG8_MMA(0, 0, At, B0); PG8_BAR; PG8_SCHED;
;       PG8_LDB(B1, 0, 1); PG8_STAGE(PG8_SB(0, 0), b2, voffB);
;       PG8_BAR; PG8_WAIT_L(0); PG8_MMA(0, 1, At, B1); PG8_BAR;
;       PG8_LDA(At, 0, 1); PG8_STAGE(PG8_SA(0, 0), a2, voffA);
;       PG8_BAR; PG8_WAIT_L(0); PG8_MMA(1, 0, At, B0); PG8_BAR; PG8_SCHED;
;       PG8_STAGE(PG8_SB(0, 1), b2 + hstepB, voffB);
;       PG8_WAIT_V(6); PG8_BAR; PG8_MMA(1, 1, At, B1); PG8_BAR;
;       PG8_LDB(B0, 1, 0); PG8_SCHED; PG8_LDA(At, 1, 0); PG8_STAGE(PG8_SA(0, 1), a2 + hstepA, voffA);
;       PG8_WAIT_L(8); PG8_BAR; PG8_WAIT_L(0); PG8_MMA(0, 0, At, B0); PG8_BAR; PG8_SCHED;
;       PG8_LDB(B1, 1, 1); PG8_STAGE(PG8_SB(1, 0), b3, voffB);
;       PG8_BAR; PG8_WAIT_L(0); PG8_MMA(0, 1, At, B1); PG8_BAR;
;       PG8_LDA(At, 1, 1); PG8_STAGE(PG8_SA(1, 0), a3, voffA);
;       PG8_BAR; PG8_WAIT_L(0); PG8_MMA(1, 0, At, B0); PG8_BAR; PG8_SCHED;
;       PG8_STAGE(PG8_SB(1, 1), b3 + hstepB, voffB);
;       PG8_WAIT_V(6); PG8_BAR; PG8_MMA(1, 1, At, B1); PG8_BAR;
	s_setprio 0
	s_add_u32 s44, s4, 0x80000
	s_addc_u32 s45, s5, 0
	s_add_i32 s43, s46, s27
	v_lshl_add_u64 v[132:133], s[44:45], 0, v[172:173]
	s_mov_b32 m0, s43
	s_nop 0
	global_load_lds_dwordx4 v[132:133], off
	v_lshl_add_u64 v[132:133], s[44:45], 0, v[168:169]
	s_add_i32 m0, s43, 0x2000
	s_nop 0
	global_load_lds_dwordx4 v[132:133], off
	s_add_i32 s43, 0, 0x18000
	v_add_u32_e32 v2, s43, v167
	s_waitcnt vmcnt(6)
	s_setprio 1
	s_barrier
	v_mfma_f32_16x16x32_bf16 v[32:35], v[216:219], v[148:151], v[32:35]
	v_mfma_f32_16x16x32_bf16 v[32:35], v[220:223], v[152:155], v[32:35]
	v_mfma_f32_16x16x32_bf16 v[24:27], v[216:219], v[156:159], v[24:27]
	v_mfma_f32_16x16x32_bf16 v[24:27], v[220:223], v[160:163], v[24:27]
	v_mfma_f32_16x16x32_bf16 v[16:19], v[216:219], v[182:185], v[16:19]
	v_mfma_f32_16x16x32_bf16 v[16:19], v[220:223], v[190:193], v[16:19]
	v_mfma_f32_16x16x32_bf16 v[8:11], v[216:219], v[194:197], v[8:11]
	v_mfma_f32_16x16x32_bf16 v[8:11], v[220:223], v[212:215], v[8:11]
	v_mfma_f32_16x16x32_bf16 v[28:31], v[224:227], v[148:151], v[28:31]
	v_mfma_f32_16x16x32_bf16 v[28:31], v[228:231], v[152:155], v[28:31]
	v_mfma_f32_16x16x32_bf16 v[20:23], v[224:227], v[156:159], v[20:23]
	v_mfma_f32_16x16x32_bf16 v[20:23], v[228:231], v[160:163], v[20:23]
	v_mfma_f32_16x16x32_bf16 v[12:15], v[224:227], v[182:185], v[12:15]
	v_mfma_f32_16x16x32_bf16 v[12:15], v[228:231], v[190:193], v[12:15]
	v_mfma_f32_16x16x32_bf16 v[4:7], v[224:227], v[194:197], v[4:7]
	v_mfma_f32_16x16x32_bf16 v[4:7], v[228:231], v[212:215], v[4:7]
	s_barrier
	s_setprio 0
	ds_read_b128 v[132:135], v2
	ds_read_b128 v[136:139], v2 offset:1024
	ds_read_b128 v[140:143], v2 offset:2048
	ds_read_b128 v[144:147], v2 offset:3072
	s_add_u32 s6, s6, 0x80000
	s_addc_u32 s7, s7, 0
	s_mov_b32 m0, s30
	v_lshl_add_u64 v[216:217], s[6:7], 0, v[174:175]
	ds_read_b128 v[148:151], v188 offset:32768
	ds_read_b128 v[152:155], v188 offset:33792
	ds_read_b128 v[156:159], v188 offset:34816
	ds_read_b128 v[160:163], v188 offset:35840
	ds_read_b128 v[182:185], v188 offset:36864
	ds_read_b128 v[190:193], v188 offset:37888
	ds_read_b128 v[194:197], v188 offset:38912
	ds_read_b128 v[212:215], v188 offset:39936
	global_load_lds_dwordx4 v[216:217], off
	v_lshl_add_u64 v[216:217], s[6:7], 0, v[170:171]
	s_mov_b32 m0, s31
	s_nop 0
	global_load_lds_dwordx4 v[216:217], off
	s_waitcnt lgkmcnt(8)
	s_setprio 1
	s_barrier
	s_waitcnt lgkmcnt(0)
	v_mfma_f32_16x16x32_bf16 v[128:131], v[132:135], v[148:151], v[128:131]
	v_mfma_f32_16x16x32_bf16 v[128:131], v[136:139], v[152:155], v[128:131]
	v_mfma_f32_16x16x32_bf16 v[120:123], v[132:135], v[156:159], v[120:123]
	v_mfma_f32_16x16x32_bf16 v[120:123], v[136:139], v[160:163], v[120:123]
	v_mfma_f32_16x16x32_bf16 v[112:115], v[132:135], v[182:185], v[112:115]
	v_mfma_f32_16x16x32_bf16 v[112:115], v[136:139], v[190:193], v[112:115]
	v_mfma_f32_16x16x32_bf16 v[104:107], v[132:135], v[194:197], v[104:107]
	v_mfma_f32_16x16x32_bf16 v[104:107], v[136:139], v[212:215], v[104:107]
	v_mfma_f32_16x16x32_bf16 v[124:127], v[140:143], v[148:151], v[124:127]
	v_mfma_f32_16x16x32_bf16 v[124:127], v[144:147], v[152:155], v[124:127]
	v_mfma_f32_16x16x32_bf16 v[116:119], v[140:143], v[156:159], v[116:119]
	v_mfma_f32_16x16x32_bf16 v[116:119], v[144:147], v[160:163], v[116:119]
	v_mfma_f32_16x16x32_bf16 v[108:111], v[140:143], v[182:185], v[108:111]
	v_mfma_f32_16x16x32_bf16 v[108:111], v[144:147], v[190:193], v[108:111]
	v_mfma_f32_16x16x32_bf16 v[100:103], v[140:143], v[194:197], v[100:103]
	v_mfma_f32_16x16x32_bf16 v[100:103], v[144:147], v[212:215], v[100:103]
	s_barrier
	s_setprio 0
	s_add_i32 s6, 0, 0x1c000
	s_add_i32 s7, s43, s27
	v_add_u32_e32 v2, s6, v167
	v_lshl_add_u64 v[0:1], v[0:1], 0, s[52:53]
	s_mov_b32 m0, s7
	ds_read_b128 v[216:219], v2
	ds_read_b128 v[220:223], v2 offset:1024
	ds_read_b128 v[224:227], v2 offset:2048
	ds_read_b128 v[228:231], v2 offset:3072
	global_load_lds_dwordx4 v[0:1], off
	v_lshl_add_u64 v[0:1], v[232:233], 0, s[52:53]
	s_add_i32 m0, s7, 0x2000
	s_nop 0
	global_load_lds_dwordx4 v[0:1], off
	s_mov_b32 m0, s38
	v_lshl_add_u64 v[0:1], v[234:235], 0, s[52:53]
	s_setprio 1
	s_barrier
	s_waitcnt lgkmcnt(0)
	v_mfma_f32_16x16x32_bf16 v[96:99], v[216:219], v[148:151], v[96:99]
	v_mfma_f32_16x16x32_bf16 v[96:99], v[220:223], v[152:155], v[96:99]
	v_mfma_f32_16x16x32_bf16 v[88:91], v[216:219], v[156:159], v[88:91]
	v_mfma_f32_16x16x32_bf16 v[88:91], v[220:223], v[160:163], v[88:91]
	v_mfma_f32_16x16x32_bf16 v[80:83], v[216:219], v[182:185], v[80:83]
	v_mfma_f32_16x16x32_bf16 v[80:83], v[220:223], v[190:193], v[80:83]
	v_mfma_f32_16x16x32_bf16 v[72:75], v[216:219], v[194:197], v[72:75]
	v_mfma_f32_16x16x32_bf16 v[72:75], v[220:223], v[212:215], v[72:75]
	v_mfma_f32_16x16x32_bf16 v[92:95], v[224:227], v[148:151], v[92:95]
	v_mfma_f32_16x16x32_bf16 v[92:95], v[228:231], v[152:155], v[92:95]
	v_mfma_f32_16x16x32_bf16 v[84:87], v[224:227], v[156:159], v[84:87]
	v_mfma_f32_16x16x32_bf16 v[84:87], v[228:231], v[160:163], v[84:87]
	v_mfma_f32_16x16x32_bf16 v[76:79], v[224:227], v[182:185], v[76:79]
	v_mfma_f32_16x16x32_bf16 v[76:79], v[228:231], v[190:193], v[76:79]
	v_mfma_f32_16x16x32_bf16 v[68:71], v[224:227], v[194:197], v[68:71]
	v_mfma_f32_16x16x32_bf16 v[68:71], v[228:231], v[212:215], v[68:71]
	s_barrier
	s_setprio 0
	ds_read_b128 v[148:151], v188 offset:49152
	ds_read_b128 v[152:155], v188 offset:50176
	ds_read_b128 v[156:159], v188 offset:51200
	ds_read_b128 v[160:163], v188 offset:52224
	ds_read_b128 v[182:185], v188 offset:53248
	ds_read_b128 v[190:193], v188 offset:54272
	ds_read_b128 v[194:197], v188 offset:55296
	ds_read_b128 v[212:215], v188 offset:56320
	global_load_lds_dwordx4 v[0:1], off
	v_lshl_add_u64 v[0:1], v[236:237], 0, s[52:53]
	s_mov_b32 m0, s39
	s_nop 0
	global_load_lds_dwordx4 v[0:1], off
	s_setprio 1
	s_barrier
; #define PG8_WAIT_V(n) asm volatile("s_waitcnt vmcnt(" #n ")" ::: "memory")
; #define PG8_WAIT_L(n) asm volatile("s_waitcnt lgkmcnt(" #n ")" ::: "memory")
; #define PG8_BAR __builtin_amdgcn_s_barrier()
; #define PG8_SCHED __builtin_amdgcn_sched_barrier(0)
; template <class Epi, class AddrA, class AddrB>
; __device__ __forceinline__ void gemm_phase(const Sched S, const int lda, const int ldb, const int K, const AddrA addrA,
;                                            const AddrB addrB, const Epi E) {
;     ...
;       PG8_BAR; PG8_WAIT_L(0); PG8_MMA(1, 0, At, B0); PG8_BAR; PG8_SCHED;
;       PG8_STAGE(PG8_SB(1, 1), b3 + hstepB, voffB);
;       PG8_WAIT_V(6); PG8_BAR; PG8_MMA(1, 1, At, B1); PG8_BAR;
;     }
;     E(acc, cur, wr, wc, fr, fq);
;   __device__ __forceinline__ void operator()(EPI_ARGS) const {
;     const int col0 = u.pn * 256 + wc * 32 + 8 * fq;
;     const int br = u.br, brn = br < 2 ? br + 1 : 2;
;     const unsigned loff0 = (unsigned)((wr * 64 + fr) * PLD + wc * 32 + 8 * fq);
;     const bf16_t* pc = proj + ((size_t)((GT + br * DM) / 256 + u.pn) * MTOK + (size_t)u.pm * 256) * PLD;
;     const bf16_t* pn_ = proj + ((size_t)((GT + brn * DM) / 256 + u.pn) * MTOK + (size_t)u.pm * 256) * PLD;
;     bf16_t* mrow = merged + ((size_t)u.pm * 256 + wr * 64 + fr) * DM + col0;
; #pragma unroll
;     for (int bj = 0; bj < 2; ++bj) {
;       const int c = col0 + bj * HALF;
;       float gc[8], gn[8];
;       {
;         const f32x4 a0 = *(const f32x4*)(bg + br * DM + c), a1 = *(const f32x4*)(bg + br * DM + c + 4);
;         const f32x4 b0 = *(const f32x4*)(bg + brn * DM + c), b1 = *(const f32x4*)(bg + brn * DM + c + 4);
; #pragma unroll
;         for (int k = 0; k < 4; ++k) { gc[k] = a0[k]; gc[4 + k] = a1[k]; gn[k] = b0[k]; gn[4 + k] = b1[k]; }
;       }
; #pragma unroll
;       for (int ai = 0; ai < 2; ++ai) {
;         unsigned loff = loff0;
;         asm volatile("" : "+v"(loff));
;         u32x4 zc[4], zn[4];
; #pragma unroll
;         for (int m = 0; m < 4; ++m) {
;           const unsigned o = loff + (unsigned)((ai * HALF + m * 16) * PLD + bj * HALF);
;           zc[m] = *(const u32x4*)(pc + o);
;           zn[m] = *(const u32x4*)(pn_ + o);
;         }
	s_waitcnt lgkmcnt(0)
	v_mfma_f32_16x16x32_bf16 v[64:67], v[132:135], v[148:151], v[64:67]
	v_mfma_f32_16x16x32_bf16 v[64:67], v[136:139], v[152:155], v[64:67]
	v_mfma_f32_16x16x32_bf16 v[56:59], v[132:135], v[156:159], v[56:59]
	v_mfma_f32_16x16x32_bf16 v[56:59], v[136:139], v[160:163], v[56:59]
	v_mfma_f32_16x16x32_bf16 v[48:51], v[132:135], v[182:185], v[48:51]
	v_mfma_f32_16x16x32_bf16 v[48:51], v[136:139], v[190:193], v[48:51]
	v_mfma_f32_16x16x32_bf16 v[40:43], v[132:135], v[194:197], v[40:43]
	v_mfma_f32_16x16x32_bf16 v[40:43], v[136:139], v[212:215], v[40:43]
	v_mfma_f32_16x16x32_bf16 v[60:63], v[140:143], v[148:151], v[60:63]
	v_mfma_f32_16x16x32_bf16 v[60:63], v[144:147], v[152:155], v[60:63]
	v_mfma_f32_16x16x32_bf16 v[52:55], v[140:143], v[156:159], v[52:55]
	v_mfma_f32_16x16x32_bf16 v[52:55], v[144:147], v[160:163], v[52:55]
	v_mfma_f32_16x16x32_bf16 v[44:47], v[140:143], v[182:185], v[44:47]
	v_mfma_f32_16x16x32_bf16 v[44:47], v[144:147], v[190:193], v[44:47]
	v_mfma_f32_16x16x32_bf16 v[36:39], v[140:143], v[194:197], v[36:39]
	v_mfma_f32_16x16x32_bf16 v[36:39], v[144:147], v[212:215], v[36:39]
	s_barrier
	s_setprio 0
	s_add_u32 s4, s4, 0x80080
	s_addc_u32 s5, s5, 0
	s_add_i32 s6, s6, s27
	v_lshl_add_u64 v[0:1], s[4:5], 0, v[172:173]
	s_mov_b32 m0, s6
	s_nop 0
	global_load_lds_dwordx4 v[0:1], off
	v_lshl_add_u64 v[0:1], s[4:5], 0, v[168:169]
	s_add_i32 m0, s6, 0x2000
	s_nop 0
	global_load_lds_dwordx4 v[0:1], off
	s_add_i32 s42, s42, 2
	s_add_u32 s33, s33, 0x100
	s_addc_u32 s41, s41, 0
	s_add_u32 s2, s2, 0x100
	s_addc_u32 s3, s3, 0
	s_waitcnt vmcnt(6)
	s_setprio 1
	s_barrier
	v_mfma_f32_16x16x32_bf16 v[32:35], v[216:219], v[148:151], v[32:35]
	v_mfma_f32_16x16x32_bf16 v[32:35], v[220:223], v[152:155], v[32:35]
	v_mfma_f32_16x16x32_bf16 v[24:27], v[216:219], v[156:159], v[24:27]
	v_mfma_f32_16x16x32_bf16 v[24:27], v[220:223], v[160:163], v[24:27]
	v_mfma_f32_16x16x32_bf16 v[16:19], v[216:219], v[182:185], v[16:19]
	v_mfma_f32_16x16x32_bf16 v[16:19], v[220:223], v[190:193], v[16:19]
	v_mfma_f32_16x16x32_bf16 v[8:11], v[216:219], v[194:197], v[8:11]
	v_mfma_f32_16x16x32_bf16 v[8:11], v[220:223], v[212:215], v[8:11]
	v_mfma_f32_16x16x32_bf16 v[28:31], v[224:227], v[148:151], v[28:31]
	v_mfma_f32_16x16x32_bf16 v[28:31], v[228:231], v[152:155], v[28:31]
	v_mfma_f32_16x16x32_bf16 v[20:23], v[224:227], v[156:159], v[20:23]
	v_mfma_f32_16x16x32_bf16 v[20:23], v[228:231], v[160:163], v[20:23]
	v_mfma_f32_16x16x32_bf16 v[12:15], v[224:227], v[182:185], v[12:15]
	v_mfma_f32_16x16x32_bf16 v[12:15], v[228:231], v[190:193], v[12:15]
	v_mfma_f32_16x16x32_bf16 v[4:7], v[224:227], v[194:197], v[4:7]
	v_mfma_f32_16x16x32_bf16 v[4:7], v[228:231], v[212:215], v[4:7]
	s_barrier
	s_setprio 0
	s_cmp_gt_u32 s42, 29
	s_cbranch_scc0 .LBB0_543
	s_cmp_gt_i32 s10, 1
	s_cselect_b64 s[6:7], -1, 0
	s_lshl_b32 s42, s10, 11
	s_add_i32 s2, s42, 0x4c00
	s_ashr_i32 s2, s2, 8
	s_add_i32 s2, s2, s11
	s_ashr_i32 s3, s2, 31
	s_min_i32 s1, s10, 1
	s_ashr_i32 s9, s8, 31
	s_lshl_b64 s[2:3], s[2:3], 23
	s_add_u32 s2, s34, s2
	s_addc_u32 s3, s35, s3
	s_lshl_b64 s[4:5], s[8:9], 17
	s_add_u32 s2, s2, s4
	s_addc_u32 s3, s3, s5
	s_lshl_b32 s1, s1, 11
	s_add_i32 s44, s1, 0x800
	s_addk_i32 s1, 0x5400
	s_ashr_i32 s1, s1, 8
	s_add_i32 s46, s1, s11
	s_ashr_i32 s47, s46, 31
	s_lshl_b64 s[46:47], s[46:47], 23
	s_add_u32 s1, s34, s46
	v_lshl_or_b32 v132, s11, 8, v187
	s_addc_u32 s11, s35, s47
	s_add_u32 s4, s1, s4
	s_addc_u32 s5, s11, s5
	s_ashr_i32 s43, s42, 31
	s_lshl_b64 s[8:9], s[8:9], 20
	s_ashr_i32 s45, s44, 31
	s_lshl_b64 s[42:43], s[42:43], 2
	s_add_u32 s42, s36, s42
	s_addc_u32 s43, s37, s43
	s_lshl_b64 s[44:45], s[44:45], 2
	s_add_u32 s44, s36, s44
	v_lshl_add_u64 v[0:1], v[176:177], 0, s[8:9]
	v_ashrrev_i32_e32 v133, 31, v132
	s_addc_u32 s45, s37, s45
	v_lshl_add_u64 v[0:1], v[132:133], 1, v[0:1]
	v_lshlrev_b64 v[132:133], 2, v[132:133]
	v_lshl_add_u64 v[182:183], s[42:43], 0, v[132:133]
	v_lshl_add_u64 v[184:185], s[44:45], 0, v[132:133]
	v_mov_b32_e32 v2, v186
	global_load_dwordx4 v[144:147], v[182:183], off
	global_load_dwordx4 v[136:139], v[182:183], off offset:16
	global_load_dwordx4 v[140:143], v[184:185], off
	global_load_dwordx4 v[132:135], v[184:185], off offset:16
	s_cmp_lt_i32 s10, 2
	v_lshlrev_b64 v[148:149], 1, v[2:3]
	v_lshl_add_u64 v[150:151], s[2:3], 0, v[148:149]
	v_lshl_add_u64 v[148:149], s[4:5], 0, v[148:149]
	flat_load_dwordx4 v[190:193], v[150:151]
	flat_load_dwordx4 v[160:163], v[148:149]
	v_add_u32_e32 v148, 0x1000, v2
	v_mov_b32_e32 v149, v3
	v_lshlrev_b64 v[148:149], 1, v[148:149]
	v_lshl_add_u64 v[150:151], s[2:3], 0, v[148:149]
	v_lshl_add_u64 v[148:149], s[4:5], 0, v[148:149]
	flat_load_dwordx4 v[194:197], v[150:151]
	flat_load_dwordx4 v[156:159], v[148:149]
	v_add_u32_e32 v148, 0x2000, v2
	v_mov_b32_e32 v149, v3
	v_lshlrev_b64 v[148:149], 1, v[148:149]
	v_lshl_add_u64 v[150:151], s[2:3], 0, v[148:149]
	v_lshl_add_u64 v[148:149], s[4:5], 0, v[148:149]
	v_add_u32_e32 v2, 0x3000, v2
	flat_load_dwordx4 v[234:237], v[150:151]
	flat_load_dwordx4 v[152:155], v[148:149]
	v_lshlrev_b64 v[148:149], 1, v[2:3]
	v_lshl_add_u64 v[150:151], s[2:3], 0, v[148:149]
	v_lshl_add_u64 v[148:149], s[4:5], 0, v[148:149]
	flat_load_dwordx4 v[238:241], v[150:151]
	s_nop 0
	flat_load_dwordx4 v[148:151], v[148:149]
	s_waitcnt vmcnt(0) lgkmcnt(0)
; __device__ __forceinline__ float sigmoidf_(float x) { return __builtin_amdgcn_rcpf(1.0f + __expf(-x)); }
;   __device__ __forceinline__ void operator()(EPI_ARGS) const {
;     ...
;             unpack8(zc[m], xc);
;             unpack8(zn[m], xn);
; #pragma unroll
;             for (int k = 0; k < 8; ++k) {
;               const float ec = __expf(-fmaxf(xc[k] + gc[k], -40.f)), en = __expf(-fmaxf(xn[k] + gn[k], -40.f));
;               const float f = (1.0f + en) * __builtin_amdgcn_rcpf(1.0f + ec);
;               acc[ai][bj][m][k >> 2][k & 3] *= f;
;             }
;           }
;         } else {
; #pragma unroll
;           for (int m = 0; m < 4; ++m) {
;             float xc[8], y[8];
;             unpack8(zc[m], xc);
; #pragma unroll
;             for (int k = 0; k < 8; ++k) y[k] = acc[ai][bj][m][k >> 2][k & 3] * sigmoidf_(fmaxf(xc[k] + gc[k], -40.f));
;             u32x4 o;
;             o.x = pack2(y[0], y[1]); o.y = pack2(y[2], y[3]); o.z = pack2(y[4], y[5]); o.w = pack2(y[6], y[7]);
;             *(u32x4*)(mrow + (size_t)(ai * HALF + m * 16) * DM + bj * HALF) = o;
	v_lshlrev_b32_e32 v2, 16, v190
	v_and_b32_e32 v189, 0xffff0000, v190
	v_lshlrev_b32_e32 v190, 16, v191
	v_and_b32_e32 v191, 0xffff0000, v191
	v_lshlrev_b32_e32 v212, 16, v192
	v_and_b32_e32 v192, 0xffff0000, v192
	v_lshlrev_b32_e32 v213, 16, v193
	v_and_b32_e32 v193, 0xffff0000, v193
	v_add_f32_e32 v2, v144, v2
	v_add_f32_e32 v189, v145, v189
	v_add_f32_e32 v190, v146, v190
	v_add_f32_e32 v191, v147, v191
	v_add_f32_e32 v212, v136, v212
	v_add_f32_e32 v192, v137, v192
	v_add_f32_e32 v213, v138, v213
	v_add_f32_e32 v193, v139, v193
	s_mov_b64 s[8:9], -1
	v_max_f32_e32 v233, 0xc2200000, v2
	v_max_f32_e32 v232, 0xc2200000, v189
	v_max_f32_e32 v231, 0xc2200000, v190
	v_max_f32_e32 v230, 0xc2200000, v191
	v_max_f32_e32 v229, 0xc2200000, v212
	v_max_f32_e32 v228, 0xc2200000, v192
	v_max_f32_e32 v227, 0xc2200000, v213
	v_max_f32_e32 v226, 0xc2200000, v193
	v_lshlrev_b32_e32 v225, 16, v194
	v_and_b32_e32 v224, 0xffff0000, v194
	v_lshlrev_b32_e32 v223, 16, v195
	v_and_b32_e32 v222, 0xffff0000, v195
	v_lshlrev_b32_e32 v221, 16, v196
	v_and_b32_e32 v220, 0xffff0000, v196
	v_lshlrev_b32_e32 v219, 16, v197
	v_and_b32_e32 v218, 0xffff0000, v197
	v_lshlrev_b32_e32 v217, 16, v234
	v_and_b32_e32 v216, 0xffff0000, v234
	v_lshlrev_b32_e32 v215, 16, v235
	v_and_b32_e32 v214, 0xffff0000, v235
	v_lshlrev_b32_e32 v213, 16, v236
	v_and_b32_e32 v212, 0xffff0000, v236
	v_lshlrev_b32_e32 v197, 16, v237
	v_and_b32_e32 v196, 0xffff0000, v237
	v_lshlrev_b32_e32 v195, 16, v238
	v_and_b32_e32 v194, 0xffff0000, v238
	v_lshlrev_b32_e32 v193, 16, v239
	v_and_b32_e32 v192, 0xffff0000, v239
	v_lshlrev_b32_e32 v191, 16, v240
	v_and_b32_e32 v190, 0xffff0000, v240
	v_lshlrev_b32_e32 v189, 16, v241
	v_and_b32_e32 v2, 0xffff0000, v241
	s_cbranch_scc1 .LBB0_546
	v_mul_f32_e32 v234, 0xbfb8aa3b, v233
	v_mul_f32_e32 v235, 0xbfb8aa3b, v232
	v_mul_f32_e32 v236, 0xbfb8aa3b, v231
	v_exp_f32_e32 v234, v234
	v_exp_f32_e32 v235, v235
	v_exp_f32_e32 v236, v236
	v_mul_f32_e32 v237, 0xbfb8aa3b, v230
	v_exp_f32_e32 v237, v237
	v_mul_f32_e32 v238, 0xbfb8aa3b, v229
	v_mul_f32_e32 v239, 0xbfb8aa3b, v228
	v_add_f32_e32 v234, 1.0, v234
	v_add_f32_e32 v235, 1.0, v235
	v_add_f32_e32 v236, 1.0, v236
	v_exp_f32_e32 v238, v238
	v_exp_f32_e32 v239, v239
	v_mul_f32_e32 v240, 0xbfb8aa3b, v227
	v_mul_f32_e32 v241, 0xbfb8aa3b, v226
	v_rcp_f32_e32 v234, v234
	v_rcp_f32_e32 v235, v235
	v_rcp_f32_e32 v236, v236
	v_add_f32_e32 v237, 1.0, v237
	v_exp_f32_e32 v240, v240
	v_exp_f32_e32 v241, v241
	v_rcp_f32_e32 v237, v237
	v_add_f32_e32 v238, 1.0, v238
	v_add_f32_e32 v239, 1.0, v239
	v_mul_f32_e32 v234, v128, v234
	v_mul_f32_e32 v235, v129, v235
	v_mul_f32_e32 v236, v130, v236
	v_rcp_f32_e32 v238, v238
	v_rcp_f32_e32 v239, v239
	v_add_f32_e32 v240, 1.0, v240
	v_add_f32_e32 v241, 1.0, v241
	v_mul_f32_e32 v237, v131, v237
	v_rcp_f32_e32 v240, v240
	v_rcp_f32_e32 v241, v241
	v_cvt_pk_bf16_f32 v234, v234, v235
	v_cvt_pk_bf16_f32 v235, v236, v237
	v_add_f32_e32 v236, v144, v225
	v_max_f32_e32 v236, 0xc2200000, v236
	v_mul_f32_e32 v236, 0xbfb8aa3b, v236
	v_mul_f32_e32 v238, v124, v238
	v_mul_f32_e32 v239, v125, v239
	v_exp_f32_e32 v242, v236
	v_cvt_pk_bf16_f32 v236, v238, v239
	v_mul_f32_e32 v240, v126, v240
	v_mul_f32_e32 v241, v127, v241
	v_cvt_pk_bf16_f32 v237, v240, v241
	flat_store_dwordx4 v[0:1], v[234:237]
	v_add_f32_e32 v238, v136, v221
	v_max_f32_e32 v238, 0xc2200000, v238
	v_add_f32_e32 v235, v145, v224
	v_add_f32_e32 v236, v146, v223
	v_max_f32_e32 v235, 0xc2200000, v235
	v_max_f32_e32 v236, 0xc2200000, v236
	v_add_f32_e32 v237, v147, v222
	v_add_f32_e32 v239, v137, v220
	v_mul_f32_e32 v235, 0xbfb8aa3b, v235
	v_mul_f32_e32 v236, 0xbfb8aa3b, v236
	v_max_f32_e32 v237, 0xc2200000, v237
	v_mul_f32_e32 v238, 0xbfb8aa3b, v238
	v_max_f32_e32 v239, 0xc2200000, v239
	v_exp_f32_e32 v235, v235
	v_exp_f32_e32 v236, v236
	v_mul_f32_e32 v237, 0xbfb8aa3b, v237
	v_exp_f32_e32 v238, v238
	v_mul_f32_e32 v239, 0xbfb8aa3b, v239
	v_add_f32_e32 v240, v138, v219
	v_exp_f32_e32 v237, v237
	v_exp_f32_e32 v239, v239
	v_max_f32_e32 v240, 0xc2200000, v240
	v_add_f32_e32 v241, v139, v218
	v_mul_f32_e32 v240, 0xbfb8aa3b, v240
	v_max_f32_e32 v241, 0xc2200000, v241
	v_exp_f32_e32 v240, v240
	v_mul_f32_e32 v241, 0xbfb8aa3b, v241
	v_add_f32_e32 v234, 1.0, v242
	v_add_f32_e32 v235, 1.0, v235
	v_add_f32_e32 v236, 1.0, v236
	v_add_f32_e32 v238, 1.0, v238
	v_exp_f32_e32 v241, v241
	v_rcp_f32_e32 v234, v234
	v_rcp_f32_e32 v235, v235
	v_rcp_f32_e32 v236, v236
	v_add_f32_e32 v237, 1.0, v237
	v_rcp_f32_e32 v238, v238
	v_add_f32_e32 v239, 1.0, v239
	v_rcp_f32_e32 v237, v237
	v_rcp_f32_e32 v239, v239
	v_add_f32_e32 v240, 1.0, v240
	v_rcp_f32_e32 v240, v240
	v_add_f32_e32 v241, 1.0, v241
	v_mul_f32_e32 v234, v120, v234
; __device__ __forceinline__ float sigmoidf_(float x) { return __builtin_amdgcn_rcpf(1.0f + __expf(-x)); }
;   __device__ __forceinline__ void operator()(EPI_ARGS) const {
;     ...
;           for (int m = 0; m < 4; ++m) {
;             float xc[8], y[8];
;             unpack8(zc[m], xc);
; #pragma unroll
;             for (int k = 0; k < 8; ++k) y[k] = acc[ai][bj][m][k >> 2][k & 3] * sigmoidf_(fmaxf(xc[k] + gc[k], -40.f));
;             u32x4 o;
;             o.x = pack2(y[0], y[1]); o.y = pack2(y[2], y[3]); o.z = pack2(y[4], y[5]); o.w = pack2(y[6], y[7]);
;             *(u32x4*)(mrow + (size_t)(ai * HALF + m * 16) * DM + bj * HALF) = o;
;           }
	v_mul_f32_e32 v235, v121, v235
	v_mul_f32_e32 v236, v122, v236
	v_rcp_f32_e32 v241, v241
	v_mul_f32_e32 v238, v116, v238
	v_mul_f32_e32 v237, v123, v237
	v_mul_f32_e32 v239, v117, v239
	v_cvt_pk_bf16_f32 v234, v234, v235
	v_cvt_pk_bf16_f32 v235, v236, v237
	v_cvt_pk_bf16_f32 v236, v238, v239
	v_add_f32_e32 v238, v144, v217
	v_max_f32_e32 v238, 0xc2200000, v238
	v_mul_f32_e32 v240, v118, v240
	v_mul_f32_e32 v238, 0xbfb8aa3b, v238
	v_mul_f32_e32 v241, v119, v241
	v_cvt_pk_bf16_f32 v237, v240, v241
	v_exp_f32_e32 v240, v238
	v_add_co_u32_e32 v238, vcc, s67, v0
	v_add_f32_e32 v241, v139, v196
	s_nop 0
	v_addc_co_u32_e32 v239, vcc, 0, v1, vcc
	flat_store_dwordx4 v[238:239], v[234:237]
	v_add_f32_e32 v238, v136, v213
	v_max_f32_e32 v238, 0xc2200000, v238
	v_add_f32_e32 v235, v145, v216
	v_add_f32_e32 v236, v146, v215
	v_max_f32_e32 v235, 0xc2200000, v235
	v_max_f32_e32 v236, 0xc2200000, v236
	v_add_f32_e32 v237, v147, v214
	v_add_f32_e32 v239, v137, v212
	v_mul_f32_e32 v235, 0xbfb8aa3b, v235
	v_mul_f32_e32 v236, 0xbfb8aa3b, v236
	v_max_f32_e32 v237, 0xc2200000, v237
	v_mul_f32_e32 v238, 0xbfb8aa3b, v238
	v_max_f32_e32 v239, 0xc2200000, v239
	v_add_f32_e32 v234, 1.0, v240
	v_exp_f32_e32 v235, v235
	v_exp_f32_e32 v236, v236
	v_mul_f32_e32 v237, 0xbfb8aa3b, v237
	v_exp_f32_e32 v238, v238
	v_mul_f32_e32 v239, 0xbfb8aa3b, v239
	v_add_f32_e32 v240, v138, v197
	v_exp_f32_e32 v237, v237
	v_exp_f32_e32 v239, v239
	v_max_f32_e32 v240, 0xc2200000, v240
	v_mul_f32_e32 v240, 0xbfb8aa3b, v240
	v_max_f32_e32 v241, 0xc2200000, v241
	v_exp_f32_e32 v240, v240
	v_mul_f32_e32 v241, 0xbfb8aa3b, v241
	v_add_f32_e32 v235, 1.0, v235
	v_add_f32_e32 v236, 1.0, v236
	v_add_f32_e32 v238, 1.0, v238
	v_exp_f32_e32 v241, v241
	v_rcp_f32_e32 v234, v234
	v_rcp_f32_e32 v235, v235
	v_rcp_f32_e32 v236, v236
	v_add_f32_e32 v237, 1.0, v237
	v_rcp_f32_e32 v238, v238
	v_add_f32_e32 v239, 1.0, v239
	v_rcp_f32_e32 v237, v237
	v_rcp_f32_e32 v239, v239
	v_add_f32_e32 v240, 1.0, v240
	v_rcp_f32_e32 v240, v240
	v_add_f32_e32 v241, 1.0, v241
	v_mul_f32_e32 v234, v112, v234
	v_mul_f32_e32 v235, v113, v235
	v_mul_f32_e32 v236, v114, v236
	v_rcp_f32_e32 v241, v241
	v_mul_f32_e32 v238, v108, v238
	v_mul_f32_e32 v237, v115, v237
	v_mul_f32_e32 v239, v109, v239
	v_cvt_pk_bf16_f32 v234, v234, v235
	v_cvt_pk_bf16_f32 v235, v236, v237
	v_cvt_pk_bf16_f32 v236, v238, v239
	v_add_f32_e32 v238, v144, v195
	v_max_f32_e32 v238, 0xc2200000, v238
	v_mul_f32_e32 v240, v110, v240
	v_mul_f32_e32 v238, 0xbfb8aa3b, v238
	s_mov_b32 s1, 0x20000
	v_mul_f32_e32 v241, v111, v241
	v_cvt_pk_bf16_f32 v237, v240, v241
	v_exp_f32_e32 v240, v238
	v_add_co_u32_e32 v238, vcc, s1, v0
	v_add_f32_e32 v241, v139, v2
	s_nop 0
	v_addc_co_u32_e32 v239, vcc, 0, v1, vcc
	flat_store_dwordx4 v[238:239], v[234:237]
	v_add_f32_e32 v238, v136, v191
	v_max_f32_e32 v238, 0xc2200000, v238
	v_add_f32_e32 v235, v145, v194
	v_add_f32_e32 v236, v146, v193
	v_max_f32_e32 v235, 0xc2200000, v235
	v_max_f32_e32 v236, 0xc2200000, v236
	v_add_f32_e32 v237, v147, v192
	v_add_f32_e32 v239, v137, v190
	v_mul_f32_e32 v235, 0xbfb8aa3b, v235
	v_mul_f32_e32 v236, 0xbfb8aa3b, v236
	v_max_f32_e32 v237, 0xc2200000, v237
	v_mul_f32_e32 v238, 0xbfb8aa3b, v238
	v_max_f32_e32 v239, 0xc2200000, v239
	v_add_f32_e32 v234, 1.0, v240
	v_exp_f32_e32 v235, v235
	v_exp_f32_e32 v236, v236
	v_mul_f32_e32 v237, 0xbfb8aa3b, v237
	v_exp_f32_e32 v238, v238
	v_mul_f32_e32 v239, 0xbfb8aa3b, v239
	v_add_f32_e32 v240, v138, v189
	v_exp_f32_e32 v237, v237
	v_exp_f32_e32 v239, v239
	v_max_f32_e32 v240, 0xc2200000, v240
	v_max_f32_e32 v241, 0xc2200000, v241
	v_mul_f32_e32 v240, 0xbfb8aa3b, v240
	v_mul_f32_e32 v241, 0xbfb8aa3b, v241
	v_exp_f32_e32 v240, v240
	v_exp_f32_e32 v241, v241
	v_add_f32_e32 v235, 1.0, v235
	v_add_f32_e32 v236, 1.0, v236
	v_add_f32_e32 v238, 1.0, v238
	v_rcp_f32_e32 v234, v234
	v_rcp_f32_e32 v235, v235
	v_rcp_f32_e32 v236, v236
	v_add_f32_e32 v237, 1.0, v237
	v_rcp_f32_e32 v238, v238
	v_add_f32_e32 v239, 1.0, v239
	v_rcp_f32_e32 v237, v237
	v_rcp_f32_e32 v239, v239
	v_add_f32_e32 v240, 1.0, v240
	v_add_f32_e32 v241, 1.0, v241
	v_rcp_f32_e32 v240, v240
	v_rcp_f32_e32 v241, v241
	v_mul_f32_e32 v234, v104, v234
	v_mul_f32_e32 v235, v105, v235
	v_mul_f32_e32 v236, v106, v236
	v_mul_f32_e32 v238, v100, v238
	v_mul_f32_e32 v237, v107, v237
	v_mul_f32_e32 v239, v101, v239
	v_cvt_pk_bf16_f32 v234, v234, v235
	v_cvt_pk_bf16_f32 v235, v236, v237
	v_cvt_pk_bf16_f32 v236, v238, v239
	v_add_co_u32_e32 v238, vcc, 0x30000, v0
	s_mov_b64 s[8:9], 0
	s_nop 0
	v_addc_co_u32_e32 v239, vcc, 0, v1, vcc
	v_mul_f32_e32 v240, v102, v240
	v_mul_f32_e32 v241, v103, v241
	v_cvt_pk_bf16_f32 v237, v240, v241
	flat_store_dwordx4 v[238:239], v[234:237]

; #define PG8_WAIT_V(n) asm volatile("s_waitcnt vmcnt(" #n ")" ::: "memory")
; #define PG8_WAIT_L(n) asm volatile("s_waitcnt lgkmcnt(" #n ")" ::: "memory")
; #define PG8_BAR __builtin_amdgcn_s_barrier()
; #define PG8_SCHED __builtin_amdgcn_sched_barrier(0)
; template <class Epi, class AddrA, class AddrB>
; __device__ __forceinline__ void gemm_phase(const Sched S, const int lda, const int ldb, const int K, const AddrA addrA,
;                                            const AddrB addrB, const Epi E) {
;     ...
;     const bool has_next = S.next(ui + 1, nxt);
;     const char* nA = has_next ? addrA(nxt) : cA;
;     const char* nB = has_next ? addrB(nxt) : cB;
;     for (int t = 0; t < nt; t += 2) {
;       const bool last = (t == nt - 2);
;       const char* a1 = cA + (size_t)(t + 1) * kstep;
;       const char* a2 = last ? nA : cA + (size_t)(t + 2) * kstep;
;       const char* b2 = last ? nB : cB + (size_t)(t + 2) * kstep;
;       const char* a3 = a2 + kstep;
;       const char* b3 = b2 + kstep;
;       PG8_LDB(B0, 0, 0); PG8_SCHED; PG8_LDA(At, 0, 0); PG8_STAGE(PG8_SA(1, 1), a1 + hstepA, voffA);
;       PG8_WAIT_L(8); PG8_BAR; PG8_WAIT_L(0); PG8_MMA(0, 0, At, B0); PG8_BAR; PG8_SCHED;
;       PG8_LDB(B1, 0, 1); PG8_STAGE(PG8_SB(0, 0), b2, voffB);
;       PG8_BAR; PG8_WAIT_L(0); PG8_MMA(0, 1, At, B1); PG8_BAR;
;       PG8_LDA(At, 0, 1); PG8_STAGE(PG8_SA(0, 0), a2, voffA);
;       PG8_BAR; PG8_WAIT_L(0); PG8_MMA(1, 0, At, B0); PG8_BAR; PG8_SCHED;
;       PG8_STAGE(PG8_SB(0, 1), b2 + hstepB, voffB);
;       PG8_WAIT_V(6); PG8_BAR; PG8_MMA(1, 1, At, B1); PG8_BAR;
.LBB0_618:
	s_ashr_i32 s3, s2, 31
	s_lshl_b64 s[8:9], s[2:3], 20
	s_add_u32 s8, s23, s8
	s_addc_u32 s9, s24, s9
	s_and_b64 s[10:11], s[18:19], exec
	s_cselect_b32 s3, s9, s17
	s_cselect_b32 s13, s8, s16
	s_ashr_i32 s5, s4, 31
	s_lshl_b64 s[10:11], s[4:5], 20
	s_add_u32 s10, s21, s10
	s_addc_u32 s11, s22, s11
	s_and_b64 s[18:19], s[18:19], exec
	s_cselect_b32 s5, s11, s15
	s_cselect_b32 s35, s10, s14
	s_add_u32 s36, s14, 0x100
	s_addc_u32 s37, s15, 0
	s_add_u32 s14, s16, 0x80080
	s_addc_u32 s15, s17, 0
	s_mov_b32 s38, -2
	s_add_i32 s39, 0, 0x10000
	v_add_u32_e32 v142, s39, v144
	ds_read_b128 v[148:151], v142
	ds_read_b128 v[152:155], v142 offset:1024
	ds_read_b128 v[156:159], v142 offset:2048
	ds_read_b128 v[160:163], v142 offset:3072
	v_lshl_add_u64 v[142:143], s[14:15], 0, v[140:141]
	s_add_i32 m0, s26, 0xc000
	ds_read_b128 v[168:171], v146
	ds_read_b128 v[172:175], v146 offset:1024
	ds_read_b128 v[176:179], v146 offset:2048
	ds_read_b128 v[180:183], v146 offset:3072
	ds_read_b128 v[184:187], v146 offset:4096
	ds_read_b128 v[188:191], v146 offset:5120
	ds_read_b128 v[192:195], v146 offset:6144
	ds_read_b128 v[212:215], v146 offset:7168
	global_load_lds_dwordx4 v[142:143], off
	v_lshl_add_u64 v[142:143], s[14:15], 0, v[138:139]
	s_add_i32 m0, s26, 0xe000
	s_nop 0
	global_load_lds_dwordx4 v[142:143], off
	s_waitcnt lgkmcnt(8)
	s_setprio 1
	s_barrier
	s_waitcnt lgkmcnt(0)
	v_mfma_f32_16x16x32_bf16 v[128:131], v[148:151], v[168:171], 0
	v_mfma_f32_16x16x32_bf16 v[128:131], v[152:155], v[172:175], v[128:131]
	v_mfma_f32_16x16x32_bf16 v[120:123], v[148:151], v[176:179], 0
	v_mfma_f32_16x16x32_bf16 v[120:123], v[152:155], v[180:183], v[120:123]
	v_mfma_f32_16x16x32_bf16 v[112:115], v[148:151], v[184:187], 0
	v_mfma_f32_16x16x32_bf16 v[112:115], v[152:155], v[188:191], v[112:115]
	v_mfma_f32_16x16x32_bf16 v[104:107], v[148:151], v[192:195], 0
	v_mfma_f32_16x16x32_bf16 v[104:107], v[152:155], v[212:215], v[104:107]
	v_mfma_f32_16x16x32_bf16 v[124:127], v[156:159], v[168:171], 0
	v_mfma_f32_16x16x32_bf16 v[124:127], v[160:163], v[172:175], v[124:127]
	v_mfma_f32_16x16x32_bf16 v[116:119], v[156:159], v[176:179], 0
	v_mfma_f32_16x16x32_bf16 v[116:119], v[160:163], v[180:183], v[116:119]
	v_mfma_f32_16x16x32_bf16 v[108:111], v[156:159], v[184:187], 0
	v_mfma_f32_16x16x32_bf16 v[108:111], v[160:163], v[188:191], v[108:111]
	v_mfma_f32_16x16x32_bf16 v[100:103], v[156:159], v[192:195], 0
	v_mfma_f32_16x16x32_bf16 v[100:103], v[160:163], v[212:215], v[100:103]
	s_barrier
	s_setprio 0
	s_add_u32 s16, s14, 0xfff80080
	s_addc_u32 s17, s15, -1
	s_cmp_eq_u32 s38, 28
	s_cselect_b32 s19, s3, s17
	s_cselect_b32 s18, s13, s16
	s_cselect_b32 s17, s5, s37
	s_cselect_b32 s16, s35, s36
	s_add_i32 s42, 0, 0x14000
	v_add_u32_e32 v142, s42, v144
	s_add_i32 s39, s39, s25
	ds_read_b128 v[216:219], v142
	ds_read_b128 v[220:223], v142 offset:1024
	ds_read_b128 v[224:227], v142 offset:2048
	ds_read_b128 v[228:231], v142 offset:3072
	v_lshl_add_u64 v[142:143], s[16:17], 0, v[2:3]
	s_mov_b32 m0, s39
	v_lshl_add_u64 v[196:197], s[16:17], 0, v[0:1]
	global_load_lds_dwordx4 v[142:143], off
	s_add_i32 m0, s39, 0x2000
	s_nop 0
	global_load_lds_dwordx4 v[196:197], off
	s_mov_b32 m0, s26
	v_lshl_add_u64 v[232:233], s[18:19], 0, v[134:135]
	s_setprio 1
	s_barrier
	s_waitcnt lgkmcnt(0)
	v_mfma_f32_16x16x32_bf16 v[96:99], v[216:219], v[168:171], 0
	v_mfma_f32_16x16x32_bf16 v[96:99], v[220:223], v[172:175], v[96:99]
	v_mfma_f32_16x16x32_bf16 v[88:91], v[216:219], v[176:179], 0
	v_mfma_f32_16x16x32_bf16 v[88:91], v[220:223], v[180:183], v[88:91]
	v_mfma_f32_16x16x32_bf16 v[80:83], v[216:219], v[184:187], 0
	v_mfma_f32_16x16x32_bf16 v[80:83], v[220:223], v[188:191], v[80:83]
	v_mfma_f32_16x16x32_bf16 v[72:75], v[216:219], v[192:195], 0
	v_mfma_f32_16x16x32_bf16 v[72:75], v[220:223], v[212:215], v[72:75]
	v_mfma_f32_16x16x32_bf16 v[92:95], v[224:227], v[168:171], 0
	v_mfma_f32_16x16x32_bf16 v[92:95], v[228:231], v[172:175], v[92:95]
	v_mfma_f32_16x16x32_bf16 v[84:87], v[224:227], v[176:179], 0
	v_mfma_f32_16x16x32_bf16 v[84:87], v[228:231], v[180:183], v[84:87]
	v_mfma_f32_16x16x32_bf16 v[76:79], v[224:227], v[184:187], 0
	v_mfma_f32_16x16x32_bf16 v[76:79], v[228:231], v[188:191], v[76:79]
	v_mfma_f32_16x16x32_bf16 v[68:71], v[224:227], v[192:195], 0
	v_mfma_f32_16x16x32_bf16 v[68:71], v[228:231], v[212:215], v[68:71]
	s_barrier
	s_setprio 0
	ds_read_b128 v[168:171], v146 offset:16384
	ds_read_b128 v[172:175], v146 offset:17408
	ds_read_b128 v[176:179], v146 offset:18432
	ds_read_b128 v[180:183], v146 offset:19456
	ds_read_b128 v[184:187], v146 offset:20480
	ds_read_b128 v[188:191], v146 offset:21504
	ds_read_b128 v[192:195], v146 offset:22528
	ds_read_b128 v[212:215], v146 offset:23552
	global_load_lds_dwordx4 v[232:233], off
	v_lshl_add_u64 v[234:235], s[18:19], 0, v[132:133]
	s_mov_b32 m0, s27
	s_nop 0
	global_load_lds_dwordx4 v[234:235], off
	s_setprio 1
	s_barrier
	s_waitcnt lgkmcnt(0)
	v_mfma_f32_16x16x32_bf16 v[64:67], v[148:151], v[168:171], 0
	v_mfma_f32_16x16x32_bf16 v[64:67], v[152:155], v[172:175], v[64:67]
	v_mfma_f32_16x16x32_bf16 v[56:59], v[148:151], v[176:179], 0
	v_mfma_f32_16x16x32_bf16 v[56:59], v[152:155], v[180:183], v[56:59]
	v_mfma_f32_16x16x32_bf16 v[48:51], v[148:151], v[184:187], 0
	v_mfma_f32_16x16x32_bf16 v[48:51], v[152:155], v[188:191], v[48:51]
	v_mfma_f32_16x16x32_bf16 v[40:43], v[148:151], v[192:195], 0
	v_mfma_f32_16x16x32_bf16 v[40:43], v[152:155], v[212:215], v[40:43]
	v_mfma_f32_16x16x32_bf16 v[60:63], v[156:159], v[168:171], 0
	v_mfma_f32_16x16x32_bf16 v[60:63], v[160:163], v[172:175], v[60:63]
	v_mfma_f32_16x16x32_bf16 v[52:55], v[156:159], v[176:179], 0
	v_mfma_f32_16x16x32_bf16 v[52:55], v[160:163], v[180:183], v[52:55]
	v_mfma_f32_16x16x32_bf16 v[44:47], v[156:159], v[184:187], 0
	v_mfma_f32_16x16x32_bf16 v[44:47], v[160:163], v[188:191], v[44:47]
	v_mfma_f32_16x16x32_bf16 v[36:39], v[156:159], v[192:195], 0
	v_mfma_f32_16x16x32_bf16 v[36:39], v[160:163], v[212:215], v[36:39]
	s_barrier
; #define PG8_WAIT_V(n) asm volatile("s_waitcnt vmcnt(" #n ")" ::: "memory")
; #define PG8_WAIT_L(n) asm volatile("s_waitcnt lgkmcnt(" #n ")" ::: "memory")
; #define PG8_BAR __builtin_amdgcn_s_barrier()
; #define PG8_SCHED __builtin_amdgcn_sched_barrier(0)
; template <class Epi, class AddrA, class AddrB>
; __device__ __forceinline__ void gemm_phase(const Sched S, const int lda, const int ldb, const int K, const AddrA addrA,
;                                            const AddrB addrB, const Epi E) {
;     ...
;       PG8_BAR; PG8_WAIT_L(0); PG8_MMA(0, 1, At, B1); PG8_BAR;
;       PG8_LDA(At, 0, 1); PG8_STAGE(PG8_SA(0, 0), a2, voffA);
;       PG8_BAR; PG8_WAIT_L(0); PG8_MMA(1, 0, At, B0); PG8_BAR; PG8_SCHED;
;       PG8_STAGE(PG8_SB(0, 1), b2 + hstepB, voffB);
;       PG8_WAIT_V(6); PG8_BAR; PG8_MMA(1, 1, At, B1); PG8_BAR;
;       PG8_LDB(B0, 1, 0); PG8_SCHED; PG8_LDA(At, 1, 0); PG8_STAGE(PG8_SA(0, 1), a2 + hstepA, voffA);
;       PG8_WAIT_L(8); PG8_BAR; PG8_WAIT_L(0); PG8_MMA(0, 0, At, B0); PG8_BAR; PG8_SCHED;
;       PG8_LDB(B1, 1, 1); PG8_STAGE(PG8_SB(1, 0), b3, voffB);
;       PG8_BAR; PG8_WAIT_L(0); PG8_MMA(0, 1, At, B1); PG8_BAR;
;       PG8_LDA(At, 1, 1); PG8_STAGE(PG8_SA(1, 0), a3, voffA);
;       PG8_BAR; PG8_WAIT_L(0); PG8_MMA(1, 0, At, B0); PG8_BAR; PG8_SCHED;
;       PG8_STAGE(PG8_SB(1, 1), b3 + hstepB, voffB);
;       PG8_WAIT_V(6); PG8_BAR; PG8_MMA(1, 1, At, B1); PG8_BAR;
	s_setprio 0
	s_add_u32 s40, s16, 0x80000
	s_addc_u32 s41, s17, 0
	s_add_i32 s39, s42, s25
	v_lshl_add_u64 v[148:149], s[40:41], 0, v[2:3]
	s_mov_b32 m0, s39
	s_nop 0
	global_load_lds_dwordx4 v[148:149], off
	v_lshl_add_u64 v[148:149], s[40:41], 0, v[0:1]
	s_add_i32 m0, s39, 0x2000
	s_nop 0
	global_load_lds_dwordx4 v[148:149], off
	s_add_i32 s39, 0, 0x18000
	v_add_u32_e32 v147, s39, v144
	s_waitcnt vmcnt(6)
	s_setprio 1
	s_barrier
	v_mfma_f32_16x16x32_bf16 v[32:35], v[216:219], v[168:171], 0
	v_mfma_f32_16x16x32_bf16 v[32:35], v[220:223], v[172:175], v[32:35]
	v_mfma_f32_16x16x32_bf16 v[24:27], v[216:219], v[176:179], 0
	v_mfma_f32_16x16x32_bf16 v[24:27], v[220:223], v[180:183], v[24:27]
	v_mfma_f32_16x16x32_bf16 v[16:19], v[216:219], v[184:187], 0
	v_mfma_f32_16x16x32_bf16 v[16:19], v[220:223], v[188:191], v[16:19]
	v_mfma_f32_16x16x32_bf16 v[8:11], v[216:219], v[192:195], 0
	v_mfma_f32_16x16x32_bf16 v[8:11], v[220:223], v[212:215], v[8:11]
	v_mfma_f32_16x16x32_bf16 v[28:31], v[224:227], v[168:171], 0
	v_mfma_f32_16x16x32_bf16 v[28:31], v[228:231], v[172:175], v[28:31]
	v_mfma_f32_16x16x32_bf16 v[20:23], v[224:227], v[176:179], 0
	v_mfma_f32_16x16x32_bf16 v[20:23], v[228:231], v[180:183], v[20:23]
	v_mfma_f32_16x16x32_bf16 v[12:15], v[224:227], v[184:187], 0
	v_mfma_f32_16x16x32_bf16 v[12:15], v[228:231], v[188:191], v[12:15]
	v_mfma_f32_16x16x32_bf16 v[4:7], v[224:227], v[192:195], 0
	v_mfma_f32_16x16x32_bf16 v[4:7], v[228:231], v[212:215], v[4:7]
	s_barrier
	s_setprio 0
	ds_read_b128 v[148:151], v147
	ds_read_b128 v[152:155], v147 offset:1024
	ds_read_b128 v[156:159], v147 offset:2048
	ds_read_b128 v[160:163], v147 offset:3072
	s_add_u32 s18, s18, 0x80000
	s_addc_u32 s19, s19, 0
	s_mov_b32 m0, s28
	v_lshl_add_u64 v[216:217], s[18:19], 0, v[134:135]
	ds_read_b128 v[168:171], v146 offset:32768
	ds_read_b128 v[172:175], v146 offset:33792
	ds_read_b128 v[176:179], v146 offset:34816
	ds_read_b128 v[180:183], v146 offset:35840
	ds_read_b128 v[184:187], v146 offset:36864
	ds_read_b128 v[188:191], v146 offset:37888
	ds_read_b128 v[192:195], v146 offset:38912
	ds_read_b128 v[212:215], v146 offset:39936
	global_load_lds_dwordx4 v[216:217], off
	v_lshl_add_u64 v[216:217], s[18:19], 0, v[132:133]
	s_mov_b32 m0, s29
	s_nop 0
	global_load_lds_dwordx4 v[216:217], off
	s_waitcnt lgkmcnt(8)
	s_setprio 1
	s_barrier
	s_waitcnt lgkmcnt(0)
	v_mfma_f32_16x16x32_bf16 v[128:131], v[148:151], v[168:171], v[128:131]
	v_mfma_f32_16x16x32_bf16 v[128:131], v[152:155], v[172:175], v[128:131]
	v_mfma_f32_16x16x32_bf16 v[120:123], v[148:151], v[176:179], v[120:123]
	v_mfma_f32_16x16x32_bf16 v[120:123], v[152:155], v[180:183], v[120:123]
	v_mfma_f32_16x16x32_bf16 v[112:115], v[148:151], v[184:187], v[112:115]
	v_mfma_f32_16x16x32_bf16 v[112:115], v[152:155], v[188:191], v[112:115]
	v_mfma_f32_16x16x32_bf16 v[104:107], v[148:151], v[192:195], v[104:107]
	v_mfma_f32_16x16x32_bf16 v[104:107], v[152:155], v[212:215], v[104:107]
	v_mfma_f32_16x16x32_bf16 v[124:127], v[156:159], v[168:171], v[124:127]
	v_mfma_f32_16x16x32_bf16 v[124:127], v[160:163], v[172:175], v[124:127]
	v_mfma_f32_16x16x32_bf16 v[116:119], v[156:159], v[176:179], v[116:119]
	v_mfma_f32_16x16x32_bf16 v[116:119], v[160:163], v[180:183], v[116:119]
	v_mfma_f32_16x16x32_bf16 v[108:111], v[156:159], v[184:187], v[108:111]
	v_mfma_f32_16x16x32_bf16 v[108:111], v[160:163], v[188:191], v[108:111]
	v_mfma_f32_16x16x32_bf16 v[100:103], v[156:159], v[192:195], v[100:103]
	v_mfma_f32_16x16x32_bf16 v[100:103], v[160:163], v[212:215], v[100:103]
	s_barrier
	s_setprio 0
	s_add_i32 s18, 0, 0x1c000
	s_add_i32 s19, s39, s25
	v_add_u32_e32 v147, s18, v144
	v_lshl_add_u64 v[142:143], v[142:143], 0, s[52:53]
	s_mov_b32 m0, s19
	ds_read_b128 v[216:219], v147
	ds_read_b128 v[220:223], v147 offset:1024
	ds_read_b128 v[224:227], v147 offset:2048
	ds_read_b128 v[228:231], v147 offset:3072
	global_load_lds_dwordx4 v[142:143], off
	v_lshl_add_u64 v[142:143], v[196:197], 0, s[52:53]
	s_add_i32 m0, s19, 0x2000
	s_nop 0
	global_load_lds_dwordx4 v[142:143], off
	s_mov_b32 m0, s30
	v_lshl_add_u64 v[142:143], v[232:233], 0, s[52:53]
	s_setprio 1
	s_barrier
	s_waitcnt lgkmcnt(0)
	v_mfma_f32_16x16x32_bf16 v[96:99], v[216:219], v[168:171], v[96:99]
	v_mfma_f32_16x16x32_bf16 v[96:99], v[220:223], v[172:175], v[96:99]
	v_mfma_f32_16x16x32_bf16 v[88:91], v[216:219], v[176:179], v[88:91]
	v_mfma_f32_16x16x32_bf16 v[88:91], v[220:223], v[180:183], v[88:91]
	v_mfma_f32_16x16x32_bf16 v[80:83], v[216:219], v[184:187], v[80:83]
	v_mfma_f32_16x16x32_bf16 v[80:83], v[220:223], v[188:191], v[80:83]
	v_mfma_f32_16x16x32_bf16 v[72:75], v[216:219], v[192:195], v[72:75]
	v_mfma_f32_16x16x32_bf16 v[72:75], v[220:223], v[212:215], v[72:75]
	v_mfma_f32_16x16x32_bf16 v[92:95], v[224:227], v[168:171], v[92:95]
	v_mfma_f32_16x16x32_bf16 v[92:95], v[228:231], v[172:175], v[92:95]
	v_mfma_f32_16x16x32_bf16 v[84:87], v[224:227], v[176:179], v[84:87]
	v_mfma_f32_16x16x32_bf16 v[84:87], v[228:231], v[180:183], v[84:87]
	v_mfma_f32_16x16x32_bf16 v[76:79], v[224:227], v[184:187], v[76:79]
	v_mfma_f32_16x16x32_bf16 v[76:79], v[228:231], v[188:191], v[76:79]
	v_mfma_f32_16x16x32_bf16 v[68:71], v[224:227], v[192:195], v[68:71]
	v_mfma_f32_16x16x32_bf16 v[68:71], v[228:231], v[212:215], v[68:71]
	s_barrier
	s_setprio 0
	ds_read_b128 v[168:171], v146 offset:49152
	ds_read_b128 v[172:175], v146 offset:50176
	ds_read_b128 v[176:179], v146 offset:51200
	ds_read_b128 v[180:183], v146 offset:52224
	ds_read_b128 v[184:187], v146 offset:53248
	ds_read_b128 v[188:191], v146 offset:54272
	ds_read_b128 v[192:195], v146 offset:55296
	ds_read_b128 v[212:215], v146 offset:56320
	global_load_lds_dwordx4 v[142:143], off
	v_lshl_add_u64 v[142:143], v[234:235], 0, s[52:53]
	s_mov_b32 m0, s31
	s_nop 0
	global_load_lds_dwordx4 v[142:143], off
	s_setprio 1
	s_barrier
; #define PG8_WAIT_V(n) asm volatile("s_waitcnt vmcnt(" #n ")" ::: "memory")
; #define PG8_WAIT_L(n) asm volatile("s_waitcnt lgkmcnt(" #n ")" ::: "memory")
; #define PG8_BAR __builtin_amdgcn_s_barrier()
; #define PG8_SCHED __builtin_amdgcn_sched_barrier(0)
; template <class Epi, class AddrA, class AddrB>
; __device__ __forceinline__ void gemm_phase(const Sched S, const int lda, const int ldb, const int K, const AddrA addrA,
;                                            const AddrB addrB, const Epi E) {
;     ...
;       PG8_LDB(B0, 0, 0); PG8_SCHED; PG8_LDA(At, 0, 0); PG8_STAGE(PG8_SA(1, 1), a1 + hstepA, voffA);
;       PG8_WAIT_L(8); PG8_BAR; PG8_WAIT_L(0); PG8_MMA(0, 0, At, B0); PG8_BAR; PG8_SCHED;
;       PG8_LDB(B1, 0, 1); PG8_STAGE(PG8_SB(0, 0), b2, voffB);
;       PG8_BAR; PG8_WAIT_L(0); PG8_MMA(0, 1, At, B1); PG8_BAR;
;     ...
;       PG8_LDB(B0, 1, 0); PG8_SCHED; PG8_LDA(At, 1, 0); PG8_STAGE(PG8_SA(0, 1), a2 + hstepA, voffA);
;       PG8_WAIT_L(8); PG8_BAR; PG8_WAIT_L(0); PG8_MMA(0, 0, At, B0); PG8_BAR; PG8_SCHED;
;       PG8_LDB(B1, 1, 1); PG8_STAGE(PG8_SB(1, 0), b3, voffB);
;       PG8_BAR; PG8_WAIT_L(0); PG8_MMA(0, 1, At, B1); PG8_BAR;
;       PG8_LDA(At, 1, 1); PG8_STAGE(PG8_SA(1, 0), a3, voffA);
;       PG8_BAR; PG8_WAIT_L(0); PG8_MMA(1, 0, At, B0); PG8_BAR; PG8_SCHED;
;       PG8_STAGE(PG8_SB(1, 1), b3 + hstepB, voffB);
;       PG8_WAIT_V(6); PG8_BAR; PG8_MMA(1, 1, At, B1); PG8_BAR;
	s_waitcnt lgkmcnt(0)
	v_mfma_f32_16x16x32_bf16 v[64:67], v[148:151], v[168:171], v[64:67]
	v_mfma_f32_16x16x32_bf16 v[64:67], v[152:155], v[172:175], v[64:67]
	v_mfma_f32_16x16x32_bf16 v[56:59], v[148:151], v[176:179], v[56:59]
	v_mfma_f32_16x16x32_bf16 v[56:59], v[152:155], v[180:183], v[56:59]
	v_mfma_f32_16x16x32_bf16 v[48:51], v[148:151], v[184:187], v[48:51]
	v_mfma_f32_16x16x32_bf16 v[48:51], v[152:155], v[188:191], v[48:51]
	v_mfma_f32_16x16x32_bf16 v[40:43], v[148:151], v[192:195], v[40:43]
	v_mfma_f32_16x16x32_bf16 v[40:43], v[152:155], v[212:215], v[40:43]
	v_mfma_f32_16x16x32_bf16 v[60:63], v[156:159], v[168:171], v[60:63]
	v_mfma_f32_16x16x32_bf16 v[60:63], v[160:163], v[172:175], v[60:63]
	v_mfma_f32_16x16x32_bf16 v[52:55], v[156:159], v[176:179], v[52:55]
	v_mfma_f32_16x16x32_bf16 v[52:55], v[160:163], v[180:183], v[52:55]
	v_mfma_f32_16x16x32_bf16 v[44:47], v[156:159], v[184:187], v[44:47]
	v_mfma_f32_16x16x32_bf16 v[44:47], v[160:163], v[188:191], v[44:47]
	v_mfma_f32_16x16x32_bf16 v[36:39], v[156:159], v[192:195], v[36:39]
	v_mfma_f32_16x16x32_bf16 v[36:39], v[160:163], v[212:215], v[36:39]
	s_barrier
	s_setprio 0
	s_add_u32 s16, s16, 0x80080
	s_addc_u32 s17, s17, 0
	s_add_i32 s18, s18, s25
	v_lshl_add_u64 v[142:143], s[16:17], 0, v[2:3]
	s_mov_b32 m0, s18
	s_nop 0
	global_load_lds_dwordx4 v[142:143], off
	v_lshl_add_u64 v[142:143], s[16:17], 0, v[0:1]
	s_add_i32 m0, s18, 0x2000
	s_nop 0
	global_load_lds_dwordx4 v[142:143], off
	s_add_i32 s38, s38, 2
	s_add_u32 s36, s36, 0x100
	s_addc_u32 s37, s37, 0
	s_add_u32 s14, s14, 0x100
	s_addc_u32 s15, s15, 0
	s_waitcnt vmcnt(6)
	s_setprio 1
	s_barrier
	v_mfma_f32_16x16x32_bf16 v[32:35], v[216:219], v[168:171], v[32:35]
	v_mfma_f32_16x16x32_bf16 v[32:35], v[220:223], v[172:175], v[32:35]
	v_mfma_f32_16x16x32_bf16 v[24:27], v[216:219], v[176:179], v[24:27]
	v_mfma_f32_16x16x32_bf16 v[24:27], v[220:223], v[180:183], v[24:27]
	v_mfma_f32_16x16x32_bf16 v[16:19], v[216:219], v[184:187], v[16:19]
	v_mfma_f32_16x16x32_bf16 v[16:19], v[220:223], v[188:191], v[16:19]
	v_mfma_f32_16x16x32_bf16 v[8:11], v[216:219], v[192:195], v[8:11]
	v_mfma_f32_16x16x32_bf16 v[8:11], v[220:223], v[212:215], v[8:11]
	v_mfma_f32_16x16x32_bf16 v[28:31], v[224:227], v[168:171], v[28:31]
	v_mfma_f32_16x16x32_bf16 v[28:31], v[228:231], v[172:175], v[28:31]
	v_mfma_f32_16x16x32_bf16 v[20:23], v[224:227], v[176:179], v[20:23]
	v_mfma_f32_16x16x32_bf16 v[20:23], v[228:231], v[180:183], v[20:23]
	v_mfma_f32_16x16x32_bf16 v[12:15], v[224:227], v[184:187], v[12:15]
	v_mfma_f32_16x16x32_bf16 v[12:15], v[228:231], v[188:191], v[12:15]
	v_mfma_f32_16x16x32_bf16 v[4:7], v[224:227], v[192:195], v[4:7]
	v_mfma_f32_16x16x32_bf16 v[4:7], v[228:231], v[212:215], v[4:7]
	s_barrier
	s_setprio 0
	s_cmp_gt_u32 s38, 29
.LBB0_619:
	s_add_i32 s39, 0, 0x10000
	v_add_u32_e32 v142, s39, v144
	ds_read_b128 v[148:151], v142
	ds_read_b128 v[152:155], v142 offset:1024
	ds_read_b128 v[156:159], v142 offset:2048
	ds_read_b128 v[160:163], v142 offset:3072
	v_lshl_add_u64 v[142:143], s[14:15], 0, v[140:141]
	s_add_i32 m0, s26, 0xc000
	ds_read_b128 v[168:171], v146
	ds_read_b128 v[172:175], v146 offset:1024
	ds_read_b128 v[176:179], v146 offset:2048
	ds_read_b128 v[180:183], v146 offset:3072
	ds_read_b128 v[184:187], v146 offset:4096
	ds_read_b128 v[188:191], v146 offset:5120
	ds_read_b128 v[192:195], v146 offset:6144
	ds_read_b128 v[212:215], v146 offset:7168
	global_load_lds_dwordx4 v[142:143], off
	v_lshl_add_u64 v[142:143], s[14:15], 0, v[138:139]
	s_add_i32 m0, s26, 0xe000
	s_nop 0
	global_load_lds_dwordx4 v[142:143], off
	s_waitcnt lgkmcnt(8)
	s_setprio 1
	s_barrier
	s_waitcnt lgkmcnt(0)
	v_mfma_f32_16x16x32_bf16 v[128:131], v[148:151], v[168:171], v[128:131]
	v_mfma_f32_16x16x32_bf16 v[128:131], v[152:155], v[172:175], v[128:131]
	v_mfma_f32_16x16x32_bf16 v[120:123], v[148:151], v[176:179], v[120:123]
	v_mfma_f32_16x16x32_bf16 v[120:123], v[152:155], v[180:183], v[120:123]
	v_mfma_f32_16x16x32_bf16 v[112:115], v[148:151], v[184:187], v[112:115]
	v_mfma_f32_16x16x32_bf16 v[112:115], v[152:155], v[188:191], v[112:115]
	v_mfma_f32_16x16x32_bf16 v[104:107], v[148:151], v[192:195], v[104:107]
	v_mfma_f32_16x16x32_bf16 v[104:107], v[152:155], v[212:215], v[104:107]
	v_mfma_f32_16x16x32_bf16 v[124:127], v[156:159], v[168:171], v[124:127]
	v_mfma_f32_16x16x32_bf16 v[124:127], v[160:163], v[172:175], v[124:127]
	v_mfma_f32_16x16x32_bf16 v[116:119], v[156:159], v[176:179], v[116:119]
	v_mfma_f32_16x16x32_bf16 v[116:119], v[160:163], v[180:183], v[116:119]
	v_mfma_f32_16x16x32_bf16 v[108:111], v[156:159], v[184:187], v[108:111]
	v_mfma_f32_16x16x32_bf16 v[108:111], v[160:163], v[188:191], v[108:111]
	v_mfma_f32_16x16x32_bf16 v[100:103], v[156:159], v[192:195], v[100:103]
	v_mfma_f32_16x16x32_bf16 v[100:103], v[160:163], v[212:215], v[100:103]
	s_barrier
	s_setprio 0
	s_add_u32 s16, s14, 0xfff80080
	s_addc_u32 s17, s15, -1
	s_cmp_eq_u32 s38, 28
	s_cselect_b32 s19, s3, s17
	s_cselect_b32 s18, s13, s16
	s_cselect_b32 s17, s5, s37
	s_cselect_b32 s16, s35, s36
	s_add_i32 s42, 0, 0x14000
	v_add_u32_e32 v142, s42, v144
	s_add_i32 s39, s39, s25
	ds_read_b128 v[216:219], v142
	ds_read_b128 v[220:223], v142 offset:1024
	ds_read_b128 v[224:227], v142 offset:2048
	ds_read_b128 v[228:231], v142 offset:3072
	v_lshl_add_u64 v[142:143], s[16:17], 0, v[2:3]
	s_mov_b32 m0, s39
	v_lshl_add_u64 v[196:197], s[16:17], 0, v[0:1]
	global_load_lds_dwordx4 v[142:143], off
	s_add_i32 m0, s39, 0x2000
	s_nop 0
	global_load_lds_dwordx4 v[196:197], off
	s_mov_b32 m0, s26
	v_lshl_add_u64 v[232:233], s[18:19], 0, v[134:135]
	s_setprio 1
	s_barrier
; #define PG8_WAIT_V(n) asm volatile("s_waitcnt vmcnt(" #n ")" ::: "memory")
; #define PG8_WAIT_L(n) asm volatile("s_waitcnt lgkmcnt(" #n ")" ::: "memory")
; #define PG8_BAR __builtin_amdgcn_s_barrier()
; #define PG8_SCHED __builtin_amdgcn_sched_barrier(0)
; template <class Epi, class AddrA, class AddrB>
; __device__ __forceinline__ void gemm_phase(const Sched S, const int lda, const int ldb, const int K, const AddrA addrA,
;                                            const AddrB addrB, const Epi E) {
;     ...
;       PG8_BAR; PG8_WAIT_L(0); PG8_MMA(0, 1, At, B1); PG8_BAR;
;       PG8_LDA(At, 0, 1); PG8_STAGE(PG8_SA(0, 0), a2, voffA);
;       PG8_BAR; PG8_WAIT_L(0); PG8_MMA(1, 0, At, B0); PG8_BAR; PG8_SCHED;
;       PG8_STAGE(PG8_SB(0, 1), b2 + hstepB, voffB);
;       PG8_WAIT_V(6); PG8_BAR; PG8_MMA(1, 1, At, B1); PG8_BAR;
;       PG8_LDB(B0, 1, 0); PG8_SCHED; PG8_LDA(At, 1, 0); PG8_STAGE(PG8_SA(0, 1), a2 + hstepA, voffA);
;       PG8_WAIT_L(8); PG8_BAR; PG8_WAIT_L(0); PG8_MMA(0, 0, At, B0); PG8_BAR; PG8_SCHED;
;       PG8_LDB(B1, 1, 1); PG8_STAGE(PG8_SB(1, 0), b3, voffB);
;       PG8_BAR; PG8_WAIT_L(0); PG8_MMA(0, 1, At, B1); PG8_BAR;
;       PG8_LDA(At, 1, 1); PG8_STAGE(PG8_SA(1, 0), a3, voffA);
;       PG8_BAR; PG8_WAIT_L(0); PG8_MMA(1, 0, At, B0); PG8_BAR; PG8_SCHED;
;       PG8_STAGE(PG8_SB(1, 1), b3 + hstepB, voffB);
	s_waitcnt lgkmcnt(0)
	v_mfma_f32_16x16x32_bf16 v[96:99], v[216:219], v[168:171], v[96:99]
	v_mfma_f32_16x16x32_bf16 v[96:99], v[220:223], v[172:175], v[96:99]
	v_mfma_f32_16x16x32_bf16 v[88:91], v[216:219], v[176:179], v[88:91]
	v_mfma_f32_16x16x32_bf16 v[88:91], v[220:223], v[180:183], v[88:91]
	v_mfma_f32_16x16x32_bf16 v[80:83], v[216:219], v[184:187], v[80:83]
	v_mfma_f32_16x16x32_bf16 v[80:83], v[220:223], v[188:191], v[80:83]
	v_mfma_f32_16x16x32_bf16 v[72:75], v[216:219], v[192:195], v[72:75]
	v_mfma_f32_16x16x32_bf16 v[72:75], v[220:223], v[212:215], v[72:75]
	v_mfma_f32_16x16x32_bf16 v[92:95], v[224:227], v[168:171], v[92:95]
	v_mfma_f32_16x16x32_bf16 v[92:95], v[228:231], v[172:175], v[92:95]
	v_mfma_f32_16x16x32_bf16 v[84:87], v[224:227], v[176:179], v[84:87]
	v_mfma_f32_16x16x32_bf16 v[84:87], v[228:231], v[180:183], v[84:87]
	v_mfma_f32_16x16x32_bf16 v[76:79], v[224:227], v[184:187], v[76:79]
	v_mfma_f32_16x16x32_bf16 v[76:79], v[228:231], v[188:191], v[76:79]
	v_mfma_f32_16x16x32_bf16 v[68:71], v[224:227], v[192:195], v[68:71]
	v_mfma_f32_16x16x32_bf16 v[68:71], v[228:231], v[212:215], v[68:71]
	s_barrier
	s_setprio 0
	ds_read_b128 v[168:171], v146 offset:16384
	ds_read_b128 v[172:175], v146 offset:17408
	ds_read_b128 v[176:179], v146 offset:18432
	ds_read_b128 v[180:183], v146 offset:19456
	ds_read_b128 v[184:187], v146 offset:20480
	ds_read_b128 v[188:191], v146 offset:21504
	ds_read_b128 v[192:195], v146 offset:22528
	ds_read_b128 v[212:215], v146 offset:23552
	global_load_lds_dwordx4 v[232:233], off
	v_lshl_add_u64 v[234:235], s[18:19], 0, v[132:133]
	s_mov_b32 m0, s27
	s_nop 0
	global_load_lds_dwordx4 v[234:235], off
	s_setprio 1
	s_barrier
	s_waitcnt lgkmcnt(0)
	v_mfma_f32_16x16x32_bf16 v[64:67], v[148:151], v[168:171], v[64:67]
	v_mfma_f32_16x16x32_bf16 v[64:67], v[152:155], v[172:175], v[64:67]
	v_mfma_f32_16x16x32_bf16 v[56:59], v[148:151], v[176:179], v[56:59]
	v_mfma_f32_16x16x32_bf16 v[56:59], v[152:155], v[180:183], v[56:59]
	v_mfma_f32_16x16x32_bf16 v[48:51], v[148:151], v[184:187], v[48:51]
	v_mfma_f32_16x16x32_bf16 v[48:51], v[152:155], v[188:191], v[48:51]
	v_mfma_f32_16x16x32_bf16 v[40:43], v[148:151], v[192:195], v[40:43]
	v_mfma_f32_16x16x32_bf16 v[40:43], v[152:155], v[212:215], v[40:43]
	v_mfma_f32_16x16x32_bf16 v[60:63], v[156:159], v[168:171], v[60:63]
	v_mfma_f32_16x16x32_bf16 v[60:63], v[160:163], v[172:175], v[60:63]
	v_mfma_f32_16x16x32_bf16 v[52:55], v[156:159], v[176:179], v[52:55]
	v_mfma_f32_16x16x32_bf16 v[52:55], v[160:163], v[180:183], v[52:55]
	v_mfma_f32_16x16x32_bf16 v[44:47], v[156:159], v[184:187], v[44:47]
	v_mfma_f32_16x16x32_bf16 v[44:47], v[160:163], v[188:191], v[44:47]
	v_mfma_f32_16x16x32_bf16 v[36:39], v[156:159], v[192:195], v[36:39]
	v_mfma_f32_16x16x32_bf16 v[36:39], v[160:163], v[212:215], v[36:39]
	s_barrier
	s_setprio 0
	s_add_u32 s40, s16, 0x80000
	s_addc_u32 s41, s17, 0
	s_add_i32 s39, s42, s25
	v_lshl_add_u64 v[148:149], s[40:41], 0, v[2:3]
	s_mov_b32 m0, s39
	s_nop 0
	global_load_lds_dwordx4 v[148:149], off
	v_lshl_add_u64 v[148:149], s[40:41], 0, v[0:1]
	s_add_i32 m0, s39, 0x2000
	s_nop 0
	global_load_lds_dwordx4 v[148:149], off
	s_add_i32 s39, 0, 0x18000
	v_add_u32_e32 v147, s39, v144
	s_waitcnt vmcnt(6)
	s_setprio 1
	s_barrier
	v_mfma_f32_16x16x32_bf16 v[32:35], v[216:219], v[168:171], v[32:35]
	v_mfma_f32_16x16x32_bf16 v[32:35], v[220:223], v[172:175], v[32:35]
	v_mfma_f32_16x16x32_bf16 v[24:27], v[216:219], v[176:179], v[24:27]
	v_mfma_f32_16x16x32_bf16 v[24:27], v[220:223], v[180:183], v[24:27]
	v_mfma_f32_16x16x32_bf16 v[16:19], v[216:219], v[184:187], v[16:19]
	v_mfma_f32_16x16x32_bf16 v[16:19], v[220:223], v[188:191], v[16:19]
	v_mfma_f32_16x16x32_bf16 v[8:11], v[216:219], v[192:195], v[8:11]
	v_mfma_f32_16x16x32_bf16 v[8:11], v[220:223], v[212:215], v[8:11]
	v_mfma_f32_16x16x32_bf16 v[28:31], v[224:227], v[168:171], v[28:31]
	v_mfma_f32_16x16x32_bf16 v[28:31], v[228:231], v[172:175], v[28:31]
	v_mfma_f32_16x16x32_bf16 v[20:23], v[224:227], v[176:179], v[20:23]
	v_mfma_f32_16x16x32_bf16 v[20:23], v[228:231], v[180:183], v[20:23]
	v_mfma_f32_16x16x32_bf16 v[12:15], v[224:227], v[184:187], v[12:15]
	v_mfma_f32_16x16x32_bf16 v[12:15], v[228:231], v[188:191], v[12:15]
	v_mfma_f32_16x16x32_bf16 v[4:7], v[224:227], v[192:195], v[4:7]
	v_mfma_f32_16x16x32_bf16 v[4:7], v[228:231], v[212:215], v[4:7]
	s_barrier
	s_setprio 0
	ds_read_b128 v[148:151], v147
	ds_read_b128 v[152:155], v147 offset:1024
	ds_read_b128 v[156:159], v147 offset:2048
	ds_read_b128 v[160:163], v147 offset:3072
	s_add_u32 s18, s18, 0x80000
	s_addc_u32 s19, s19, 0
	s_mov_b32 m0, s28
	v_lshl_add_u64 v[216:217], s[18:19], 0, v[134:135]
	ds_read_b128 v[168:171], v146 offset:32768
	ds_read_b128 v[172:175], v146 offset:33792
	ds_read_b128 v[176:179], v146 offset:34816
	ds_read_b128 v[180:183], v146 offset:35840
	ds_read_b128 v[184:187], v146 offset:36864
	ds_read_b128 v[188:191], v146 offset:37888
	ds_read_b128 v[192:195], v146 offset:38912
	ds_read_b128 v[212:215], v146 offset:39936
	global_load_lds_dwordx4 v[216:217], off
	v_lshl_add_u64 v[216:217], s[18:19], 0, v[132:133]
	s_mov_b32 m0, s29
	s_nop 0
	global_load_lds_dwordx4 v[216:217], off
	s_waitcnt lgkmcnt(8)
	s_setprio 1
	s_barrier
; #define PG8_WAIT_V(n) asm volatile("s_waitcnt vmcnt(" #n ")" ::: "memory")
; #define PG8_WAIT_L(n) asm volatile("s_waitcnt lgkmcnt(" #n ")" ::: "memory")
; #define PG8_BAR __builtin_amdgcn_s_barrier()
; #define PG8_SCHED __builtin_amdgcn_sched_barrier(0)
; template <class Epi, class AddrA, class AddrB>
; __device__ __forceinline__ void gemm_phase(const Sched S, const int lda, const int ldb, const int K, const AddrA addrA,
;                                            const AddrB addrB, const Epi E) {
;     ...
;       PG8_WAIT_L(8); PG8_BAR; PG8_WAIT_L(0); PG8_MMA(0, 0, At, B0); PG8_BAR; PG8_SCHED;
;       PG8_LDB(B1, 1, 1); PG8_STAGE(PG8_SB(1, 0), b3, voffB);
;       PG8_BAR; PG8_WAIT_L(0); PG8_MMA(0, 1, At, B1); PG8_BAR;
;       PG8_LDA(At, 1, 1); PG8_STAGE(PG8_SA(1, 0), a3, voffA);
;       PG8_BAR; PG8_WAIT_L(0); PG8_MMA(1, 0, At, B0); PG8_BAR; PG8_SCHED;
;       PG8_STAGE(PG8_SB(1, 1), b3 + hstepB, voffB);
;       PG8_WAIT_V(6); PG8_BAR; PG8_MMA(1, 1, At, B1); PG8_BAR;
	s_waitcnt lgkmcnt(0)
	v_mfma_f32_16x16x32_bf16 v[128:131], v[148:151], v[168:171], v[128:131]
	v_mfma_f32_16x16x32_bf16 v[128:131], v[152:155], v[172:175], v[128:131]
	v_mfma_f32_16x16x32_bf16 v[120:123], v[148:151], v[176:179], v[120:123]
	v_mfma_f32_16x16x32_bf16 v[120:123], v[152:155], v[180:183], v[120:123]
	v_mfma_f32_16x16x32_bf16 v[112:115], v[148:151], v[184:187], v[112:115]
	v_mfma_f32_16x16x32_bf16 v[112:115], v[152:155], v[188:191], v[112:115]
	v_mfma_f32_16x16x32_bf16 v[104:107], v[148:151], v[192:195], v[104:107]
	v_mfma_f32_16x16x32_bf16 v[104:107], v[152:155], v[212:215], v[104:107]
	v_mfma_f32_16x16x32_bf16 v[124:127], v[156:159], v[168:171], v[124:127]
	v_mfma_f32_16x16x32_bf16 v[124:127], v[160:163], v[172:175], v[124:127]
	v_mfma_f32_16x16x32_bf16 v[116:119], v[156:159], v[176:179], v[116:119]
	v_mfma_f32_16x16x32_bf16 v[116:119], v[160:163], v[180:183], v[116:119]
	v_mfma_f32_16x16x32_bf16 v[108:111], v[156:159], v[184:187], v[108:111]
	v_mfma_f32_16x16x32_bf16 v[108:111], v[160:163], v[188:191], v[108:111]
	v_mfma_f32_16x16x32_bf16 v[100:103], v[156:159], v[192:195], v[100:103]
	v_mfma_f32_16x16x32_bf16 v[100:103], v[160:163], v[212:215], v[100:103]
	s_barrier
	s_setprio 0
	s_add_i32 s18, 0, 0x1c000
	s_add_i32 s19, s39, s25
	v_add_u32_e32 v147, s18, v144
	v_lshl_add_u64 v[142:143], v[142:143], 0, s[52:53]
	s_mov_b32 m0, s19
	ds_read_b128 v[216:219], v147
	ds_read_b128 v[220:223], v147 offset:1024
	ds_read_b128 v[224:227], v147 offset:2048
	ds_read_b128 v[228:231], v147 offset:3072
	global_load_lds_dwordx4 v[142:143], off
	v_lshl_add_u64 v[142:143], v[196:197], 0, s[52:53]
	s_add_i32 m0, s19, 0x2000
	s_nop 0
	global_load_lds_dwordx4 v[142:143], off
	s_mov_b32 m0, s30
	v_lshl_add_u64 v[142:143], v[232:233], 0, s[52:53]
	s_setprio 1
	s_barrier
	s_waitcnt lgkmcnt(0)
	v_mfma_f32_16x16x32_bf16 v[96:99], v[216:219], v[168:171], v[96:99]
	v_mfma_f32_16x16x32_bf16 v[96:99], v[220:223], v[172:175], v[96:99]
	v_mfma_f32_16x16x32_bf16 v[88:91], v[216:219], v[176:179], v[88:91]
	v_mfma_f32_16x16x32_bf16 v[88:91], v[220:223], v[180:183], v[88:91]
	v_mfma_f32_16x16x32_bf16 v[80:83], v[216:219], v[184:187], v[80:83]
	v_mfma_f32_16x16x32_bf16 v[80:83], v[220:223], v[188:191], v[80:83]
	v_mfma_f32_16x16x32_bf16 v[72:75], v[216:219], v[192:195], v[72:75]
	v_mfma_f32_16x16x32_bf16 v[72:75], v[220:223], v[212:215], v[72:75]
	v_mfma_f32_16x16x32_bf16 v[92:95], v[224:227], v[168:171], v[92:95]
	v_mfma_f32_16x16x32_bf16 v[92:95], v[228:231], v[172:175], v[92:95]
	v_mfma_f32_16x16x32_bf16 v[84:87], v[224:227], v[176:179], v[84:87]
	v_mfma_f32_16x16x32_bf16 v[84:87], v[228:231], v[180:183], v[84:87]
	v_mfma_f32_16x16x32_bf16 v[76:79], v[224:227], v[184:187], v[76:79]
	v_mfma_f32_16x16x32_bf16 v[76:79], v[228:231], v[188:191], v[76:79]
	v_mfma_f32_16x16x32_bf16 v[68:71], v[224:227], v[192:195], v[68:71]
	v_mfma_f32_16x16x32_bf16 v[68:71], v[228:231], v[212:215], v[68:71]
	s_barrier
	s_setprio 0
	ds_read_b128 v[168:171], v146 offset:49152
	ds_read_b128 v[172:175], v146 offset:50176
	ds_read_b128 v[176:179], v146 offset:51200
	ds_read_b128 v[180:183], v146 offset:52224
	ds_read_b128 v[184:187], v146 offset:53248
	ds_read_b128 v[188:191], v146 offset:54272
	ds_read_b128 v[192:195], v146 offset:55296
	ds_read_b128 v[212:215], v146 offset:56320
	global_load_lds_dwordx4 v[142:143], off
	v_lshl_add_u64 v[142:143], v[234:235], 0, s[52:53]
	s_mov_b32 m0, s31
	s_nop 0
	global_load_lds_dwordx4 v[142:143], off
	s_setprio 1
	s_barrier
	s_waitcnt lgkmcnt(0)
	v_mfma_f32_16x16x32_bf16 v[64:67], v[148:151], v[168:171], v[64:67]
	v_mfma_f32_16x16x32_bf16 v[64:67], v[152:155], v[172:175], v[64:67]
	v_mfma_f32_16x16x32_bf16 v[56:59], v[148:151], v[176:179], v[56:59]
	v_mfma_f32_16x16x32_bf16 v[56:59], v[152:155], v[180:183], v[56:59]
	v_mfma_f32_16x16x32_bf16 v[48:51], v[148:151], v[184:187], v[48:51]
	v_mfma_f32_16x16x32_bf16 v[48:51], v[152:155], v[188:191], v[48:51]
	v_mfma_f32_16x16x32_bf16 v[40:43], v[148:151], v[192:195], v[40:43]
	v_mfma_f32_16x16x32_bf16 v[40:43], v[152:155], v[212:215], v[40:43]
	v_mfma_f32_16x16x32_bf16 v[60:63], v[156:159], v[168:171], v[60:63]
	v_mfma_f32_16x16x32_bf16 v[60:63], v[160:163], v[172:175], v[60:63]
	v_mfma_f32_16x16x32_bf16 v[52:55], v[156:159], v[176:179], v[52:55]
	v_mfma_f32_16x16x32_bf16 v[52:55], v[160:163], v[180:183], v[52:55]
	v_mfma_f32_16x16x32_bf16 v[44:47], v[156:159], v[184:187], v[44:47]
	v_mfma_f32_16x16x32_bf16 v[44:47], v[160:163], v[188:191], v[44:47]
	v_mfma_f32_16x16x32_bf16 v[36:39], v[156:159], v[192:195], v[36:39]
	v_mfma_f32_16x16x32_bf16 v[36:39], v[160:163], v[212:215], v[36:39]
	s_barrier
	s_setprio 0
	s_add_u32 s16, s16, 0x80080
	s_addc_u32 s17, s17, 0
	s_add_i32 s18, s18, s25
	v_lshl_add_u64 v[142:143], s[16:17], 0, v[2:3]
	s_mov_b32 m0, s18
	s_nop 0
	global_load_lds_dwordx4 v[142:143], off
	v_lshl_add_u64 v[142:143], s[16:17], 0, v[0:1]
	s_add_i32 m0, s18, 0x2000
	s_nop 0
	global_load_lds_dwordx4 v[142:143], off
	s_add_i32 s38, s38, 2
	s_add_u32 s36, s36, 0x100
	s_addc_u32 s37, s37, 0
	s_add_u32 s14, s14, 0x100
	s_addc_u32 s15, s15, 0
	s_waitcnt vmcnt(6)
	s_setprio 1
	s_barrier
;   __device__ __forceinline__ void operator()(EPI_ARGS) const {
;     const size_t row0 = (size_t)u.pm * 256 + wr * 64 + fr;
;     const int col0 = u.pn * 256 + wc * 32 + 8 * fq;
; #pragma unroll
;     for (int ai = 0; ai < 2; ++ai)
; #pragma unroll
;       for (int bj = 0; bj < 2; ++bj) {
;         f32x4 x0[4], x1[4];
; #pragma unroll
;         for (int m = 0; m < 4; ++m) {
;           const size_t o = (row0 + ai * HALF + m * 16) * DM + col0 + bj * HALF;
;           x0[m] = *(const f32x4*)(xres + o);
;           x1[m] = *(const f32x4*)(xres + o + 4);
;         }
;         __builtin_amdgcn_sched_barrier(0);
; #pragma unroll
;         for (int m = 0; m < 4; ++m) {
;           const size_t o = (row0 + ai * HALF + m * 16) * DM + col0 + bj * HALF;
;           *(f32x4*)(hbuf + o) = acc[ai][bj][m][0] + x0[m] * ALPHA;
;           *(f32x4*)(hbuf + o + 4) = acc[ai][bj][m][1] + x1[m] * ALPHA;
;         }
	v_mfma_f32_16x16x32_bf16 v[32:35], v[216:219], v[168:171], v[32:35]
	v_mfma_f32_16x16x32_bf16 v[32:35], v[220:223], v[172:175], v[32:35]
	v_mfma_f32_16x16x32_bf16 v[24:27], v[216:219], v[176:179], v[24:27]
	v_mfma_f32_16x16x32_bf16 v[24:27], v[220:223], v[180:183], v[24:27]
	v_mfma_f32_16x16x32_bf16 v[16:19], v[216:219], v[184:187], v[16:19]
	v_mfma_f32_16x16x32_bf16 v[16:19], v[220:223], v[188:191], v[16:19]
	v_mfma_f32_16x16x32_bf16 v[8:11], v[216:219], v[192:195], v[8:11]
	v_mfma_f32_16x16x32_bf16 v[8:11], v[220:223], v[212:215], v[8:11]
	v_mfma_f32_16x16x32_bf16 v[28:31], v[224:227], v[168:171], v[28:31]
	v_mfma_f32_16x16x32_bf16 v[28:31], v[228:231], v[172:175], v[28:31]
	v_mfma_f32_16x16x32_bf16 v[20:23], v[224:227], v[176:179], v[20:23]
	v_mfma_f32_16x16x32_bf16 v[20:23], v[228:231], v[180:183], v[20:23]
	v_mfma_f32_16x16x32_bf16 v[12:15], v[224:227], v[184:187], v[12:15]
	v_mfma_f32_16x16x32_bf16 v[12:15], v[228:231], v[188:191], v[12:15]
	v_mfma_f32_16x16x32_bf16 v[4:7], v[224:227], v[192:195], v[4:7]
	v_mfma_f32_16x16x32_bf16 v[4:7], v[228:231], v[212:215], v[4:7]
	s_barrier
	s_setprio 0
	s_cmp_gt_u32 s38, 29
	s_cbranch_scc0 .LBB0_619
	s_ashr_i32 s13, s12, 31
	v_lshl_or_b32 v142, s34, 8, v145
	v_ashrrev_i32_e32 v143, 31, v142
	s_lshl_b64 s[12:13], s[12:13], 21
	v_lshlrev_b64 v[184:185], 2, v[142:143]
	v_lshl_add_u64 v[188:189], s[12:13], 0, v[136:137]
	v_lshl_add_u64 v[186:187], s[0:1], 0, v[184:185]
	v_or_b32_e32 v190, 0x20000, v188
	v_mov_b32_e32 v191, v189
	v_or_b32_e32 v192, 0x40000, v188
	v_mov_b32_e32 v193, v189
	v_or_b32_e32 v194, 0x60000, v188
	v_mov_b32_e32 v195, v189
	v_lshl_add_u64 v[142:143], v[186:187], 0, v[188:189]
	v_lshl_add_u64 v[160:161], v[186:187], 0, v[190:191]
	v_lshl_add_u64 v[172:173], v[186:187], 0, v[192:193]
	v_lshl_add_u64 v[180:181], v[186:187], 0, v[194:195]
	flat_load_dwordx4 v[148:151], v[142:143]
	flat_load_dwordx4 v[152:155], v[142:143] offset:16
	flat_load_dwordx4 v[156:159], v[160:161]
	s_nop 0
	flat_load_dwordx4 v[160:163], v[160:161] offset:16
	s_nop 0
	flat_load_dwordx4 v[168:171], v[172:173]
	s_nop 0
	flat_load_dwordx4 v[172:175], v[172:173] offset:16
	s_nop 0
	flat_load_dwordx4 v[176:179], v[180:181]
	s_nop 0
	flat_load_dwordx4 v[180:183], v[180:181] offset:16
	v_lshl_add_u64 v[184:185], s[48:49], 0, v[184:185]
	s_mov_b32 s14, 0x3fb504f3
	s_waitcnt vmcnt(0) lgkmcnt(0)
	v_pk_fma_f32 v[148:149], v[148:149], s[14:15], v[128:129] op_sel_hi:[1,0,1]
	v_lshl_add_u64 v[128:129], v[184:185], 0, v[188:189]
	v_pk_fma_f32 v[126:127], v[154:155], s[14:15], v[126:127] op_sel_hi:[1,0,1]
	v_pk_fma_f32 v[124:125], v[152:153], s[14:15], v[124:125] op_sel_hi:[1,0,1]
	global_store_dwordx4 v[128:129], v[124:127], off offset:16
	v_pk_fma_f32 v[118:119], v[162:163], s[14:15], v[118:119] op_sel_hi:[1,0,1]
	v_pk_fma_f32 v[116:117], v[160:161], s[14:15], v[116:117] op_sel_hi:[1,0,1]
	v_lshl_add_u64 v[124:125], v[184:185], 0, v[190:191]
	v_pk_fma_f32 v[122:123], v[158:159], s[14:15], v[122:123] op_sel_hi:[1,0,1]
	v_pk_fma_f32 v[120:121], v[156:157], s[14:15], v[120:121] op_sel_hi:[1,0,1]
	global_store_dwordx4 v[124:125], v[116:119], off offset:16
	v_pk_fma_f32 v[110:111], v[174:175], s[14:15], v[110:111] op_sel_hi:[1,0,1]
	v_pk_fma_f32 v[108:109], v[172:173], s[14:15], v[108:109] op_sel_hi:[1,0,1]
	v_lshl_add_u64 v[116:117], v[184:185], 0, v[192:193]
	s_mov_b64 s[12:13], 0x200
	v_pk_fma_f32 v[150:151], v[150:151], s[14:15], v[130:131] op_sel_hi:[1,0,1]
	global_store_dwordx4 v[124:125], v[120:123], off
	v_pk_fma_f32 v[114:115], v[170:171], s[14:15], v[114:115] op_sel_hi:[1,0,1]
	v_pk_fma_f32 v[112:113], v[168:169], s[14:15], v[112:113] op_sel_hi:[1,0,1]
	global_store_dwordx4 v[116:117], v[108:111], off offset:16
	v_pk_fma_f32 v[106:107], v[178:179], s[14:15], v[106:107] op_sel_hi:[1,0,1]
	v_pk_fma_f32 v[104:105], v[176:177], s[14:15], v[104:105] op_sel_hi:[1,0,1]
	v_lshl_add_u64 v[108:109], v[184:185], 0, v[194:195]
	v_pk_fma_f32 v[102:103], v[182:183], s[14:15], v[102:103] op_sel_hi:[1,0,1]
	v_pk_fma_f32 v[100:101], v[180:181], s[14:15], v[100:101] op_sel_hi:[1,0,1]
	v_lshl_add_u64 v[124:125], v[186:187], 0, s[12:13]
	global_store_dwordx4 v[128:129], v[148:151], off
	global_store_dwordx4 v[116:117], v[112:115], off
	global_store_dwordx4 v[108:109], v[104:107], off
	global_store_dwordx4 v[108:109], v[100:103], off offset:16
	v_lshl_add_u64 v[112:113], v[124:125], 0, v[190:191]
	v_lshl_add_u64 v[120:121], v[124:125], 0, v[192:193]
	v_lshl_add_u64 v[130:131], v[124:125], 0, v[194:195]
	flat_load_dwordx4 v[100:103], v[142:143] offset:512
	flat_load_dwordx4 v[104:107], v[142:143] offset:528
	flat_load_dwordx4 v[108:111], v[112:113]
	s_nop 0
	flat_load_dwordx4 v[112:115], v[112:113] offset:16
	s_nop 0
	flat_load_dwordx4 v[116:119], v[120:121]
	s_nop 0
	flat_load_dwordx4 v[120:123], v[120:121] offset:16
	s_nop 0
	flat_load_dwordx4 v[124:127], v[130:131]
	flat_load_dwordx4 v[148:151], v[130:131] offset:16
	s_mov_b32 s3, 0x100000
	s_waitcnt vmcnt(0) lgkmcnt(0)
;   __device__ __forceinline__ void operator()(EPI_ARGS) const {
;     ...
;     for (int ai = 0; ai < 2; ++ai)
; #pragma unroll
;       for (int bj = 0; bj < 2; ++bj) {
;         f32x4 x0[4], x1[4];
; #pragma unroll
;         for (int m = 0; m < 4; ++m) {
;           const size_t o = (row0 + ai * HALF + m * 16) * DM + col0 + bj * HALF;
;           x0[m] = *(const f32x4*)(xres + o);
;           x1[m] = *(const f32x4*)(xres + o + 4);
;         }
;         __builtin_amdgcn_sched_barrier(0);
; #pragma unroll
;         for (int m = 0; m < 4; ++m) {
;           const size_t o = (row0 + ai * HALF + m * 16) * DM + col0 + bj * HALF;
;           *(f32x4*)(hbuf + o) = acc[ai][bj][m][0] + x0[m] * ALPHA;
;           *(f32x4*)(hbuf + o + 4) = acc[ai][bj][m][1] + x1[m] * ALPHA;
;         }
	v_pk_fma_f32 v[96:97], v[100:101], s[14:15], v[96:97] op_sel_hi:[1,0,1]
	v_add_co_u32_e32 v100, vcc, s3, v142
	s_mov_b32 s5, 0x120000
	s_nop 0
	v_addc_co_u32_e32 v101, vcc, 0, v143, vcc
	v_pk_fma_f32 v[98:99], v[102:103], s[14:15], v[98:99] op_sel_hi:[1,0,1]
	v_add_co_u32_e32 v102, vcc, s5, v142
	v_lshl_add_u64 v[130:131], v[184:185], 0, s[12:13]
	v_pk_fma_f32 v[94:95], v[106:107], s[14:15], v[94:95] op_sel_hi:[1,0,1]
	v_pk_fma_f32 v[92:93], v[104:105], s[14:15], v[92:93] op_sel_hi:[1,0,1]
	v_addc_co_u32_e32 v103, vcc, 0, v143, vcc
	s_mov_b32 s12, 0x140000
	global_store_dwordx4 v[128:129], v[92:95], off offset:528
	v_pk_fma_f32 v[86:87], v[114:115], s[14:15], v[86:87] op_sel_hi:[1,0,1]
	v_pk_fma_f32 v[84:85], v[112:113], s[14:15], v[84:85] op_sel_hi:[1,0,1]
	v_lshl_add_u64 v[92:93], v[130:131], 0, v[190:191]
	v_add_co_u32_e32 v104, vcc, s12, v142
	global_store_dwordx4 v[92:93], v[84:87], off offset:16
	v_pk_fma_f32 v[78:79], v[122:123], s[14:15], v[78:79] op_sel_hi:[1,0,1]
	v_pk_fma_f32 v[76:77], v[120:121], s[14:15], v[76:77] op_sel_hi:[1,0,1]
	v_lshl_add_u64 v[84:85], v[130:131], 0, v[192:193]
	v_addc_co_u32_e32 v105, vcc, 0, v143, vcc
	s_mov_b32 s13, 0x160000
	v_pk_fma_f32 v[90:91], v[110:111], s[14:15], v[90:91] op_sel_hi:[1,0,1]
	v_pk_fma_f32 v[88:89], v[108:109], s[14:15], v[88:89] op_sel_hi:[1,0,1]
	v_pk_fma_f32 v[82:83], v[118:119], s[14:15], v[82:83] op_sel_hi:[1,0,1]
	v_pk_fma_f32 v[80:81], v[116:117], s[14:15], v[80:81] op_sel_hi:[1,0,1]
	global_store_dwordx4 v[84:85], v[76:79], off offset:16
	v_pk_fma_f32 v[74:75], v[126:127], s[14:15], v[74:75] op_sel_hi:[1,0,1]
	v_pk_fma_f32 v[72:73], v[124:125], s[14:15], v[72:73] op_sel_hi:[1,0,1]
	v_lshl_add_u64 v[76:77], v[130:131], 0, v[194:195]
	v_pk_fma_f32 v[70:71], v[150:151], s[14:15], v[70:71] op_sel_hi:[1,0,1]
	v_pk_fma_f32 v[68:69], v[148:149], s[14:15], v[68:69] op_sel_hi:[1,0,1]
	s_mov_b64 s[16:17], 0x100000
	s_mov_b64 s[18:19], 0x120000
	s_mov_b64 s[34:35], 0x140000
	s_mov_b64 s[36:37], 0x160000
	v_add_co_u32_e32 v106, vcc, s13, v142
	global_store_dwordx4 v[128:129], v[96:99], off offset:512
	global_store_dwordx4 v[92:93], v[88:91], off
	global_store_dwordx4 v[84:85], v[80:83], off
	global_store_dwordx4 v[76:77], v[72:75], off
	global_store_dwordx4 v[76:77], v[68:71], off offset:16
	v_lshl_add_u64 v[80:81], v[142:143], 0, s[18:19]
	v_lshl_add_u64 v[72:73], v[142:143], 0, s[16:17]
	v_lshl_add_u64 v[88:89], v[142:143], 0, s[34:35]
	v_lshl_add_u64 v[96:97], v[142:143], 0, s[36:37]
	v_addc_co_u32_e32 v107, vcc, 0, v143, vcc
	flat_load_dwordx4 v[68:71], v[100:101]
	s_nop 0
	flat_load_dwordx4 v[72:75], v[72:73] offset:16
	s_nop 0
	flat_load_dwordx4 v[76:79], v[102:103]
	s_nop 0
	flat_load_dwordx4 v[80:83], v[80:81] offset:16
	s_nop 0
	flat_load_dwordx4 v[84:87], v[104:105]
	s_nop 0
	flat_load_dwordx4 v[88:91], v[88:89] offset:16
	s_nop 0
	flat_load_dwordx4 v[92:95], v[106:107]
	s_nop 0
	flat_load_dwordx4 v[96:99], v[96:97] offset:16
	s_waitcnt vmcnt(0) lgkmcnt(0)
; #define PG8_WAIT_V(n) asm volatile("s_waitcnt vmcnt(" #n ")" ::: "memory")
; #define PG8_BAR __builtin_amdgcn_s_barrier()
; template <class Epi, class AddrA, class AddrB>
; __device__ __forceinline__ void gemm_phase(const Sched S, const int lda, const int ldb, const int K, const AddrA addrA,
;                                            const AddrB addrB, const Epi E) {
;     ...
;     cur = nxt; cA = nA; cB = nB; ++ui;
;   }
;   PG8_WAIT_V(0);
;   if (wr == 0) PG8_BAR;
;   PG8_BAR;
;   __device__ __forceinline__ void operator()(EPI_ARGS) const {
;     ...
;     for (int ai = 0; ai < 2; ++ai)
; #pragma unroll
;       for (int bj = 0; bj < 2; ++bj) {
;         f32x4 x0[4], x1[4];
; #pragma unroll
;         for (int m = 0; m < 4; ++m) {
;           const size_t o = (row0 + ai * HALF + m * 16) * DM + col0 + bj * HALF;
;           x0[m] = *(const f32x4*)(xres + o);
;           x1[m] = *(const f32x4*)(xres + o + 4);
;         }
;         __builtin_amdgcn_sched_barrier(0);
; #pragma unroll
;         for (int m = 0; m < 4; ++m) {
;           const size_t o = (row0 + ai * HALF + m * 16) * DM + col0 + bj * HALF;
;           *(f32x4*)(hbuf + o) = acc[ai][bj][m][0] + x0[m] * ALPHA;
;           *(f32x4*)(hbuf + o + 4) = acc[ai][bj][m][1] + x1[m] * ALPHA;
;         }
	v_pk_fma_f32 v[66:67], v[70:71], s[14:15], v[66:67] op_sel_hi:[1,0,1]
	v_add_co_u32_e32 v70, vcc, s3, v128
	v_pk_fma_f32 v[64:65], v[68:69], s[14:15], v[64:65] op_sel_hi:[1,0,1]
	v_lshl_add_u64 v[68:69], v[128:129], 0, s[16:17]
	v_addc_co_u32_e32 v71, vcc, 0, v129, vcc
	v_pk_fma_f32 v[62:63], v[74:75], s[14:15], v[62:63] op_sel_hi:[1,0,1]
	v_pk_fma_f32 v[60:61], v[72:73], s[14:15], v[60:61] op_sel_hi:[1,0,1]
	global_store_dwordx4 v[68:69], v[60:63], off offset:16
	v_add_co_u32_e32 v68, vcc, s5, v128
	s_nop 0
	v_lshl_add_u64 v[60:61], v[128:129], 0, s[18:19]
	v_addc_co_u32_e32 v69, vcc, 0, v129, vcc
	v_add_co_u32_e32 v72, vcc, s12, v128
	v_pk_fma_f32 v[54:55], v[82:83], s[14:15], v[54:55] op_sel_hi:[1,0,1]
	v_pk_fma_f32 v[52:53], v[80:81], s[14:15], v[52:53] op_sel_hi:[1,0,1]
	v_addc_co_u32_e32 v73, vcc, 0, v129, vcc
	global_store_dwordx4 v[60:61], v[52:55], off offset:16
	v_pk_fma_f32 v[46:47], v[90:91], s[14:15], v[46:47] op_sel_hi:[1,0,1]
	v_pk_fma_f32 v[44:45], v[88:89], s[14:15], v[44:45] op_sel_hi:[1,0,1]
	v_lshl_add_u64 v[52:53], v[128:129], 0, s[34:35]
	v_add_co_u32_e32 v74, vcc, s13, v128
	v_pk_fma_f32 v[58:59], v[78:79], s[14:15], v[58:59] op_sel_hi:[1,0,1]
	v_pk_fma_f32 v[56:57], v[76:77], s[14:15], v[56:57] op_sel_hi:[1,0,1]
	v_pk_fma_f32 v[50:51], v[86:87], s[14:15], v[50:51] op_sel_hi:[1,0,1]
	v_pk_fma_f32 v[48:49], v[84:85], s[14:15], v[48:49] op_sel_hi:[1,0,1]
	global_store_dwordx4 v[52:53], v[44:47], off offset:16
	v_pk_fma_f32 v[42:43], v[94:95], s[14:15], v[42:43] op_sel_hi:[1,0,1]
	v_pk_fma_f32 v[40:41], v[92:93], s[14:15], v[40:41] op_sel_hi:[1,0,1]
	v_lshl_add_u64 v[44:45], v[128:129], 0, s[36:37]
	v_addc_co_u32_e32 v75, vcc, 0, v129, vcc
	v_pk_fma_f32 v[38:39], v[98:99], s[14:15], v[38:39] op_sel_hi:[1,0,1]
	v_pk_fma_f32 v[36:37], v[96:97], s[14:15], v[36:37] op_sel_hi:[1,0,1]
	s_mov_b64 s[12:13], 0x100200
	s_mov_b64 s[16:17], 0x120200
	s_mov_b64 s[18:19], 0x140200
	s_mov_b64 s[34:35], 0x160200
	global_store_dwordx4 v[70:71], v[64:67], off
	global_store_dwordx4 v[68:69], v[56:59], off
	global_store_dwordx4 v[72:73], v[48:51], off
	global_store_dwordx4 v[74:75], v[40:43], off
	global_store_dwordx4 v[44:45], v[36:39], off offset:16
	v_lshl_add_u64 v[44:45], v[142:143], 0, s[12:13]
	v_lshl_add_u64 v[48:49], v[142:143], 0, s[16:17]
	v_lshl_add_u64 v[60:61], v[142:143], 0, s[18:19]
	v_lshl_add_u64 v[64:65], v[142:143], 0, s[34:35]
	flat_load_dwordx4 v[36:39], v[100:101] offset:512
	flat_load_dwordx4 v[40:43], v[102:103] offset:512
	s_nop 0
	flat_load_dwordx4 v[44:47], v[44:45] offset:16
	s_nop 0
	flat_load_dwordx4 v[48:51], v[48:49] offset:16
	s_nop 0
	flat_load_dwordx4 v[52:55], v[104:105] offset:512
	flat_load_dwordx4 v[56:59], v[106:107] offset:512
	s_nop 0
	flat_load_dwordx4 v[60:63], v[60:61] offset:16
	s_nop 0
	flat_load_dwordx4 v[64:67], v[64:65] offset:16
	s_waitcnt vmcnt(0) lgkmcnt(0)
	v_pk_fma_f32 v[32:33], v[36:37], s[14:15], v[32:33] op_sel_hi:[1,0,1]
	v_lshl_add_u64 v[36:37], v[128:129], 0, s[12:13]
	v_pk_fma_f32 v[30:31], v[46:47], s[14:15], v[30:31] op_sel_hi:[1,0,1]
	v_pk_fma_f32 v[28:29], v[44:45], s[14:15], v[28:29] op_sel_hi:[1,0,1]
	global_store_dwordx4 v[36:37], v[28:31], off offset:16
	v_pk_fma_f32 v[22:23], v[50:51], s[14:15], v[22:23] op_sel_hi:[1,0,1]
	v_pk_fma_f32 v[20:21], v[48:49], s[14:15], v[20:21] op_sel_hi:[1,0,1]
	v_lshl_add_u64 v[28:29], v[128:129], 0, s[16:17]
	global_store_dwordx4 v[28:29], v[20:23], off offset:16
	v_pk_fma_f32 v[14:15], v[62:63], s[14:15], v[14:15] op_sel_hi:[1,0,1]
	v_pk_fma_f32 v[12:13], v[60:61], s[14:15], v[12:13] op_sel_hi:[1,0,1]
	v_lshl_add_u64 v[20:21], v[128:129], 0, s[18:19]
	v_pk_fma_f32 v[34:35], v[38:39], s[14:15], v[34:35] op_sel_hi:[1,0,1]
	v_pk_fma_f32 v[26:27], v[42:43], s[14:15], v[26:27] op_sel_hi:[1,0,1]
	v_pk_fma_f32 v[24:25], v[40:41], s[14:15], v[24:25] op_sel_hi:[1,0,1]
	v_pk_fma_f32 v[18:19], v[54:55], s[14:15], v[18:19] op_sel_hi:[1,0,1]
	v_pk_fma_f32 v[16:17], v[52:53], s[14:15], v[16:17] op_sel_hi:[1,0,1]
	global_store_dwordx4 v[20:21], v[12:15], off offset:16
	v_pk_fma_f32 v[10:11], v[58:59], s[14:15], v[10:11] op_sel_hi:[1,0,1]
	v_pk_fma_f32 v[8:9], v[56:57], s[14:15], v[8:9] op_sel_hi:[1,0,1]
	v_lshl_add_u64 v[12:13], v[128:129], 0, s[34:35]
	v_pk_fma_f32 v[6:7], v[66:67], s[14:15], v[6:7] op_sel_hi:[1,0,1]
	v_pk_fma_f32 v[4:5], v[64:65], s[14:15], v[4:5] op_sel_hi:[1,0,1]
	s_and_b64 vcc, exec, s[6:7]
	s_mov_b32 s34, s4
	s_mov_b32 s12, s2
	s_mov_b64 s[14:15], s[10:11]
	s_mov_b64 s[16:17], s[8:9]
	global_store_dwordx4 v[70:71], v[32:35], off offset:512
	global_store_dwordx4 v[68:69], v[24:27], off offset:512
	global_store_dwordx4 v[72:73], v[16:19], off offset:512
	global_store_dwordx4 v[74:75], v[8:11], off offset:512
	global_store_dwordx4 v[12:13], v[4:7], off offset:16
	s_cbranch_vccz .LBB0_616
	s_waitcnt vmcnt(0)
	s_cmpk_gt_u32 s20, 0xff
	s_cbranch_scc1 .LBB0_623
	s_barrier
